# P0 weight transposes: inner loop unrolled so all 32 row loads of an item are in flight before the LDS writes
# baseline (speedup 1.0000x reference)
; #define LAS __attribute__((address_space(3)))
; __device__ __forceinline__ void transpose_item(const float* W, int N, bf16_t* WT, int dstK, size_t drow0, int kdst0, int k0, int n0, LAS float* scr, int lane) {
; #pragma unroll 8
;     for (int i = 0; i < 32; ++i) { const int kk = 2 * i + (lane >> 5); scr[kk * 33 + (lane & 31)] = W[(size_t)(k0 + kk) * N + n0 + (lane & 31)]; }
.LBB0_9:
	s_lshl_b32 s10, s20, 1
	s_lshl_b32 s11, s9, 1
	v_or_b32_e32 v5, s10, v1
	v_or_b32_e32 v7, s11, v8
	s_add_i32 s21, s10, 4
	s_add_i32 s22, s11, 4
	s_add_i32 s23, s10, 8
	s_add_i32 s24, s11, 8
	s_add_i32 s25, s10, 12
	s_add_i32 s27, s11, 12
	s_add_i32 s28, s10, 16
	s_add_i32 s29, s11, 16
	s_add_i32 s30, s10, 20
	s_add_i32 s31, s11, 20
	s_add_i32 s33, s10, 24
	s_add_i32 s34, s11, 24
	s_add_i32 s10, s10, 28
	s_add_i32 s11, s11, 28
	v_add_u32_e32 v9, s3, v5
	v_add_u32_e32 v13, s2, v7
	v_or_b32_e32 v15, s21, v1
	v_or_b32_e32 v19, s22, v8
	v_or_b32_e32 v21, s23, v1
	v_or_b32_e32 v23, s24, v8
	v_or_b32_e32 v58, s25, v1
	v_or_b32_e32 v59, s27, v8
	v_or_b32_e32 v60, s28, v1
	v_or_b32_e32 v61, s29, v8
	v_or_b32_e32 v62, s30, v1
	v_or_b32_e32 v63, s31, v8
	v_or_b32_e32 v64, s33, v1
	v_or_b32_e32 v65, s34, v8
	v_or_b32_e32 v66, s10, v1
	v_or_b32_e32 v67, s11, v8
	v_mad_i64_i32 v[26:27], s[22:23], v13, s7, v[24:25]
	v_mad_i64_i32 v[28:29], s[22:23], v9, s7, v[24:25]
	v_add_u32_e32 v9, s3, v15
	v_add_u32_e32 v13, s2, v19
	v_add_u32_e32 v36, s3, v21
	v_add_u32_e32 v34, s2, v23
	v_add_u32_e32 v40, s3, v58
	v_add_u32_e32 v38, s2, v59
	v_add_u32_e32 v44, s3, v60
	v_add_u32_e32 v42, s2, v61
	v_add_u32_e32 v48, s3, v62
	v_add_u32_e32 v46, s2, v63
	v_add_u32_e32 v52, s3, v64
	v_add_u32_e32 v50, s2, v65
	v_add_u32_e32 v56, s3, v66
	v_add_u32_e32 v54, s2, v67
	v_mad_i64_i32 v[30:31], s[22:23], v13, s7, v[24:25]
	v_mad_i64_i32 v[32:33], s[22:23], v9, s7, v[24:25]
	v_mad_i64_i32 v[34:35], s[22:23], v34, s7, v[24:25]
	v_mad_i64_i32 v[36:37], s[22:23], v36, s7, v[24:25]
	v_mad_i64_i32 v[38:39], s[22:23], v38, s7, v[24:25]
	v_mad_i64_i32 v[40:41], s[22:23], v40, s7, v[24:25]
	v_mad_i64_i32 v[42:43], s[22:23], v42, s7, v[24:25]
	v_mad_i64_i32 v[44:45], s[22:23], v44, s7, v[24:25]
	v_mad_i64_i32 v[46:47], s[22:23], v46, s7, v[24:25]
	v_mad_i64_i32 v[48:49], s[22:23], v48, s7, v[24:25]
	v_mad_i64_i32 v[50:51], s[22:23], v50, s7, v[24:25]
	v_mad_i64_i32 v[52:53], s[22:23], v52, s7, v[24:25]
	v_mad_i64_i32 v[54:55], s[22:23], v54, s7, v[24:25]
	v_mad_i64_i32 v[56:57], s[22:23], v56, s7, v[24:25]
	global_load_dword v9, v[26:27], off
	global_load_dword v13, v[28:29], off
	global_load_dword v68, v[30:31], off
	global_load_dword v69, v[32:33], off
	global_load_dword v70, v[34:35], off
	global_load_dword v71, v[36:37], off
	global_load_dword v72, v[38:39], off
	global_load_dword v73, v[40:41], off
	global_load_dword v74, v[42:43], off
	global_load_dword v75, v[44:45], off
	global_load_dword v76, v[46:47], off
	global_load_dword v77, v[48:49], off
	global_load_dword v78, v[50:51], off
	global_load_dword v79, v[52:53], off
	global_load_dword v80, v[54:55], off
	global_load_dword v81, v[56:57], off
	s_add_i32 s9, s9, 16
	s_add_i32 s20, s20, 16
	s_add_i32 s19, s19, -16
	s_cmp_lg_u32 s19, 0
	s_lshl_b32 s10, s20, 1
	s_lshl_b32 s11, s9, 1
	v_or_b32_e32 v128, s10, v1
	v_or_b32_e32 v129, s11, v8
	s_add_i32 s21, s10, 4
	s_add_i32 s22, s11, 4
	s_add_i32 s23, s10, 8
	s_add_i32 s24, s11, 8
	s_add_i32 s25, s10, 12
	s_add_i32 s27, s11, 12
	s_add_i32 s28, s10, 16
	s_add_i32 s29, s11, 16
	s_add_i32 s30, s10, 20
	s_add_i32 s31, s11, 20
	s_add_i32 s33, s10, 24
	s_add_i32 s34, s11, 24
	s_add_i32 s10, s10, 28
	s_add_i32 s11, s11, 28
	v_add_u32_e32 v130, s3, v128
	v_add_u32_e32 v131, s2, v129
	v_or_b32_e32 v132, s21, v1
	v_or_b32_e32 v133, s22, v8
	v_or_b32_e32 v134, s23, v1
	v_or_b32_e32 v135, s24, v8
	v_or_b32_e32 v136, s25, v1
	v_or_b32_e32 v137, s27, v8
	v_or_b32_e32 v138, s28, v1
	v_or_b32_e32 v139, s29, v8
	v_or_b32_e32 v140, s30, v1
	v_or_b32_e32 v141, s31, v8
	v_or_b32_e32 v142, s33, v1
	v_or_b32_e32 v143, s34, v8
	v_or_b32_e32 v144, s10, v1
	v_or_b32_e32 v145, s11, v8
	v_mad_i64_i32 v[96:97], s[22:23], v131, s7, v[24:25]
	v_mad_i64_i32 v[98:99], s[22:23], v130, s7, v[24:25]
	v_add_u32_e32 v130, s3, v132
	v_add_u32_e32 v131, s2, v133
	v_add_u32_e32 v106, s3, v134
	v_add_u32_e32 v104, s2, v135
	v_add_u32_e32 v110, s3, v136
	v_add_u32_e32 v108, s2, v137
	v_add_u32_e32 v114, s3, v138
	v_add_u32_e32 v112, s2, v139
	v_add_u32_e32 v118, s3, v140
	v_add_u32_e32 v116, s2, v141
	v_add_u32_e32 v122, s3, v142
	v_add_u32_e32 v120, s2, v143
	v_add_u32_e32 v126, s3, v144
	v_add_u32_e32 v124, s2, v145
	v_mad_i64_i32 v[100:101], s[22:23], v131, s7, v[24:25]
	v_mad_i64_i32 v[102:103], s[22:23], v130, s7, v[24:25]
	v_mad_i64_i32 v[104:105], s[22:23], v104, s7, v[24:25]
	v_mad_i64_i32 v[106:107], s[22:23], v106, s7, v[24:25]
	v_mad_i64_i32 v[108:109], s[22:23], v108, s7, v[24:25]
	v_mad_i64_i32 v[110:111], s[22:23], v110, s7, v[24:25]
	v_mad_i64_i32 v[112:113], s[22:23], v112, s7, v[24:25]
	v_mad_i64_i32 v[114:115], s[22:23], v114, s7, v[24:25]
	v_mad_i64_i32 v[116:117], s[22:23], v116, s7, v[24:25]
	v_mad_i64_i32 v[118:119], s[22:23], v118, s7, v[24:25]
	v_mad_i64_i32 v[120:121], s[22:23], v120, s7, v[24:25]
	v_mad_i64_i32 v[122:123], s[22:23], v122, s7, v[24:25]
	v_mad_i64_i32 v[124:125], s[22:23], v124, s7, v[24:25]
	v_mad_i64_i32 v[126:127], s[22:23], v126, s7, v[24:25]
	global_load_dword v130, v[96:97], off
	global_load_dword v131, v[98:99], off
	global_load_dword v146, v[100:101], off
	global_load_dword v147, v[102:103], off
	global_load_dword v148, v[104:105], off
	global_load_dword v149, v[106:107], off
	global_load_dword v150, v[108:109], off
	global_load_dword v151, v[110:111], off
	global_load_dword v152, v[112:113], off
	global_load_dword v153, v[114:115], off
	global_load_dword v154, v[116:117], off
	global_load_dword v155, v[118:119], off
	global_load_dword v156, v[120:121], off
	global_load_dword v157, v[122:123], off
	global_load_dword v158, v[124:125], off
	global_load_dword v159, v[126:127], off
	s_add_i32 s9, s9, 16
	s_add_i32 s20, s20, 16
	s_add_i32 s19, s19, -16
	s_cmp_lg_u32 s19, 0
	s_waitcnt vmcnt(30)
; #define LAS __attribute__((address_space(3)))
; __device__ __forceinline__ unsigned cvt_pk_bf16(float lo, float hi) { f32x2_c v = {lo, hi}; bf16x2_c r = __builtin_convertvector(v, bf16x2_c); return __builtin_bit_cast(unsigned, r); }
; #define LDS_WAIT() asm volatile("s_waitcnt lgkmcnt(0)" ::: "memory")
; __device__ __forceinline__ void transpose_item(const float* W, int N, bf16_t* WT, int dstK, size_t drow0, int kdst0, int k0, int n0, LAS float* scr, int lane) {
;     ...
;     for (int i = 0; i < 32; ++i) { const int kk = 2 * i + (lane >> 5); scr[kk * 33 + (lane & 31)] = W[(size_t)(k0 + kk) * N + n0 + (lane & 31)]; }
;     LDS_WAIT();
;     const int c = lane & 7;
; #pragma unroll
;     for (int j = 0; j < 4; ++j) { const int n = (lane >> 3) + 8 * j; const LAS float* s = scr + (8 * c) * 33 + n;
;         u32x4 o; o.x = cvt_pk_bf16(s[0 * 33], s[1 * 33]); o.y = cvt_pk_bf16(s[2 * 33], s[3 * 33]); o.z = cvt_pk_bf16(s[4 * 33], s[5 * 33]); o.w = cvt_pk_bf16(s[6 * 33], s[7 * 33]);
;         *(u32x4*)(WT + (drow0 + n) * dstK + kdst0 + k0 + 8 * c) = o; }
;     LDS_WAIT();
; __device__ __forceinline__ void transpose_matrix(const float* W, int K, int N, bf16_t* WT, int dstK, int kdst0, int mode, LAS float* scr, int gw, int NGW, int lane) {
;     ...
;     for (int it = gw; it < items; it += NGW) {
;         const int kb = it / nblk, nb = it % nblk, n0 = nb * 32;
;         size_t drow0 = (size_t)n0;
;         if (mode == 1) { const int half = n0 >= DFF ? 1 : 0, nn = n0 - half * DFF; drow0 = (size_t)(nn >> 7) * 256 + half * 128 + (nn & 127); }
;         transpose_item(W, N, WT, dstK, drow0, kdst0, kb * 64, n0, scr, lane);
;     }
	v_mad_u64_u32 v[26:27], s[22:23], v7, s6, v[12:13]
	v_mad_u64_u32 v[28:29], s[22:23], v5, s6, v[12:13]
	v_mad_u64_u32 v[30:31], s[22:23], v19, s6, v[12:13]
	v_mad_u64_u32 v[32:33], s[22:23], v15, s6, v[12:13]
	v_mad_u64_u32 v[34:35], s[22:23], v23, s6, v[12:13]
	v_mad_u64_u32 v[36:37], s[22:23], v21, s6, v[12:13]
	v_mad_u64_u32 v[38:39], s[22:23], v59, s6, v[12:13]
	v_mad_u64_u32 v[40:41], s[22:23], v58, s6, v[12:13]
	v_mad_u64_u32 v[42:43], s[22:23], v61, s6, v[12:13]
	v_mad_u64_u32 v[44:45], s[22:23], v60, s6, v[12:13]
	v_mad_u64_u32 v[46:47], s[22:23], v63, s6, v[12:13]
	v_mad_u64_u32 v[48:49], s[22:23], v62, s6, v[12:13]
	v_mad_u64_u32 v[50:51], s[22:23], v65, s6, v[12:13]
	v_mad_u64_u32 v[52:53], s[22:23], v64, s6, v[12:13]
	v_mad_u64_u32 v[54:55], s[22:23], v67, s6, v[12:13]
	v_mad_u64_u32 v[56:57], s[22:23], v66, s6, v[12:13]
	ds_write_b32 v26, v9
	ds_write_b32 v28, v13
	s_waitcnt vmcnt(29)
	ds_write_b32 v30, v68
	s_waitcnt vmcnt(28)
	ds_write_b32 v32, v69
	s_waitcnt vmcnt(27)
	ds_write_b32 v34, v70
	s_waitcnt vmcnt(26)
	ds_write_b32 v36, v71
	s_waitcnt vmcnt(25)
	ds_write_b32 v38, v72
	s_waitcnt vmcnt(24)
	ds_write_b32 v40, v73
	s_waitcnt vmcnt(23)
	ds_write_b32 v42, v74
	s_waitcnt vmcnt(22)
	ds_write_b32 v44, v75
	s_waitcnt vmcnt(21)
	ds_write_b32 v46, v76
	s_waitcnt vmcnt(20)
	ds_write_b32 v48, v77
	s_waitcnt vmcnt(19)
	ds_write_b32 v50, v78
	s_waitcnt vmcnt(18)
	ds_write_b32 v52, v79
	s_waitcnt vmcnt(17)
	ds_write_b32 v54, v80
	s_waitcnt vmcnt(16)
	ds_write_b32 v56, v81
	s_waitcnt vmcnt(14)
	v_mad_u64_u32 v[96:97], s[22:23], v129, s6, v[12:13]
	v_mad_u64_u32 v[98:99], s[22:23], v128, s6, v[12:13]
	v_mad_u64_u32 v[100:101], s[22:23], v133, s6, v[12:13]
	v_mad_u64_u32 v[102:103], s[22:23], v132, s6, v[12:13]
	v_mad_u64_u32 v[104:105], s[22:23], v135, s6, v[12:13]
	v_mad_u64_u32 v[106:107], s[22:23], v134, s6, v[12:13]
	v_mad_u64_u32 v[108:109], s[22:23], v137, s6, v[12:13]
	v_mad_u64_u32 v[110:111], s[22:23], v136, s6, v[12:13]
	v_mad_u64_u32 v[112:113], s[22:23], v139, s6, v[12:13]
	v_mad_u64_u32 v[114:115], s[22:23], v138, s6, v[12:13]
	v_mad_u64_u32 v[116:117], s[22:23], v141, s6, v[12:13]
	v_mad_u64_u32 v[118:119], s[22:23], v140, s6, v[12:13]
	v_mad_u64_u32 v[120:121], s[22:23], v143, s6, v[12:13]
	v_mad_u64_u32 v[122:123], s[22:23], v142, s6, v[12:13]
	v_mad_u64_u32 v[124:125], s[22:23], v145, s6, v[12:13]
	v_mad_u64_u32 v[126:127], s[22:23], v144, s6, v[12:13]
	ds_write_b32 v96, v130
	ds_write_b32 v98, v131
	s_waitcnt vmcnt(13)
	ds_write_b32 v100, v146
	s_waitcnt vmcnt(12)
	ds_write_b32 v102, v147
	s_waitcnt vmcnt(11)
	ds_write_b32 v104, v148
	s_waitcnt vmcnt(10)
	ds_write_b32 v106, v149
	s_waitcnt vmcnt(9)
	ds_write_b32 v108, v150
	s_waitcnt vmcnt(8)
	ds_write_b32 v110, v151
	s_waitcnt vmcnt(7)
	ds_write_b32 v112, v152
	s_waitcnt vmcnt(6)
	ds_write_b32 v114, v153
	s_waitcnt vmcnt(5)
	ds_write_b32 v116, v154
	s_waitcnt vmcnt(4)
	ds_write_b32 v118, v155
	s_waitcnt vmcnt(3)
	ds_write_b32 v120, v156
	s_waitcnt vmcnt(2)
	ds_write_b32 v122, v157
	s_waitcnt vmcnt(1)
	ds_write_b32 v124, v158
	s_waitcnt vmcnt(0)
	ds_write_b32 v126, v159
	s_cmpk_gt_i32 s0, 0xaf
	s_cselect_b32 s3, 0xffffea00, 0
	s_cselect_b32 s0, 0x80, 0
	s_add_i32 s3, s3, s18
	s_ashr_i32 s20, s3, 7
	s_ashr_i32 s21, s20, 31
	s_waitcnt lgkmcnt(0)
	s_and_b32 s3, s18, 0x60
	s_lshl_b64 s[18:19], s[20:21], 8
	ds_read2_b32 v[28:29], v3 offset0:33 offset1:41
	ds_read2_b32 v[30:31], v3 offset1:8
	ds_read2_b32 v[32:33], v3 offset0:66 offset1:74
	ds_read2_b32 v[34:35], v3 offset0:99 offset1:107
	ds_read2_b32 v[36:37], v3 offset0:132 offset1:140
	ds_read2_b32 v[38:39], v3 offset0:165 offset1:173
	ds_read2_b32 v[40:41], v3 offset0:198 offset1:206
	ds_read2_b32 v[42:43], v3 offset0:231 offset1:239
	s_or_b64 s[18:19], s[18:19], s[0:1]
	s_or_b32 s0, s18, s3
	s_ashr_i32 s3, s2, 31
	v_mov_b32_e32 v47, s19
	v_or_b32_e32 v46, s0, v14
	v_lshl_add_u64 v[44:45], s[2:3], 1, v[16:17]
	v_lshlrev_b64 v[46:47], 12, v[46:47]
	s_waitcnt lgkmcnt(6)
	v_cvt_pk_bf16_f32 v24, v30, v28
	s_waitcnt lgkmcnt(4)
	v_cvt_pk_bf16_f32 v25, v32, v34
	s_waitcnt lgkmcnt(2)
	v_cvt_pk_bf16_f32 v26, v36, v38
	s_waitcnt lgkmcnt(0)
	v_cvt_pk_bf16_f32 v27, v40, v42
	v_lshl_add_u64 v[46:47], v[44:45], 0, v[46:47]
	global_store_dwordx4 v[46:47], v[24:27], off
	v_or_b32_e32 v28, s0, v18
	s_add_i32 s8, s8, s36
	v_cvt_pk_bf16_f32 v24, v31, v29
	v_cvt_pk_bf16_f32 v25, v33, v35
	v_cvt_pk_bf16_f32 v26, v37, v39
	v_cvt_pk_bf16_f32 v27, v41, v43
	v_mov_b32_e32 v29, s19
	ds_read2_b32 v[30:31], v3 offset0:49 offset1:57
	ds_read2_b32 v[32:33], v3 offset0:16 offset1:24
	ds_read2_b32 v[34:35], v3 offset0:82 offset1:90
	ds_read2_b32 v[36:37], v3 offset0:115 offset1:123
	ds_read2_b32 v[38:39], v3 offset0:148 offset1:156
	ds_read2_b32 v[40:41], v3 offset0:181 offset1:189
	ds_read2_b32 v[42:43], v3 offset0:214 offset1:222
	ds_read2_b32 v[46:47], v3 offset0:247 offset1:255
	v_lshlrev_b64 v[28:29], 12, v[28:29]
	v_lshl_add_u64 v[28:29], v[44:45], 0, v[28:29]
	global_store_dwordx4 v[28:29], v[24:27], off
	v_mov_b32_e32 v29, s19
	v_or_b32_e32 v28, s0, v20
	v_lshlrev_b64 v[28:29], 12, v[28:29]
	s_waitcnt lgkmcnt(6)
	v_cvt_pk_bf16_f32 v24, v32, v30
	s_waitcnt lgkmcnt(4)
	v_cvt_pk_bf16_f32 v25, v34, v36
	s_waitcnt lgkmcnt(2)
	v_cvt_pk_bf16_f32 v26, v38, v40
	s_waitcnt lgkmcnt(0)
	v_cvt_pk_bf16_f32 v27, v42, v46
	v_lshl_add_u64 v[28:29], v[44:45], 0, v[28:29]
	global_store_dwordx4 v[28:29], v[24:27], off
	v_mov_b32_e32 v29, s19
	v_or_b32_e32 v28, s0, v22
	v_lshlrev_b64 v[28:29], 12, v[28:29]
	v_cvt_pk_bf16_f32 v24, v33, v31
	v_cvt_pk_bf16_f32 v25, v35, v37
	v_cvt_pk_bf16_f32 v26, v39, v41
	v_cvt_pk_bf16_f32 v27, v43, v47
	v_lshl_add_u64 v[28:29], v[44:45], 0, v[28:29]
	global_store_dwordx4 v[28:29], v[24:27], off
	s_waitcnt lgkmcnt(0)
	s_cmpk_lt_i32 s8, 0x2c00
	s_cbranch_scc1 .LBB0_8

; #define LAS __attribute__((address_space(3)))
; __device__ __forceinline__ void transpose_item(const float* W, int N, bf16_t* WT, int dstK, size_t drow0, int kdst0, int k0, int n0, LAS float* scr, int lane) {
; #pragma unroll 8
;     for (int i = 0; i < 32; ++i) { const int kk = 2 * i + (lane >> 5); scr[kk * 33 + (lane & 31)] = W[(size_t)(k0 + kk) * N + n0 + (lane & 31)]; }
.LBB0_14:
	s_lshl_b32 s10, s20, 1
	s_lshl_b32 s11, s19, 1
	v_or_b32_e32 v5, s10, v1
	v_or_b32_e32 v7, s11, v8
	s_add_i32 s21, s10, 4
	s_add_i32 s22, s11, 4
	s_add_i32 s23, s10, 8
	s_add_i32 s24, s11, 8
	s_add_i32 s25, s10, 12
	s_add_i32 s27, s11, 12
	s_add_i32 s28, s10, 16
	s_add_i32 s29, s11, 16
	s_add_i32 s30, s10, 20
	s_add_i32 s31, s11, 20
	s_add_i32 s33, s10, 24
	s_add_i32 s34, s11, 24
	s_add_i32 s10, s10, 28
	s_add_i32 s11, s11, 28
	v_add_u32_e32 v28, s18, v7
	v_or_b32_e32 v9, s21, v1
	v_or_b32_e32 v13, s22, v8
	v_or_b32_e32 v15, s23, v1
	v_or_b32_e32 v19, s24, v8
	v_or_b32_e32 v21, s25, v1
	v_or_b32_e32 v23, s27, v8
	v_or_b32_e32 v58, s28, v1
	v_or_b32_e32 v59, s29, v8
	v_or_b32_e32 v60, s30, v1
	v_or_b32_e32 v61, s31, v8
	v_or_b32_e32 v62, s33, v1
	v_or_b32_e32 v63, s34, v8
	v_or_b32_e32 v64, s10, v1
	v_or_b32_e32 v65, s11, v8
	v_add_u32_e32 v26, s3, v5
	v_ashrrev_i32_e32 v29, 31, v28
	v_add_u32_e32 v30, s3, v9
	v_add_u32_e32 v32, s18, v13
	v_add_u32_e32 v34, s3, v15
	v_add_u32_e32 v36, s18, v19
	v_add_u32_e32 v38, s3, v21
	v_add_u32_e32 v40, s18, v23
	v_add_u32_e32 v42, s3, v58
	v_add_u32_e32 v44, s18, v59
	v_add_u32_e32 v46, s3, v60
	v_add_u32_e32 v48, s18, v61
	v_add_u32_e32 v50, s3, v62
	v_add_u32_e32 v52, s18, v63
	v_add_u32_e32 v54, s3, v64
	v_add_u32_e32 v56, s18, v65
	v_ashrrev_i32_e32 v27, 31, v26
	v_lshlrev_b64 v[28:29], 13, v[28:29]
	v_ashrrev_i32_e32 v33, 31, v32
	v_ashrrev_i32_e32 v31, 31, v30
	v_ashrrev_i32_e32 v37, 31, v36
	v_ashrrev_i32_e32 v35, 31, v34
	v_ashrrev_i32_e32 v41, 31, v40
	v_ashrrev_i32_e32 v39, 31, v38
	v_ashrrev_i32_e32 v45, 31, v44
	v_ashrrev_i32_e32 v43, 31, v42
	v_ashrrev_i32_e32 v49, 31, v48
	v_ashrrev_i32_e32 v47, 31, v46
	v_ashrrev_i32_e32 v53, 31, v52
	v_ashrrev_i32_e32 v51, 31, v50
	v_ashrrev_i32_e32 v57, 31, v56
	v_ashrrev_i32_e32 v55, 31, v54
	v_lshlrev_b64 v[26:27], 13, v[26:27]
	v_lshl_add_u64 v[28:29], v[24:25], 0, v[28:29]
	v_lshlrev_b64 v[30:31], 13, v[30:31]
	v_lshlrev_b64 v[32:33], 13, v[32:33]
	v_lshlrev_b64 v[34:35], 13, v[34:35]
	v_lshlrev_b64 v[36:37], 13, v[36:37]
	v_lshlrev_b64 v[38:39], 13, v[38:39]
	v_lshlrev_b64 v[40:41], 13, v[40:41]
	v_lshlrev_b64 v[42:43], 13, v[42:43]
	v_lshlrev_b64 v[44:45], 13, v[44:45]
	v_lshlrev_b64 v[46:47], 13, v[46:47]
	v_lshlrev_b64 v[48:49], 13, v[48:49]
	v_lshlrev_b64 v[50:51], 13, v[50:51]
	v_lshlrev_b64 v[52:53], 13, v[52:53]
	v_lshlrev_b64 v[54:55], 13, v[54:55]
	v_lshlrev_b64 v[56:57], 13, v[56:57]
	v_lshl_add_u64 v[26:27], v[24:25], 0, v[26:27]
	v_lshl_add_u64 v[32:33], v[24:25], 0, v[32:33]
	v_lshl_add_u64 v[30:31], v[24:25], 0, v[30:31]
	v_lshl_add_u64 v[36:37], v[24:25], 0, v[36:37]
	v_lshl_add_u64 v[34:35], v[24:25], 0, v[34:35]
	v_lshl_add_u64 v[40:41], v[24:25], 0, v[40:41]
	v_lshl_add_u64 v[38:39], v[24:25], 0, v[38:39]
	v_lshl_add_u64 v[44:45], v[24:25], 0, v[44:45]
	v_lshl_add_u64 v[42:43], v[24:25], 0, v[42:43]
	v_lshl_add_u64 v[48:49], v[24:25], 0, v[48:49]
	v_lshl_add_u64 v[46:47], v[24:25], 0, v[46:47]
	v_lshl_add_u64 v[52:53], v[24:25], 0, v[52:53]
	v_lshl_add_u64 v[50:51], v[24:25], 0, v[50:51]
	v_lshl_add_u64 v[56:57], v[24:25], 0, v[56:57]
	v_lshl_add_u64 v[54:55], v[24:25], 0, v[54:55]
	global_load_dword v66, v[28:29], off
	global_load_dword v67, v[26:27], off
	global_load_dword v68, v[32:33], off
	global_load_dword v69, v[30:31], off
	global_load_dword v70, v[36:37], off
	global_load_dword v71, v[34:35], off
	global_load_dword v72, v[40:41], off
	global_load_dword v73, v[38:39], off
	global_load_dword v74, v[44:45], off
	global_load_dword v75, v[42:43], off
	global_load_dword v76, v[48:49], off
	global_load_dword v77, v[46:47], off
	global_load_dword v78, v[52:53], off
	global_load_dword v79, v[50:51], off
	global_load_dword v80, v[56:57], off
	global_load_dword v81, v[54:55], off
	s_add_i32 s19, s19, 16
	s_add_i32 s20, s20, 16
	s_add_i32 s9, s9, -16
	v_mad_u64_u32 v[26:27], s[22:23], v7, s6, v[12:13]
	s_cmp_lg_u32 s9, 0
	v_mad_u64_u32 v[28:29], s[22:23], v5, s6, v[12:13]
	v_mad_u64_u32 v[30:31], s[22:23], v13, s6, v[12:13]
	v_mad_u64_u32 v[32:33], s[22:23], v9, s6, v[12:13]
	v_mad_u64_u32 v[34:35], s[22:23], v19, s6, v[12:13]
	v_mad_u64_u32 v[36:37], s[22:23], v15, s6, v[12:13]
	v_mad_u64_u32 v[38:39], s[22:23], v23, s6, v[12:13]
	v_mad_u64_u32 v[40:41], s[22:23], v21, s6, v[12:13]
	v_mad_u64_u32 v[42:43], s[22:23], v59, s6, v[12:13]
	v_mad_u64_u32 v[44:45], s[22:23], v58, s6, v[12:13]
	v_mad_u64_u32 v[46:47], s[22:23], v61, s6, v[12:13]
	v_mad_u64_u32 v[48:49], s[22:23], v60, s6, v[12:13]
	v_mad_u64_u32 v[50:51], s[22:23], v63, s6, v[12:13]
	v_mad_u64_u32 v[52:53], s[22:23], v62, s6, v[12:13]
	v_mad_u64_u32 v[54:55], s[22:23], v65, s6, v[12:13]
	v_mad_u64_u32 v[56:57], s[22:23], v64, s6, v[12:13]
	s_lshl_b32 s10, s20, 1
	s_lshl_b32 s11, s19, 1
	v_or_b32_e32 v128, s10, v1
	v_or_b32_e32 v129, s11, v8
	s_add_i32 s21, s10, 4
	s_add_i32 s22, s11, 4
	s_add_i32 s23, s10, 8
	s_add_i32 s24, s11, 8
	s_add_i32 s25, s10, 12
	s_add_i32 s27, s11, 12
	s_add_i32 s28, s10, 16
	s_add_i32 s29, s11, 16
	s_add_i32 s30, s10, 20
	s_add_i32 s31, s11, 20
	s_add_i32 s33, s10, 24
	s_add_i32 s34, s11, 24
	s_add_i32 s10, s10, 28
	s_add_i32 s11, s11, 28
	v_add_u32_e32 v98, s18, v129
	v_or_b32_e32 v130, s21, v1
	v_or_b32_e32 v131, s22, v8
	v_or_b32_e32 v132, s23, v1
	v_or_b32_e32 v133, s24, v8
	v_or_b32_e32 v134, s25, v1
	v_or_b32_e32 v135, s27, v8
	v_or_b32_e32 v136, s28, v1
	v_or_b32_e32 v137, s29, v8
	v_or_b32_e32 v138, s30, v1
	v_or_b32_e32 v139, s31, v8
	v_or_b32_e32 v140, s33, v1
	v_or_b32_e32 v141, s34, v8
	v_or_b32_e32 v142, s10, v1
	v_or_b32_e32 v143, s11, v8
	v_add_u32_e32 v96, s3, v128
	v_ashrrev_i32_e32 v99, 31, v98
	v_add_u32_e32 v100, s3, v130
; #define LDS_WAIT() asm volatile("s_waitcnt lgkmcnt(0)" ::: "memory")
; __device__ __forceinline__ void transpose_item(const float* W, int N, bf16_t* WT, int dstK, size_t drow0, int kdst0, int k0, int n0, LAS float* scr, int lane) {
;     ...
;     for (int i = 0; i < 32; ++i) { const int kk = 2 * i + (lane >> 5); scr[kk * 33 + (lane & 31)] = W[(size_t)(k0 + kk) * N + n0 + (lane & 31)]; }
;     LDS_WAIT();
	v_add_u32_e32 v102, s18, v131
	v_add_u32_e32 v104, s3, v132
	v_add_u32_e32 v106, s18, v133
	v_add_u32_e32 v108, s3, v134
	v_add_u32_e32 v110, s18, v135
	v_add_u32_e32 v112, s3, v136
	v_add_u32_e32 v114, s18, v137
	v_add_u32_e32 v116, s3, v138
	v_add_u32_e32 v118, s18, v139
	v_add_u32_e32 v120, s3, v140
	v_add_u32_e32 v122, s18, v141
	v_add_u32_e32 v124, s3, v142
	v_add_u32_e32 v126, s18, v143
	v_ashrrev_i32_e32 v97, 31, v96
	v_lshlrev_b64 v[98:99], 13, v[98:99]
	v_ashrrev_i32_e32 v103, 31, v102
	v_ashrrev_i32_e32 v101, 31, v100
	v_ashrrev_i32_e32 v107, 31, v106
	v_ashrrev_i32_e32 v105, 31, v104
	v_ashrrev_i32_e32 v111, 31, v110
	v_ashrrev_i32_e32 v109, 31, v108
	v_ashrrev_i32_e32 v115, 31, v114
	v_ashrrev_i32_e32 v113, 31, v112
	v_ashrrev_i32_e32 v119, 31, v118
	v_ashrrev_i32_e32 v117, 31, v116
	v_ashrrev_i32_e32 v123, 31, v122
	v_ashrrev_i32_e32 v121, 31, v120
	v_ashrrev_i32_e32 v127, 31, v126
	v_ashrrev_i32_e32 v125, 31, v124
	v_lshlrev_b64 v[96:97], 13, v[96:97]
	v_lshl_add_u64 v[98:99], v[24:25], 0, v[98:99]
	v_lshlrev_b64 v[100:101], 13, v[100:101]
	v_lshlrev_b64 v[102:103], 13, v[102:103]
	v_lshlrev_b64 v[104:105], 13, v[104:105]
	v_lshlrev_b64 v[106:107], 13, v[106:107]
	v_lshlrev_b64 v[108:109], 13, v[108:109]
	v_lshlrev_b64 v[110:111], 13, v[110:111]
	v_lshlrev_b64 v[112:113], 13, v[112:113]
	v_lshlrev_b64 v[114:115], 13, v[114:115]
	v_lshlrev_b64 v[116:117], 13, v[116:117]
	v_lshlrev_b64 v[118:119], 13, v[118:119]
	v_lshlrev_b64 v[120:121], 13, v[120:121]
	v_lshlrev_b64 v[122:123], 13, v[122:123]
	v_lshlrev_b64 v[124:125], 13, v[124:125]
	v_lshlrev_b64 v[126:127], 13, v[126:127]
	v_lshl_add_u64 v[96:97], v[24:25], 0, v[96:97]
	v_lshl_add_u64 v[102:103], v[24:25], 0, v[102:103]
	v_lshl_add_u64 v[100:101], v[24:25], 0, v[100:101]
	v_lshl_add_u64 v[106:107], v[24:25], 0, v[106:107]
	v_lshl_add_u64 v[104:105], v[24:25], 0, v[104:105]
	v_lshl_add_u64 v[110:111], v[24:25], 0, v[110:111]
	v_lshl_add_u64 v[108:109], v[24:25], 0, v[108:109]
	v_lshl_add_u64 v[114:115], v[24:25], 0, v[114:115]
	v_lshl_add_u64 v[112:113], v[24:25], 0, v[112:113]
	v_lshl_add_u64 v[118:119], v[24:25], 0, v[118:119]
	v_lshl_add_u64 v[116:117], v[24:25], 0, v[116:117]
	v_lshl_add_u64 v[122:123], v[24:25], 0, v[122:123]
	v_lshl_add_u64 v[120:121], v[24:25], 0, v[120:121]
	v_lshl_add_u64 v[126:127], v[24:25], 0, v[126:127]
	v_lshl_add_u64 v[124:125], v[24:25], 0, v[124:125]
	global_load_dword v144, v[98:99], off
	global_load_dword v145, v[96:97], off
	global_load_dword v146, v[102:103], off
	global_load_dword v147, v[100:101], off
	global_load_dword v148, v[106:107], off
	global_load_dword v149, v[104:105], off
	global_load_dword v150, v[110:111], off
	global_load_dword v151, v[108:109], off
	global_load_dword v152, v[114:115], off
	global_load_dword v153, v[112:113], off
	global_load_dword v154, v[118:119], off
	global_load_dword v155, v[116:117], off
	global_load_dword v156, v[122:123], off
	global_load_dword v157, v[120:121], off
	global_load_dword v158, v[126:127], off
	global_load_dword v159, v[124:125], off
	s_add_i32 s19, s19, 16
	s_add_i32 s20, s20, 16
	s_add_i32 s9, s9, -16
	v_mad_u64_u32 v[96:97], s[22:23], v129, s6, v[12:13]
	s_cmp_lg_u32 s9, 0
	v_mad_u64_u32 v[98:99], s[22:23], v128, s6, v[12:13]
	v_mad_u64_u32 v[100:101], s[22:23], v131, s6, v[12:13]
	v_mad_u64_u32 v[102:103], s[22:23], v130, s6, v[12:13]
	v_mad_u64_u32 v[104:105], s[22:23], v133, s6, v[12:13]
	v_mad_u64_u32 v[106:107], s[22:23], v132, s6, v[12:13]
	v_mad_u64_u32 v[108:109], s[22:23], v135, s6, v[12:13]
	v_mad_u64_u32 v[110:111], s[22:23], v134, s6, v[12:13]
	v_mad_u64_u32 v[112:113], s[22:23], v137, s6, v[12:13]
	v_mad_u64_u32 v[114:115], s[22:23], v136, s6, v[12:13]
	v_mad_u64_u32 v[116:117], s[22:23], v139, s6, v[12:13]
	v_mad_u64_u32 v[118:119], s[22:23], v138, s6, v[12:13]
	v_mad_u64_u32 v[120:121], s[22:23], v141, s6, v[12:13]
	v_mad_u64_u32 v[122:123], s[22:23], v140, s6, v[12:13]
	v_mad_u64_u32 v[124:125], s[22:23], v143, s6, v[12:13]
	v_mad_u64_u32 v[126:127], s[22:23], v142, s6, v[12:13]
	s_waitcnt vmcnt(31)
	ds_write_b32 v26, v66
	s_waitcnt vmcnt(30)
; #define LAS __attribute__((address_space(3)))
; __device__ __forceinline__ unsigned cvt_pk_bf16(float lo, float hi) { f32x2_c v = {lo, hi}; bf16x2_c r = __builtin_convertvector(v, bf16x2_c); return __builtin_bit_cast(unsigned, r); }
; #define LDS_WAIT() asm volatile("s_waitcnt lgkmcnt(0)" ::: "memory")
; __device__ __forceinline__ void transpose_item(const float* W, int N, bf16_t* WT, int dstK, size_t drow0, int kdst0, int k0, int n0, LAS float* scr, int lane) {
;     ...
;     for (int i = 0; i < 32; ++i) { const int kk = 2 * i + (lane >> 5); scr[kk * 33 + (lane & 31)] = W[(size_t)(k0 + kk) * N + n0 + (lane & 31)]; }
;     LDS_WAIT();
;     const int c = lane & 7;
; #pragma unroll
;     for (int j = 0; j < 4; ++j) { const int n = (lane >> 3) + 8 * j; const LAS float* s = scr + (8 * c) * 33 + n;
;         u32x4 o; o.x = cvt_pk_bf16(s[0 * 33], s[1 * 33]); o.y = cvt_pk_bf16(s[2 * 33], s[3 * 33]); o.z = cvt_pk_bf16(s[4 * 33], s[5 * 33]); o.w = cvt_pk_bf16(s[6 * 33], s[7 * 33]);
;         *(u32x4*)(WT + (drow0 + n) * dstK + kdst0 + k0 + 8 * c) = o; }
;     LDS_WAIT();
; }
; __device__ __forceinline__ void transpose_matrix(const float* W, int K, int N, bf16_t* WT, int dstK, int kdst0, int mode, LAS float* scr, int gw, int NGW, int lane) {
;     ...
;     for (int it = gw; it < items; it += NGW) {
;         const int kb = it / nblk, nb = it % nblk, n0 = nb * 32;
;         size_t drow0 = (size_t)n0;
;         if (mode == 1) { const int half = n0 >= DFF ? 1 : 0, nn = n0 - half * DFF; drow0 = (size_t)(nn >> 7) * 256 + half * 128 + (nn & 127); }
;         transpose_item(W, N, WT, dstK, drow0, kdst0, kb * 64, n0, scr, lane);
;     }
	ds_write_b32 v28, v67
	s_waitcnt vmcnt(29)
	ds_write_b32 v30, v68
	s_waitcnt vmcnt(28)
	ds_write_b32 v32, v69
	s_waitcnt vmcnt(27)
	ds_write_b32 v34, v70
	s_waitcnt vmcnt(26)
	ds_write_b32 v36, v71
	s_waitcnt vmcnt(25)
	ds_write_b32 v38, v72
	s_waitcnt vmcnt(24)
	ds_write_b32 v40, v73
	s_waitcnt vmcnt(23)
	ds_write_b32 v42, v74
	s_waitcnt vmcnt(22)
	ds_write_b32 v44, v75
	s_waitcnt vmcnt(21)
	ds_write_b32 v46, v76
	s_waitcnt vmcnt(20)
	ds_write_b32 v48, v77
	s_waitcnt vmcnt(19)
	ds_write_b32 v50, v78
	s_waitcnt vmcnt(18)
	ds_write_b32 v52, v79
	s_waitcnt vmcnt(17)
	ds_write_b32 v54, v80
	s_waitcnt vmcnt(16)
	ds_write_b32 v56, v81
	s_waitcnt vmcnt(15)
	ds_write_b32 v96, v144
	s_waitcnt vmcnt(14)
	ds_write_b32 v98, v145
	s_waitcnt vmcnt(13)
	ds_write_b32 v100, v146
	s_waitcnt vmcnt(12)
	ds_write_b32 v102, v147
	s_waitcnt vmcnt(11)
	ds_write_b32 v104, v148
	s_waitcnt vmcnt(10)
	ds_write_b32 v106, v149
	s_waitcnt vmcnt(9)
	ds_write_b32 v108, v150
	s_waitcnt vmcnt(8)
	ds_write_b32 v110, v151
	s_waitcnt vmcnt(7)
	ds_write_b32 v112, v152
	s_waitcnt vmcnt(6)
	ds_write_b32 v114, v153
	s_waitcnt vmcnt(5)
	ds_write_b32 v116, v154
	s_waitcnt vmcnt(4)
	ds_write_b32 v118, v155
	s_waitcnt vmcnt(3)
	ds_write_b32 v120, v156
	s_waitcnt vmcnt(2)
	ds_write_b32 v122, v157
	s_waitcnt vmcnt(1)
	ds_write_b32 v124, v158
	s_waitcnt vmcnt(0)
	ds_write_b32 v126, v159
	s_waitcnt lgkmcnt(0)
	ds_read2_b32 v[28:29], v3 offset0:33 offset1:41
	ds_read2_b32 v[30:31], v3 offset1:8
	ds_read2_b32 v[32:33], v3 offset0:66 offset1:74
	ds_read2_b32 v[34:35], v3 offset0:99 offset1:107
	ds_read2_b32 v[36:37], v3 offset0:132 offset1:140
	ds_read2_b32 v[38:39], v3 offset0:165 offset1:173
	ds_read2_b32 v[40:41], v3 offset0:198 offset1:206
	ds_read2_b32 v[42:43], v3 offset0:231 offset1:239
	s_ashr_i32 s19, s18, 31
	v_lshl_add_u64 v[44:45], s[18:19], 1, v[16:17]
	v_or_b32_e32 v5, s2, v14
	s_waitcnt lgkmcnt(6)
	v_cvt_pk_bf16_f32 v24, v30, v28
	s_waitcnt lgkmcnt(4)
	v_cvt_pk_bf16_f32 v25, v32, v34
	s_waitcnt lgkmcnt(2)
	v_cvt_pk_bf16_f32 v26, v36, v38
	s_waitcnt lgkmcnt(0)
	v_cvt_pk_bf16_f32 v27, v40, v42
	v_mad_i64_i32 v[46:47], s[18:19], v5, s7, v[44:45]
	global_store_dwordx4 v[46:47], v[24:27], off
	v_or_b32_e32 v5, s2, v18
	s_add_i32 s8, s8, s36
	v_cvt_pk_bf16_f32 v24, v31, v29
	v_cvt_pk_bf16_f32 v25, v33, v35
	v_cvt_pk_bf16_f32 v26, v37, v39
	v_cvt_pk_bf16_f32 v27, v41, v43
	ds_read2_b32 v[30:31], v3 offset0:49 offset1:57
	ds_read2_b32 v[32:33], v3 offset0:16 offset1:24
	ds_read2_b32 v[34:35], v3 offset0:82 offset1:90
	ds_read2_b32 v[36:37], v3 offset0:115 offset1:123
	ds_read2_b32 v[38:39], v3 offset0:148 offset1:156
	ds_read2_b32 v[40:41], v3 offset0:181 offset1:189
	ds_read2_b32 v[42:43], v3 offset0:214 offset1:222
	ds_read2_b32 v[46:47], v3 offset0:247 offset1:255
	v_mad_i64_i32 v[28:29], s[18:19], v5, s7, v[44:45]
	v_or_b32_e32 v5, s2, v20
	global_store_dwordx4 v[28:29], v[24:27], off
	v_mad_i64_i32 v[28:29], s[18:19], v5, s7, v[44:45]
	s_waitcnt lgkmcnt(6)
	v_cvt_pk_bf16_f32 v24, v32, v30
	s_waitcnt lgkmcnt(4)
	v_cvt_pk_bf16_f32 v25, v34, v36
	s_waitcnt lgkmcnt(2)
	v_cvt_pk_bf16_f32 v26, v38, v40
	s_waitcnt lgkmcnt(0)
	v_cvt_pk_bf16_f32 v27, v42, v46
	v_or_b32_e32 v5, s2, v22
	global_store_dwordx4 v[28:29], v[24:27], off
	v_mad_i64_i32 v[28:29], s[2:3], v5, s7, v[44:45]
	s_nop 0
	v_cvt_pk_bf16_f32 v24, v33, v31
	v_cvt_pk_bf16_f32 v25, v35, v37
	v_cvt_pk_bf16_f32 v26, v39, v41
	v_cvt_pk_bf16_f32 v27, v43, v47
	global_store_dwordx4 v[28:29], v[24:27], off
	s_waitcnt lgkmcnt(0)
	s_cmpk_lt_i32 s8, 0x1600
	s_cbranch_scc1 .LBB0_13
	v_readlane_b32 s48, v245, 24
	v_readlane_b32 s49, v245, 25
	v_readlane_b32 s56, v245, 32
	v_readlane_b32 s57, v245, 33
	v_readlane_b32 s60, v245, 36
	v_readlane_b32 s61, v245, 37
	v_readlane_b32 s50, v245, 26
	v_readlane_b32 s51, v245, 27
	v_readlane_b32 s52, v245, 28
	v_readlane_b32 s53, v245, 29
	v_readlane_b32 s54, v245, 30
	v_readlane_b32 s55, v245, 31
	v_readlane_b32 s58, v245, 34
	v_readlane_b32 s59, v245, 35
	v_readlane_b32 s62, v245, 38
	v_readlane_b32 s63, v245, 39
	s_cmpk_gt_i32 s38, 0x27ff
	s_cbranch_scc0 .LBB0_19

; #define LAS __attribute__((address_space(3)))
; __device__ __forceinline__ void transpose_item(const float* W, int N, bf16_t* WT, int dstK, size_t drow0, int kdst0, int k0, int n0, LAS float* scr, int lane) {
; #pragma unroll 8
;     for (int i = 0; i < 32; ++i) { const int kk = 2 * i + (lane >> 5); scr[kk * 33 + (lane & 31)] = W[(size_t)(k0 + kk) * N + n0 + (lane & 31)]; }
.LBB0_21:
	s_lshl_b32 s10, s21, 1
	s_lshl_b32 s11, s20, 1
	v_or_b32_e32 v5, s10, v1
	v_or_b32_e32 v7, s11, v8
	s_add_i32 s22, s10, 4
	s_add_i32 s23, s11, 4
	s_add_i32 s24, s10, 8
	s_add_i32 s25, s11, 8
	s_add_i32 s27, s10, 12
	s_add_i32 s28, s11, 12
	s_add_i32 s29, s10, 16
	s_add_i32 s30, s11, 16
	s_add_i32 s31, s10, 20
	s_add_i32 s33, s11, 20
	s_add_i32 s34, s10, 24
	s_add_i32 s35, s11, 24
	s_add_i32 s10, s10, 28
	s_add_i32 s11, s11, 28
	v_add_u32_e32 v9, s9, v5
	v_add_u32_e32 v13, s18, v7
	v_or_b32_e32 v15, s22, v1
	v_or_b32_e32 v19, s23, v8
	v_or_b32_e32 v21, s24, v1
	v_or_b32_e32 v23, s25, v8
	v_or_b32_e32 v58, s27, v1
	v_or_b32_e32 v59, s28, v8
	v_or_b32_e32 v60, s29, v1
	v_or_b32_e32 v61, s30, v8
	v_or_b32_e32 v62, s31, v1
	v_or_b32_e32 v63, s33, v8
	v_or_b32_e32 v64, s34, v1
	v_or_b32_e32 v65, s35, v8
	v_or_b32_e32 v66, s10, v1
	v_or_b32_e32 v67, s11, v8
	v_mad_i64_i32 v[26:27], s[22:23], v13, s7, v[24:25]
	v_mad_i64_i32 v[28:29], s[22:23], v9, s7, v[24:25]
	v_add_u32_e32 v9, s9, v15
	v_add_u32_e32 v13, s18, v19
	v_add_u32_e32 v36, s9, v21
	v_add_u32_e32 v34, s18, v23
	v_add_u32_e32 v40, s9, v58
	v_add_u32_e32 v38, s18, v59
	v_add_u32_e32 v44, s9, v60
	v_add_u32_e32 v42, s18, v61
	v_add_u32_e32 v48, s9, v62
	v_add_u32_e32 v46, s18, v63
	v_add_u32_e32 v52, s9, v64
	v_add_u32_e32 v50, s18, v65
	v_add_u32_e32 v56, s9, v66
	v_add_u32_e32 v54, s18, v67
	v_mad_i64_i32 v[30:31], s[22:23], v13, s7, v[24:25]
	v_mad_i64_i32 v[32:33], s[22:23], v9, s7, v[24:25]
	v_mad_i64_i32 v[34:35], s[22:23], v34, s7, v[24:25]
	v_mad_i64_i32 v[36:37], s[22:23], v36, s7, v[24:25]
	v_mad_i64_i32 v[38:39], s[22:23], v38, s7, v[24:25]
	v_mad_i64_i32 v[40:41], s[22:23], v40, s7, v[24:25]
	v_mad_i64_i32 v[42:43], s[22:23], v42, s7, v[24:25]
	v_mad_i64_i32 v[44:45], s[22:23], v44, s7, v[24:25]
	v_mad_i64_i32 v[46:47], s[22:23], v46, s7, v[24:25]
	v_mad_i64_i32 v[48:49], s[22:23], v48, s7, v[24:25]
	v_mad_i64_i32 v[50:51], s[22:23], v50, s7, v[24:25]
	v_mad_i64_i32 v[52:53], s[22:23], v52, s7, v[24:25]
	v_mad_i64_i32 v[54:55], s[22:23], v54, s7, v[24:25]
	v_mad_i64_i32 v[56:57], s[22:23], v56, s7, v[24:25]
	global_load_dword v9, v[26:27], off
	global_load_dword v13, v[28:29], off
	global_load_dword v68, v[30:31], off
	global_load_dword v69, v[32:33], off
	global_load_dword v70, v[34:35], off
	global_load_dword v71, v[36:37], off
	global_load_dword v72, v[38:39], off
	global_load_dword v73, v[40:41], off
	global_load_dword v74, v[42:43], off
	global_load_dword v75, v[44:45], off
	global_load_dword v76, v[46:47], off
	global_load_dword v77, v[48:49], off
	global_load_dword v78, v[50:51], off
	global_load_dword v79, v[52:53], off
	global_load_dword v80, v[54:55], off
	global_load_dword v81, v[56:57], off
	s_add_i32 s20, s20, 16
	s_add_i32 s21, s21, 16
	s_add_i32 s19, s19, -16
	s_cmp_lg_u32 s19, 0
	s_lshl_b32 s10, s21, 1
	s_lshl_b32 s11, s20, 1
	v_or_b32_e32 v128, s10, v1
	v_or_b32_e32 v129, s11, v8
	s_add_i32 s22, s10, 4
	s_add_i32 s23, s11, 4
	s_add_i32 s24, s10, 8
	s_add_i32 s25, s11, 8
	s_add_i32 s27, s10, 12
	s_add_i32 s28, s11, 12
	s_add_i32 s29, s10, 16
	s_add_i32 s30, s11, 16
	s_add_i32 s31, s10, 20
	s_add_i32 s33, s11, 20
	s_add_i32 s34, s10, 24
	s_add_i32 s35, s11, 24
	s_add_i32 s10, s10, 28
	s_add_i32 s11, s11, 28
	v_add_u32_e32 v130, s9, v128
	v_add_u32_e32 v131, s18, v129
	v_or_b32_e32 v132, s22, v1
	v_or_b32_e32 v133, s23, v8
	v_or_b32_e32 v134, s24, v1
	v_or_b32_e32 v135, s25, v8
	v_or_b32_e32 v136, s27, v1
	v_or_b32_e32 v137, s28, v8
	v_or_b32_e32 v138, s29, v1
	v_or_b32_e32 v139, s30, v8
	v_or_b32_e32 v140, s31, v1
	v_or_b32_e32 v141, s33, v8
	v_or_b32_e32 v142, s34, v1
	v_or_b32_e32 v143, s35, v8
	v_or_b32_e32 v144, s10, v1
	v_or_b32_e32 v145, s11, v8
	v_mad_i64_i32 v[96:97], s[22:23], v131, s7, v[24:25]
	v_mad_i64_i32 v[98:99], s[22:23], v130, s7, v[24:25]
	v_add_u32_e32 v130, s9, v132
	v_add_u32_e32 v131, s18, v133
	v_add_u32_e32 v106, s9, v134
	v_add_u32_e32 v104, s18, v135
	v_add_u32_e32 v110, s9, v136
	v_add_u32_e32 v108, s18, v137
	v_add_u32_e32 v114, s9, v138
	v_add_u32_e32 v112, s18, v139
	v_add_u32_e32 v118, s9, v140
	v_add_u32_e32 v116, s18, v141
	v_add_u32_e32 v122, s9, v142
	v_add_u32_e32 v120, s18, v143
	v_add_u32_e32 v126, s9, v144
	v_add_u32_e32 v124, s18, v145
	v_mad_i64_i32 v[100:101], s[22:23], v131, s7, v[24:25]
	v_mad_i64_i32 v[102:103], s[22:23], v130, s7, v[24:25]
	v_mad_i64_i32 v[104:105], s[22:23], v104, s7, v[24:25]
	v_mad_i64_i32 v[106:107], s[22:23], v106, s7, v[24:25]
	v_mad_i64_i32 v[108:109], s[22:23], v108, s7, v[24:25]
	v_mad_i64_i32 v[110:111], s[22:23], v110, s7, v[24:25]
	v_mad_i64_i32 v[112:113], s[22:23], v112, s7, v[24:25]
	v_mad_i64_i32 v[114:115], s[22:23], v114, s7, v[24:25]
	v_mad_i64_i32 v[116:117], s[22:23], v116, s7, v[24:25]
	v_mad_i64_i32 v[118:119], s[22:23], v118, s7, v[24:25]
	v_mad_i64_i32 v[120:121], s[22:23], v120, s7, v[24:25]
	v_mad_i64_i32 v[122:123], s[22:23], v122, s7, v[24:25]
	v_mad_i64_i32 v[124:125], s[22:23], v124, s7, v[24:25]
	v_mad_i64_i32 v[126:127], s[22:23], v126, s7, v[24:25]
	global_load_dword v130, v[96:97], off
	global_load_dword v131, v[98:99], off
	global_load_dword v146, v[100:101], off
	global_load_dword v147, v[102:103], off
	global_load_dword v148, v[104:105], off
	global_load_dword v149, v[106:107], off
	global_load_dword v150, v[108:109], off
	global_load_dword v151, v[110:111], off
	global_load_dword v152, v[112:113], off
	global_load_dword v153, v[114:115], off
	global_load_dword v154, v[116:117], off
	global_load_dword v155, v[118:119], off
	global_load_dword v156, v[120:121], off
	global_load_dword v157, v[122:123], off
	global_load_dword v158, v[124:125], off
	global_load_dword v159, v[126:127], off
	s_add_i32 s20, s20, 16
	s_add_i32 s21, s21, 16
	s_add_i32 s19, s19, -16
	s_cmp_lg_u32 s19, 0
	s_waitcnt vmcnt(30)
; #define LAS __attribute__((address_space(3)))
; __device__ __forceinline__ unsigned cvt_pk_bf16(float lo, float hi) { f32x2_c v = {lo, hi}; bf16x2_c r = __builtin_convertvector(v, bf16x2_c); return __builtin_bit_cast(unsigned, r); }
; #define LDS_WAIT() asm volatile("s_waitcnt lgkmcnt(0)" ::: "memory")
; __device__ __forceinline__ void transpose_item(const float* W, int N, bf16_t* WT, int dstK, size_t drow0, int kdst0, int k0, int n0, LAS float* scr, int lane) {
;     ...
;     for (int i = 0; i < 32; ++i) { const int kk = 2 * i + (lane >> 5); scr[kk * 33 + (lane & 31)] = W[(size_t)(k0 + kk) * N + n0 + (lane & 31)]; }
;     LDS_WAIT();
;     const int c = lane & 7;
; #pragma unroll
;     for (int j = 0; j < 4; ++j) { const int n = (lane >> 3) + 8 * j; const LAS float* s = scr + (8 * c) * 33 + n;
;         u32x4 o; o.x = cvt_pk_bf16(s[0 * 33], s[1 * 33]); o.y = cvt_pk_bf16(s[2 * 33], s[3 * 33]); o.z = cvt_pk_bf16(s[4 * 33], s[5 * 33]); o.w = cvt_pk_bf16(s[6 * 33], s[7 * 33]);
;         *(u32x4*)(WT + (drow0 + n) * dstK + kdst0 + k0 + 8 * c) = o; }
;     LDS_WAIT();
; __device__ __forceinline__ void transpose_matrix(const float* W, int K, int N, bf16_t* WT, int dstK, int kdst0, int mode, LAS float* scr, int gw, int NGW, int lane) {
;     ...
;     for (int it = gw; it < items; it += NGW) {
;         const int kb = it / nblk, nb = it % nblk, n0 = nb * 32;
;         size_t drow0 = (size_t)n0;
;         if (mode == 1) { const int half = n0 >= DFF ? 1 : 0, nn = n0 - half * DFF; drow0 = (size_t)(nn >> 7) * 256 + half * 128 + (nn & 127); }
;         transpose_item(W, N, WT, dstK, drow0, kdst0, kb * 64, n0, scr, lane);
;     }
	v_mad_u64_u32 v[26:27], s[22:23], v7, s6, v[12:13]
	v_mad_u64_u32 v[28:29], s[22:23], v5, s6, v[12:13]
	v_mad_u64_u32 v[30:31], s[22:23], v19, s6, v[12:13]
	v_mad_u64_u32 v[32:33], s[22:23], v15, s6, v[12:13]
	v_mad_u64_u32 v[34:35], s[22:23], v23, s6, v[12:13]
	v_mad_u64_u32 v[36:37], s[22:23], v21, s6, v[12:13]
	v_mad_u64_u32 v[38:39], s[22:23], v59, s6, v[12:13]
	v_mad_u64_u32 v[40:41], s[22:23], v58, s6, v[12:13]
	v_mad_u64_u32 v[42:43], s[22:23], v61, s6, v[12:13]
	v_mad_u64_u32 v[44:45], s[22:23], v60, s6, v[12:13]
	v_mad_u64_u32 v[46:47], s[22:23], v63, s6, v[12:13]
	v_mad_u64_u32 v[48:49], s[22:23], v62, s6, v[12:13]
	v_mad_u64_u32 v[50:51], s[22:23], v65, s6, v[12:13]
	v_mad_u64_u32 v[52:53], s[22:23], v64, s6, v[12:13]
	v_mad_u64_u32 v[54:55], s[22:23], v67, s6, v[12:13]
	v_mad_u64_u32 v[56:57], s[22:23], v66, s6, v[12:13]
	ds_write_b32 v26, v9
	ds_write_b32 v28, v13
	s_waitcnt vmcnt(29)
	ds_write_b32 v30, v68
	s_waitcnt vmcnt(28)
	ds_write_b32 v32, v69
	s_waitcnt vmcnt(27)
	ds_write_b32 v34, v70
	s_waitcnt vmcnt(26)
	ds_write_b32 v36, v71
	s_waitcnt vmcnt(25)
	ds_write_b32 v38, v72
	s_waitcnt vmcnt(24)
	ds_write_b32 v40, v73
	s_waitcnt vmcnt(23)
	ds_write_b32 v42, v74
	s_waitcnt vmcnt(22)
	ds_write_b32 v44, v75
	s_waitcnt vmcnt(21)
	ds_write_b32 v46, v76
	s_waitcnt vmcnt(20)
	ds_write_b32 v48, v77
	s_waitcnt vmcnt(19)
	ds_write_b32 v50, v78
	s_waitcnt vmcnt(18)
	ds_write_b32 v52, v79
	s_waitcnt vmcnt(17)
	ds_write_b32 v54, v80
	s_waitcnt vmcnt(16)
	ds_write_b32 v56, v81
	s_waitcnt vmcnt(14)
	v_mad_u64_u32 v[96:97], s[22:23], v129, s6, v[12:13]
	v_mad_u64_u32 v[98:99], s[22:23], v128, s6, v[12:13]
	v_mad_u64_u32 v[100:101], s[22:23], v133, s6, v[12:13]
	v_mad_u64_u32 v[102:103], s[22:23], v132, s6, v[12:13]
	v_mad_u64_u32 v[104:105], s[22:23], v135, s6, v[12:13]
	v_mad_u64_u32 v[106:107], s[22:23], v134, s6, v[12:13]
	v_mad_u64_u32 v[108:109], s[22:23], v137, s6, v[12:13]
	v_mad_u64_u32 v[110:111], s[22:23], v136, s6, v[12:13]
	v_mad_u64_u32 v[112:113], s[22:23], v139, s6, v[12:13]
	v_mad_u64_u32 v[114:115], s[22:23], v138, s6, v[12:13]
	v_mad_u64_u32 v[116:117], s[22:23], v141, s6, v[12:13]
	v_mad_u64_u32 v[118:119], s[22:23], v140, s6, v[12:13]
	v_mad_u64_u32 v[120:121], s[22:23], v143, s6, v[12:13]
	v_mad_u64_u32 v[122:123], s[22:23], v142, s6, v[12:13]
	v_mad_u64_u32 v[124:125], s[22:23], v145, s6, v[12:13]
	v_mad_u64_u32 v[126:127], s[22:23], v144, s6, v[12:13]
	ds_write_b32 v96, v130
	ds_write_b32 v98, v131
	s_waitcnt vmcnt(13)
	ds_write_b32 v100, v146
	s_waitcnt vmcnt(12)
	ds_write_b32 v102, v147
	s_waitcnt vmcnt(11)
	ds_write_b32 v104, v148
	s_waitcnt vmcnt(10)
	ds_write_b32 v106, v149
	s_waitcnt vmcnt(9)
	ds_write_b32 v108, v150
	s_waitcnt vmcnt(8)
	ds_write_b32 v110, v151
	s_waitcnt vmcnt(7)
	ds_write_b32 v112, v152
	s_waitcnt vmcnt(6)
	ds_write_b32 v114, v153
	s_waitcnt vmcnt(5)
	ds_write_b32 v116, v154
	s_waitcnt vmcnt(4)
	ds_write_b32 v118, v155
	s_waitcnt vmcnt(3)
	ds_write_b32 v120, v156
	s_waitcnt vmcnt(2)
	ds_write_b32 v122, v157
	s_waitcnt vmcnt(1)
	ds_write_b32 v124, v158
	s_waitcnt vmcnt(0)
	ds_write_b32 v126, v159
	s_waitcnt lgkmcnt(0)
	ds_read2_b32 v[28:29], v3 offset0:33 offset1:41
	ds_read2_b32 v[30:31], v3 offset1:8
	ds_read2_b32 v[32:33], v3 offset0:66 offset1:74
	ds_read2_b32 v[34:35], v3 offset0:99 offset1:107
	ds_read2_b32 v[36:37], v3 offset0:132 offset1:140
	ds_read2_b32 v[38:39], v3 offset0:165 offset1:173
	ds_read2_b32 v[40:41], v3 offset0:198 offset1:206
	ds_read2_b32 v[42:43], v3 offset0:231 offset1:239
	s_ashr_i32 s19, s18, 31
	v_mov_b32_e32 v47, s3
	v_or_b32_e32 v46, s2, v14
	v_lshl_add_u64 v[44:45], s[18:19], 1, v[16:17]
	v_lshlrev_b64 v[46:47], 12, v[46:47]
	s_waitcnt lgkmcnt(6)
	v_cvt_pk_bf16_f32 v24, v30, v28
	s_waitcnt lgkmcnt(4)
	v_cvt_pk_bf16_f32 v25, v32, v34
	s_waitcnt lgkmcnt(2)
	v_cvt_pk_bf16_f32 v26, v36, v38
	s_waitcnt lgkmcnt(0)
	v_cvt_pk_bf16_f32 v27, v40, v42
	v_lshl_add_u64 v[46:47], v[44:45], 0, v[46:47]
	global_store_dwordx4 v[46:47], v[24:27], off
	v_or_b32_e32 v28, s2, v18
	s_add_i32 s8, s8, s36
	v_cvt_pk_bf16_f32 v24, v31, v29
	v_cvt_pk_bf16_f32 v25, v33, v35
	v_cvt_pk_bf16_f32 v26, v37, v39
	v_cvt_pk_bf16_f32 v27, v41, v43
	v_mov_b32_e32 v29, s3
	ds_read2_b32 v[30:31], v3 offset0:49 offset1:57
	ds_read2_b32 v[32:33], v3 offset0:16 offset1:24
	ds_read2_b32 v[34:35], v3 offset0:82 offset1:90
	ds_read2_b32 v[36:37], v3 offset0:115 offset1:123
	ds_read2_b32 v[38:39], v3 offset0:148 offset1:156
	ds_read2_b32 v[40:41], v3 offset0:181 offset1:189
	ds_read2_b32 v[42:43], v3 offset0:214 offset1:222
	ds_read2_b32 v[46:47], v3 offset0:247 offset1:255
	v_lshlrev_b64 v[28:29], 12, v[28:29]
	v_lshl_add_u64 v[28:29], v[44:45], 0, v[28:29]
	global_store_dwordx4 v[28:29], v[24:27], off
	v_mov_b32_e32 v29, s3
	v_or_b32_e32 v28, s2, v20
	v_lshlrev_b64 v[28:29], 12, v[28:29]
	s_waitcnt lgkmcnt(6)
	v_cvt_pk_bf16_f32 v24, v32, v30
	s_waitcnt lgkmcnt(4)
	v_cvt_pk_bf16_f32 v25, v34, v36
	s_waitcnt lgkmcnt(2)
	v_cvt_pk_bf16_f32 v26, v38, v40
	s_waitcnt lgkmcnt(0)
	v_cvt_pk_bf16_f32 v27, v42, v46
	v_lshl_add_u64 v[28:29], v[44:45], 0, v[28:29]
	global_store_dwordx4 v[28:29], v[24:27], off
	v_mov_b32_e32 v29, s3
	v_or_b32_e32 v28, s2, v22
	v_lshlrev_b64 v[28:29], 12, v[28:29]
	v_cvt_pk_bf16_f32 v24, v33, v31
	v_cvt_pk_bf16_f32 v25, v35, v37
	v_cvt_pk_bf16_f32 v26, v39, v41
	v_cvt_pk_bf16_f32 v27, v43, v47
	v_lshl_add_u64 v[28:29], v[44:45], 0, v[28:29]
	global_store_dwordx4 v[28:29], v[24:27], off
	s_waitcnt lgkmcnt(0)
	s_cmpk_lt_i32 s8, 0x2800
	s_cbranch_scc1 .LBB0_20
	v_readlane_b32 s48, v245, 24
	v_readlane_b32 s49, v245, 25
	v_readlane_b32 s56, v245, 32
	v_readlane_b32 s57, v245, 33
	v_readlane_b32 s60, v245, 36
	v_readlane_b32 s61, v245, 37
	v_readlane_b32 s50, v245, 26
	v_readlane_b32 s51, v245, 27
	v_readlane_b32 s52, v245, 28
	v_readlane_b32 s53, v245, 29
	v_readlane_b32 s54, v245, 30
	v_readlane_b32 s55, v245, 31
	v_readlane_b32 s58, v245, 34
	v_readlane_b32 s59, v245, 35
	v_readlane_b32 s62, v245, 38
	v_readlane_b32 s63, v245, 39
	s_cmpk_gt_i32 s38, 0x3ff
	s_cbranch_scc1 .LBB0_32

; #define LAS __attribute__((address_space(3)))
; __device__ __forceinline__ void transpose_item(const float* W, int N, bf16_t* WT, int dstK, size_t drow0, int kdst0, int k0, int n0, LAS float* scr, int lane) {
; #pragma unroll 8
;     for (int i = 0; i < 32; ++i) { const int kk = 2 * i + (lane >> 5); scr[kk * 33 + (lane & 31)] = W[(size_t)(k0 + kk) * N + n0 + (lane & 31)]; }
.LBB0_26:
	s_lshl_b32 s10, s20, 1
	s_lshl_b32 s11, s19, 1
	v_or_b32_e32 v5, s10, v1
	v_or_b32_e32 v7, s11, v8
	s_add_i32 s21, s10, 4
	s_add_i32 s22, s11, 4
	s_add_i32 s23, s10, 8
	s_add_i32 s24, s11, 8
	s_add_i32 s25, s10, 12
	s_add_i32 s27, s11, 12
	s_add_i32 s28, s10, 16
	s_add_i32 s29, s11, 16
	s_add_i32 s30, s10, 20
	s_add_i32 s31, s11, 20
	s_add_i32 s33, s10, 24
	s_add_i32 s34, s11, 24
	s_add_i32 s10, s10, 28
	s_add_i32 s11, s11, 28
	v_add_u32_e32 v32, s18, v7
	v_or_b32_e32 v9, s21, v1
	v_or_b32_e32 v11, s22, v8
	v_or_b32_e32 v13, s23, v1
	v_or_b32_e32 v15, s24, v8
	v_or_b32_e32 v17, s25, v1
	v_or_b32_e32 v19, s27, v8
	v_or_b32_e32 v21, s28, v1
	v_or_b32_e32 v23, s29, v8
	v_or_b32_e32 v62, s30, v1
	v_or_b32_e32 v63, s31, v8
	v_or_b32_e32 v64, s33, v1
	v_or_b32_e32 v65, s34, v8
	v_or_b32_e32 v66, s10, v1
	v_or_b32_e32 v67, s11, v8
	v_add_u32_e32 v30, s8, v5
	v_ashrrev_i32_e32 v33, 31, v32
	v_add_u32_e32 v34, s8, v9
	v_add_u32_e32 v36, s18, v11
	v_add_u32_e32 v38, s8, v13
	v_add_u32_e32 v40, s18, v15
	v_add_u32_e32 v42, s8, v17
	v_add_u32_e32 v44, s18, v19
	v_add_u32_e32 v46, s8, v21
	v_add_u32_e32 v48, s18, v23
	v_add_u32_e32 v50, s8, v62
	v_add_u32_e32 v52, s18, v63
	v_add_u32_e32 v54, s8, v64
	v_add_u32_e32 v56, s18, v65
	v_add_u32_e32 v58, s8, v66
	v_add_u32_e32 v60, s18, v67
	v_ashrrev_i32_e32 v31, 31, v30
	v_lshlrev_b64 v[32:33], 13, v[32:33]
	v_ashrrev_i32_e32 v37, 31, v36
	v_ashrrev_i32_e32 v35, 31, v34
	v_ashrrev_i32_e32 v41, 31, v40
	v_ashrrev_i32_e32 v39, 31, v38
	v_ashrrev_i32_e32 v45, 31, v44
	v_ashrrev_i32_e32 v43, 31, v42
	v_ashrrev_i32_e32 v49, 31, v48
	v_ashrrev_i32_e32 v47, 31, v46
	v_ashrrev_i32_e32 v53, 31, v52
	v_ashrrev_i32_e32 v51, 31, v50
	v_ashrrev_i32_e32 v57, 31, v56
	v_ashrrev_i32_e32 v55, 31, v54
	v_ashrrev_i32_e32 v61, 31, v60
	v_ashrrev_i32_e32 v59, 31, v58
	v_lshlrev_b64 v[30:31], 13, v[30:31]
	v_lshl_add_u64 v[32:33], v[28:29], 0, v[32:33]
	v_lshlrev_b64 v[34:35], 13, v[34:35]
	v_lshlrev_b64 v[36:37], 13, v[36:37]
	v_lshlrev_b64 v[38:39], 13, v[38:39]
	v_lshlrev_b64 v[40:41], 13, v[40:41]
	v_lshlrev_b64 v[42:43], 13, v[42:43]
	v_lshlrev_b64 v[44:45], 13, v[44:45]
	v_lshlrev_b64 v[46:47], 13, v[46:47]
	v_lshlrev_b64 v[48:49], 13, v[48:49]
	v_lshlrev_b64 v[50:51], 13, v[50:51]
	v_lshlrev_b64 v[52:53], 13, v[52:53]
	v_lshlrev_b64 v[54:55], 13, v[54:55]
	v_lshlrev_b64 v[56:57], 13, v[56:57]
	v_lshlrev_b64 v[58:59], 13, v[58:59]
	v_lshlrev_b64 v[60:61], 13, v[60:61]
	v_lshl_add_u64 v[30:31], v[28:29], 0, v[30:31]
	v_lshl_add_u64 v[36:37], v[28:29], 0, v[36:37]
	v_lshl_add_u64 v[34:35], v[28:29], 0, v[34:35]
	v_lshl_add_u64 v[40:41], v[28:29], 0, v[40:41]
	v_lshl_add_u64 v[38:39], v[28:29], 0, v[38:39]
	v_lshl_add_u64 v[44:45], v[28:29], 0, v[44:45]
	v_lshl_add_u64 v[42:43], v[28:29], 0, v[42:43]
	v_lshl_add_u64 v[48:49], v[28:29], 0, v[48:49]
	v_lshl_add_u64 v[46:47], v[28:29], 0, v[46:47]
	v_lshl_add_u64 v[52:53], v[28:29], 0, v[52:53]
	v_lshl_add_u64 v[50:51], v[28:29], 0, v[50:51]
	v_lshl_add_u64 v[56:57], v[28:29], 0, v[56:57]
	v_lshl_add_u64 v[54:55], v[28:29], 0, v[54:55]
	v_lshl_add_u64 v[60:61], v[28:29], 0, v[60:61]
	v_lshl_add_u64 v[58:59], v[28:29], 0, v[58:59]
	global_load_dword v68, v[32:33], off
	global_load_dword v69, v[30:31], off
	global_load_dword v70, v[36:37], off
	global_load_dword v71, v[34:35], off
	global_load_dword v72, v[40:41], off
	global_load_dword v73, v[38:39], off
	global_load_dword v74, v[44:45], off
	global_load_dword v75, v[42:43], off
	global_load_dword v76, v[48:49], off
	global_load_dword v77, v[46:47], off
	global_load_dword v78, v[52:53], off
	global_load_dword v79, v[50:51], off
	global_load_dword v80, v[56:57], off
	global_load_dword v81, v[54:55], off
	global_load_dword v82, v[60:61], off
	global_load_dword v83, v[58:59], off
	s_add_i32 s19, s19, 16
	s_add_i32 s20, s20, 16
	s_add_i32 s9, s9, -16
	v_mad_u64_u32 v[30:31], s[22:23], v7, s6, v[10:11]
	s_cmp_lg_u32 s9, 0
	v_mad_u64_u32 v[32:33], s[22:23], v5, s6, v[10:11]
	v_mad_u64_u32 v[34:35], s[22:23], v11, s6, v[10:11]
	v_mad_u64_u32 v[36:37], s[22:23], v9, s6, v[10:11]
	v_mad_u64_u32 v[38:39], s[22:23], v15, s6, v[10:11]
	v_mad_u64_u32 v[40:41], s[22:23], v13, s6, v[10:11]
	v_mad_u64_u32 v[42:43], s[22:23], v19, s6, v[10:11]
	v_mad_u64_u32 v[44:45], s[22:23], v17, s6, v[10:11]
	v_mad_u64_u32 v[46:47], s[22:23], v23, s6, v[10:11]
	v_mad_u64_u32 v[48:49], s[22:23], v21, s6, v[10:11]
	v_mad_u64_u32 v[50:51], s[22:23], v63, s6, v[10:11]
	v_mad_u64_u32 v[52:53], s[22:23], v62, s6, v[10:11]
	v_mad_u64_u32 v[54:55], s[22:23], v65, s6, v[10:11]
	v_mad_u64_u32 v[56:57], s[22:23], v64, s6, v[10:11]
	v_mad_u64_u32 v[58:59], s[22:23], v67, s6, v[10:11]
	v_mad_u64_u32 v[60:61], s[22:23], v66, s6, v[10:11]
	s_lshl_b32 s10, s20, 1
	s_lshl_b32 s11, s19, 1
	v_or_b32_e32 v128, s10, v1
	v_or_b32_e32 v129, s11, v8
	s_add_i32 s21, s10, 4
	s_add_i32 s22, s11, 4
	s_add_i32 s23, s10, 8
	s_add_i32 s24, s11, 8
	s_add_i32 s25, s10, 12
	s_add_i32 s27, s11, 12
	s_add_i32 s28, s10, 16
	s_add_i32 s29, s11, 16
	s_add_i32 s30, s10, 20
	s_add_i32 s31, s11, 20
	s_add_i32 s33, s10, 24
	s_add_i32 s34, s11, 24
	s_add_i32 s10, s10, 28
	s_add_i32 s11, s11, 28
	v_add_u32_e32 v98, s18, v129
	v_or_b32_e32 v130, s21, v1
	v_or_b32_e32 v131, s22, v8
	v_or_b32_e32 v132, s23, v1
	v_or_b32_e32 v133, s24, v8
	v_or_b32_e32 v134, s25, v1
	v_or_b32_e32 v135, s27, v8
	v_or_b32_e32 v136, s28, v1
	v_or_b32_e32 v137, s29, v8
	v_or_b32_e32 v138, s30, v1
	v_or_b32_e32 v139, s31, v8
	v_or_b32_e32 v140, s33, v1
	v_or_b32_e32 v141, s34, v8
	v_or_b32_e32 v142, s10, v1
	v_or_b32_e32 v143, s11, v8
	v_add_u32_e32 v96, s8, v128
	v_ashrrev_i32_e32 v99, 31, v98
	v_add_u32_e32 v100, s8, v130
; #define LDS_WAIT() asm volatile("s_waitcnt lgkmcnt(0)" ::: "memory")
; __device__ __forceinline__ void transpose_item(const float* W, int N, bf16_t* WT, int dstK, size_t drow0, int kdst0, int k0, int n0, LAS float* scr, int lane) {
;     ...
;     for (int i = 0; i < 32; ++i) { const int kk = 2 * i + (lane >> 5); scr[kk * 33 + (lane & 31)] = W[(size_t)(k0 + kk) * N + n0 + (lane & 31)]; }
;     LDS_WAIT();
	v_add_u32_e32 v102, s18, v131
	v_add_u32_e32 v104, s8, v132
	v_add_u32_e32 v106, s18, v133
	v_add_u32_e32 v108, s8, v134
	v_add_u32_e32 v110, s18, v135
	v_add_u32_e32 v112, s8, v136
	v_add_u32_e32 v114, s18, v137
	v_add_u32_e32 v116, s8, v138
	v_add_u32_e32 v118, s18, v139
	v_add_u32_e32 v120, s8, v140
	v_add_u32_e32 v122, s18, v141
	v_add_u32_e32 v124, s8, v142
	v_add_u32_e32 v126, s18, v143
	v_ashrrev_i32_e32 v97, 31, v96
	v_lshlrev_b64 v[98:99], 13, v[98:99]
	v_ashrrev_i32_e32 v103, 31, v102
	v_ashrrev_i32_e32 v101, 31, v100
	v_ashrrev_i32_e32 v107, 31, v106
	v_ashrrev_i32_e32 v105, 31, v104
	v_ashrrev_i32_e32 v111, 31, v110
	v_ashrrev_i32_e32 v109, 31, v108
	v_ashrrev_i32_e32 v115, 31, v114
	v_ashrrev_i32_e32 v113, 31, v112
	v_ashrrev_i32_e32 v119, 31, v118
	v_ashrrev_i32_e32 v117, 31, v116
	v_ashrrev_i32_e32 v123, 31, v122
	v_ashrrev_i32_e32 v121, 31, v120
	v_ashrrev_i32_e32 v127, 31, v126
	v_ashrrev_i32_e32 v125, 31, v124
	v_lshlrev_b64 v[96:97], 13, v[96:97]
	v_lshl_add_u64 v[98:99], v[28:29], 0, v[98:99]
	v_lshlrev_b64 v[100:101], 13, v[100:101]
	v_lshlrev_b64 v[102:103], 13, v[102:103]
	v_lshlrev_b64 v[104:105], 13, v[104:105]
	v_lshlrev_b64 v[106:107], 13, v[106:107]
	v_lshlrev_b64 v[108:109], 13, v[108:109]
	v_lshlrev_b64 v[110:111], 13, v[110:111]
	v_lshlrev_b64 v[112:113], 13, v[112:113]
	v_lshlrev_b64 v[114:115], 13, v[114:115]
	v_lshlrev_b64 v[116:117], 13, v[116:117]
	v_lshlrev_b64 v[118:119], 13, v[118:119]
	v_lshlrev_b64 v[120:121], 13, v[120:121]
	v_lshlrev_b64 v[122:123], 13, v[122:123]
	v_lshlrev_b64 v[124:125], 13, v[124:125]
	v_lshlrev_b64 v[126:127], 13, v[126:127]
	v_lshl_add_u64 v[96:97], v[28:29], 0, v[96:97]
	v_lshl_add_u64 v[102:103], v[28:29], 0, v[102:103]
	v_lshl_add_u64 v[100:101], v[28:29], 0, v[100:101]
	v_lshl_add_u64 v[106:107], v[28:29], 0, v[106:107]
	v_lshl_add_u64 v[104:105], v[28:29], 0, v[104:105]
	v_lshl_add_u64 v[110:111], v[28:29], 0, v[110:111]
	v_lshl_add_u64 v[108:109], v[28:29], 0, v[108:109]
	v_lshl_add_u64 v[114:115], v[28:29], 0, v[114:115]
	v_lshl_add_u64 v[112:113], v[28:29], 0, v[112:113]
	v_lshl_add_u64 v[118:119], v[28:29], 0, v[118:119]
	v_lshl_add_u64 v[116:117], v[28:29], 0, v[116:117]
	v_lshl_add_u64 v[122:123], v[28:29], 0, v[122:123]
	v_lshl_add_u64 v[120:121], v[28:29], 0, v[120:121]
	v_lshl_add_u64 v[126:127], v[28:29], 0, v[126:127]
	v_lshl_add_u64 v[124:125], v[28:29], 0, v[124:125]
	global_load_dword v144, v[98:99], off
	global_load_dword v145, v[96:97], off
	global_load_dword v146, v[102:103], off
	global_load_dword v147, v[100:101], off
	global_load_dword v148, v[106:107], off
	global_load_dword v149, v[104:105], off
	global_load_dword v150, v[110:111], off
	global_load_dword v151, v[108:109], off
	global_load_dword v152, v[114:115], off
	global_load_dword v153, v[112:113], off
	global_load_dword v154, v[118:119], off
	global_load_dword v155, v[116:117], off
	global_load_dword v156, v[122:123], off
	global_load_dword v157, v[120:121], off
	global_load_dword v158, v[126:127], off
	global_load_dword v159, v[124:125], off
	s_add_i32 s19, s19, 16
	s_add_i32 s20, s20, 16
	s_add_i32 s9, s9, -16
	v_mad_u64_u32 v[96:97], s[22:23], v129, s6, v[10:11]
	s_cmp_lg_u32 s9, 0
	v_mad_u64_u32 v[98:99], s[22:23], v128, s6, v[10:11]
	v_mad_u64_u32 v[100:101], s[22:23], v131, s6, v[10:11]
	v_mad_u64_u32 v[102:103], s[22:23], v130, s6, v[10:11]
	v_mad_u64_u32 v[104:105], s[22:23], v133, s6, v[10:11]
	v_mad_u64_u32 v[106:107], s[22:23], v132, s6, v[10:11]
	v_mad_u64_u32 v[108:109], s[22:23], v135, s6, v[10:11]
	v_mad_u64_u32 v[110:111], s[22:23], v134, s6, v[10:11]
	v_mad_u64_u32 v[112:113], s[22:23], v137, s6, v[10:11]
	v_mad_u64_u32 v[114:115], s[22:23], v136, s6, v[10:11]
	v_mad_u64_u32 v[116:117], s[22:23], v139, s6, v[10:11]
	v_mad_u64_u32 v[118:119], s[22:23], v138, s6, v[10:11]
	v_mad_u64_u32 v[120:121], s[22:23], v141, s6, v[10:11]
	v_mad_u64_u32 v[122:123], s[22:23], v140, s6, v[10:11]
	v_mad_u64_u32 v[124:125], s[22:23], v143, s6, v[10:11]
	v_mad_u64_u32 v[126:127], s[22:23], v142, s6, v[10:11]
	s_waitcnt vmcnt(31)
	ds_write_b32 v30, v68
	s_waitcnt vmcnt(30)
	ds_write_b32 v32, v69
	s_waitcnt vmcnt(29)
	ds_write_b32 v34, v70
	s_waitcnt vmcnt(28)
	ds_write_b32 v36, v71
	s_waitcnt vmcnt(27)
	ds_write_b32 v38, v72
	s_waitcnt vmcnt(26)
	ds_write_b32 v40, v73
	s_waitcnt vmcnt(25)
	ds_write_b32 v42, v74
	s_waitcnt vmcnt(24)
	ds_write_b32 v44, v75
	s_waitcnt vmcnt(23)
	ds_write_b32 v46, v76
	s_waitcnt vmcnt(22)
	ds_write_b32 v48, v77
	s_waitcnt vmcnt(21)
	ds_write_b32 v50, v78
	s_waitcnt vmcnt(20)
	ds_write_b32 v52, v79
	s_waitcnt vmcnt(19)
; #define LAS __attribute__((address_space(3)))
; __device__ __forceinline__ unsigned cvt_pk_bf16(float lo, float hi) { f32x2_c v = {lo, hi}; bf16x2_c r = __builtin_convertvector(v, bf16x2_c); return __builtin_bit_cast(unsigned, r); }
; #define LDS_WAIT() asm volatile("s_waitcnt lgkmcnt(0)" ::: "memory")
; __device__ __forceinline__ void transpose_item(const float* W, int N, bf16_t* WT, int dstK, size_t drow0, int kdst0, int k0, int n0, LAS float* scr, int lane) {
;     ...
;     for (int i = 0; i < 32; ++i) { const int kk = 2 * i + (lane >> 5); scr[kk * 33 + (lane & 31)] = W[(size_t)(k0 + kk) * N + n0 + (lane & 31)]; }
;     LDS_WAIT();
;     const int c = lane & 7;
; #pragma unroll
;     for (int j = 0; j < 4; ++j) { const int n = (lane >> 3) + 8 * j; const LAS float* s = scr + (8 * c) * 33 + n;
;         u32x4 o; o.x = cvt_pk_bf16(s[0 * 33], s[1 * 33]); o.y = cvt_pk_bf16(s[2 * 33], s[3 * 33]); o.z = cvt_pk_bf16(s[4 * 33], s[5 * 33]); o.w = cvt_pk_bf16(s[6 * 33], s[7 * 33]);
;         *(u32x4*)(WT + (drow0 + n) * dstK + kdst0 + k0 + 8 * c) = o; }
;     LDS_WAIT();
; __global__ void __launch_bounds__(NTHREADS, 2) fwd_kernel(Args args) {
;     ...
;         transpose_matrix(w_in, D, 10240, WIN, D, 0, 0, scr, gw, NGW, lane);
;         transpose_matrix(w_branch_a, HW, D, WAB, D, 0, 0, scr, gw, NGW, lane);
;         transpose_matrix(w_branch_b, HW, D, WAB, D, HW, 0, scr, gw, NGW, lane);
;         transpose_matrix(w_out, D, D, WOUT, D, 0, 0, scr, gw, NGW, lane);
	ds_write_b32 v54, v80
	s_waitcnt vmcnt(18)
	ds_write_b32 v56, v81
	s_waitcnt vmcnt(17)
	ds_write_b32 v58, v82
	s_waitcnt vmcnt(16)
	ds_write_b32 v60, v83
	s_waitcnt vmcnt(15)
	ds_write_b32 v96, v144
	s_waitcnt vmcnt(14)
	ds_write_b32 v98, v145
	s_waitcnt vmcnt(13)
	ds_write_b32 v100, v146
	s_waitcnt vmcnt(12)
	ds_write_b32 v102, v147
	s_waitcnt vmcnt(11)
	ds_write_b32 v104, v148
	s_waitcnt vmcnt(10)
	ds_write_b32 v106, v149
	s_waitcnt vmcnt(9)
	ds_write_b32 v108, v150
	s_waitcnt vmcnt(8)
	ds_write_b32 v110, v151
	s_waitcnt vmcnt(7)
	ds_write_b32 v112, v152
	s_waitcnt vmcnt(6)
	ds_write_b32 v114, v153
	s_waitcnt vmcnt(5)
	ds_write_b32 v116, v154
	s_waitcnt vmcnt(4)
	ds_write_b32 v118, v155
	s_waitcnt vmcnt(3)
	ds_write_b32 v120, v156
	s_waitcnt vmcnt(2)
	ds_write_b32 v122, v157
	s_waitcnt vmcnt(1)
	ds_write_b32 v124, v158
	s_waitcnt vmcnt(0)
	ds_write_b32 v126, v159
	s_waitcnt lgkmcnt(0)
	ds_read2_b32 v[32:33], v3 offset0:33 offset1:41
	ds_read2_b32 v[34:35], v3 offset1:8
	ds_read2_b32 v[36:37], v3 offset0:66 offset1:74
	ds_read2_b32 v[38:39], v3 offset0:99 offset1:107
	ds_read2_b32 v[40:41], v3 offset0:132 offset1:140
	ds_read2_b32 v[42:43], v3 offset0:165 offset1:173
	ds_read2_b32 v[44:45], v3 offset0:198 offset1:206
	ds_read2_b32 v[46:47], v3 offset0:231 offset1:239
	s_ashr_i32 s19, s18, 31
	v_mov_b32_e32 v51, s3
	v_or_b32_e32 v50, s2, v12
	v_lshl_add_u64 v[48:49], s[18:19], 1, v[26:27]
	v_lshlrev_b64 v[50:51], 12, v[50:51]
	s_waitcnt lgkmcnt(6)
	v_cvt_pk_bf16_f32 v28, v34, v32
	s_waitcnt lgkmcnt(4)
	v_cvt_pk_bf16_f32 v29, v36, v38
	s_waitcnt lgkmcnt(2)
	v_cvt_pk_bf16_f32 v30, v40, v42
	s_waitcnt lgkmcnt(0)
	v_cvt_pk_bf16_f32 v31, v44, v46
	v_lshl_add_u64 v[50:51], v[48:49], 0, v[50:51]
	global_store_dwordx4 v[50:51], v[28:31], off
	v_or_b32_e32 v32, s2, v14
	s_add_i32 s7, s7, s36
	v_cvt_pk_bf16_f32 v28, v35, v33
	v_cvt_pk_bf16_f32 v29, v37, v39
	v_cvt_pk_bf16_f32 v30, v41, v43
	v_cvt_pk_bf16_f32 v31, v45, v47
	v_mov_b32_e32 v33, s3
	ds_read2_b32 v[34:35], v3 offset0:49 offset1:57
	ds_read2_b32 v[36:37], v3 offset0:16 offset1:24
	ds_read2_b32 v[38:39], v3 offset0:82 offset1:90
	ds_read2_b32 v[40:41], v3 offset0:115 offset1:123
	ds_read2_b32 v[42:43], v3 offset0:148 offset1:156
	ds_read2_b32 v[44:45], v3 offset0:181 offset1:189
	ds_read2_b32 v[46:47], v3 offset0:214 offset1:222
	ds_read2_b32 v[50:51], v3 offset0:247 offset1:255
	v_lshlrev_b64 v[32:33], 12, v[32:33]
	v_lshl_add_u64 v[32:33], v[48:49], 0, v[32:33]
	global_store_dwordx4 v[32:33], v[28:31], off
	v_mov_b32_e32 v33, s3
	v_or_b32_e32 v32, s2, v16
	v_lshlrev_b64 v[32:33], 12, v[32:33]
	s_waitcnt lgkmcnt(6)
	v_cvt_pk_bf16_f32 v28, v36, v34
	s_waitcnt lgkmcnt(4)
	v_cvt_pk_bf16_f32 v29, v38, v40
	s_waitcnt lgkmcnt(2)
	v_cvt_pk_bf16_f32 v30, v42, v44
	s_waitcnt lgkmcnt(0)
	v_cvt_pk_bf16_f32 v31, v46, v50
	v_lshl_add_u64 v[32:33], v[48:49], 0, v[32:33]
	global_store_dwordx4 v[32:33], v[28:31], off
	v_mov_b32_e32 v33, s3
	v_or_b32_e32 v32, s2, v18
	v_lshlrev_b64 v[32:33], 12, v[32:33]
	v_cvt_pk_bf16_f32 v28, v37, v35
	v_cvt_pk_bf16_f32 v29, v39, v41
	v_cvt_pk_bf16_f32 v30, v43, v45
	v_cvt_pk_bf16_f32 v31, v47, v51
	v_lshl_add_u64 v[32:33], v[48:49], 0, v[32:33]
	global_store_dwordx4 v[32:33], v[28:31], off
	s_waitcnt lgkmcnt(0)
	s_cmpk_lt_i32 s7, 0x400
	s_cbranch_scc1 .LBB0_25
	v_readlane_b32 s48, v245, 49
	v_lshlrev_b32_e32 v24, 2, v20
	v_mov_b32_e32 v25, 0
	v_readlane_b32 s52, v245, 53
	v_readlane_b32 s53, v245, 54
	v_readlane_b32 s49, v245, 50
	v_readlane_b32 s50, v245, 51
	v_readlane_b32 s51, v245, 52
	v_readlane_b32 s54, v245, 55
	v_readlane_b32 s55, v245, 56
	v_readlane_b32 s56, v245, 57
	v_readlane_b32 s57, v245, 58
	v_readlane_b32 s58, v245, 59
	v_readlane_b32 s59, v245, 60
	v_readlane_b32 s60, v245, 61
	v_readlane_b32 s61, v245, 62
	v_readlane_b32 s62, v245, 63
	v_readlane_b32 s63, v244, 0
	v_lshl_add_u64 v[20:21], s[52:53], 0, v[24:25]
	v_lshlrev_b32_e32 v24, 1, v22
	v_lshl_add_u64 v[22:23], s[92:93], 0, v[24:25]
	s_mov_b64 s[2:3], 0x6b00800
	v_readlane_b32 s48, v245, 24
	v_lshl_add_u64 v[22:23], v[22:23], 0, s[2:3]
	s_movk_i32 s6, 0x84
	s_mov_b32 s7, s38
	v_readlane_b32 s49, v245, 25
	v_readlane_b32 s56, v245, 32
	v_readlane_b32 s57, v245, 33
	v_readlane_b32 s60, v245, 36
	v_readlane_b32 s61, v245, 37
	v_readlane_b32 s50, v245, 26
	v_readlane_b32 s51, v245, 27
	v_readlane_b32 s52, v245, 28
	v_readlane_b32 s53, v245, 29
	v_readlane_b32 s54, v245, 30
	v_readlane_b32 s55, v245, 31
	v_readlane_b32 s58, v245, 34
	v_readlane_b32 s59, v245, 35
	v_readlane_b32 s62, v245, 38
	v_readlane_b32 s63, v245, 39

; #define LAS __attribute__((address_space(3)))
; __device__ __forceinline__ void transpose_item(const float* W, int N, bf16_t* WT, int dstK, size_t drow0, int kdst0, int k0, int n0, LAS float* scr, int lane) {
; #pragma unroll 8
;     for (int i = 0; i < 32; ++i) { const int kk = 2 * i + (lane >> 5); scr[kk * 33 + (lane & 31)] = W[(size_t)(k0 + kk) * N + n0 + (lane & 31)]; }
.LBB0_30:
	s_lshl_b32 s10, s20, 1
	s_lshl_b32 s11, s19, 1
	v_or_b32_e32 v5, s10, v1
	v_or_b32_e32 v7, s11, v8
	s_add_i32 s21, s10, 4
	s_add_i32 s22, s11, 4
	s_add_i32 s23, s10, 8
	s_add_i32 s24, s11, 8
	s_add_i32 s25, s10, 12
	s_add_i32 s27, s11, 12
	s_add_i32 s28, s10, 16
	s_add_i32 s29, s11, 16
	s_add_i32 s30, s10, 20
	s_add_i32 s31, s11, 20
	s_add_i32 s33, s10, 24
	s_add_i32 s34, s11, 24
	s_add_i32 s10, s10, 28
	s_add_i32 s11, s11, 28
	v_add_u32_e32 v28, s18, v7
	v_or_b32_e32 v9, s21, v1
	v_or_b32_e32 v11, s22, v8
	v_or_b32_e32 v13, s23, v1
	v_or_b32_e32 v15, s24, v8
	v_or_b32_e32 v17, s25, v1
	v_or_b32_e32 v19, s27, v8
	v_or_b32_e32 v58, s28, v1
	v_or_b32_e32 v59, s29, v8
	v_or_b32_e32 v60, s30, v1
	v_or_b32_e32 v61, s31, v8
	v_or_b32_e32 v62, s33, v1
	v_or_b32_e32 v63, s34, v8
	v_or_b32_e32 v64, s10, v1
	v_or_b32_e32 v65, s11, v8
	v_add_u32_e32 v26, s8, v5
	v_ashrrev_i32_e32 v29, 31, v28
	v_add_u32_e32 v30, s8, v9
	v_add_u32_e32 v32, s18, v11
	v_add_u32_e32 v34, s8, v13
	v_add_u32_e32 v36, s18, v15
	v_add_u32_e32 v38, s8, v17
	v_add_u32_e32 v40, s18, v19
	v_add_u32_e32 v42, s8, v58
	v_add_u32_e32 v44, s18, v59
	v_add_u32_e32 v46, s8, v60
	v_add_u32_e32 v48, s18, v61
	v_add_u32_e32 v50, s8, v62
	v_add_u32_e32 v52, s18, v63
	v_add_u32_e32 v54, s8, v64
	v_add_u32_e32 v56, s18, v65
	v_ashrrev_i32_e32 v27, 31, v26
	v_lshlrev_b64 v[28:29], 13, v[28:29]
	v_ashrrev_i32_e32 v33, 31, v32
	v_ashrrev_i32_e32 v31, 31, v30
	v_ashrrev_i32_e32 v37, 31, v36
	v_ashrrev_i32_e32 v35, 31, v34
	v_ashrrev_i32_e32 v41, 31, v40
	v_ashrrev_i32_e32 v39, 31, v38
	v_ashrrev_i32_e32 v45, 31, v44
	v_ashrrev_i32_e32 v43, 31, v42
	v_ashrrev_i32_e32 v49, 31, v48
	v_ashrrev_i32_e32 v47, 31, v46
	v_ashrrev_i32_e32 v53, 31, v52
	v_ashrrev_i32_e32 v51, 31, v50
	v_ashrrev_i32_e32 v57, 31, v56
	v_ashrrev_i32_e32 v55, 31, v54
	v_lshlrev_b64 v[26:27], 13, v[26:27]
	v_lshl_add_u64 v[28:29], v[24:25], 0, v[28:29]
	v_lshlrev_b64 v[30:31], 13, v[30:31]
	v_lshlrev_b64 v[32:33], 13, v[32:33]
	v_lshlrev_b64 v[34:35], 13, v[34:35]
	v_lshlrev_b64 v[36:37], 13, v[36:37]
	v_lshlrev_b64 v[38:39], 13, v[38:39]
	v_lshlrev_b64 v[40:41], 13, v[40:41]
	v_lshlrev_b64 v[42:43], 13, v[42:43]
	v_lshlrev_b64 v[44:45], 13, v[44:45]
	v_lshlrev_b64 v[46:47], 13, v[46:47]
	v_lshlrev_b64 v[48:49], 13, v[48:49]
	v_lshlrev_b64 v[50:51], 13, v[50:51]
	v_lshlrev_b64 v[52:53], 13, v[52:53]
	v_lshlrev_b64 v[54:55], 13, v[54:55]
	v_lshlrev_b64 v[56:57], 13, v[56:57]
	v_lshl_add_u64 v[26:27], v[24:25], 0, v[26:27]
	v_lshl_add_u64 v[32:33], v[24:25], 0, v[32:33]
	v_lshl_add_u64 v[30:31], v[24:25], 0, v[30:31]
	v_lshl_add_u64 v[36:37], v[24:25], 0, v[36:37]
	v_lshl_add_u64 v[34:35], v[24:25], 0, v[34:35]
	v_lshl_add_u64 v[40:41], v[24:25], 0, v[40:41]
	v_lshl_add_u64 v[38:39], v[24:25], 0, v[38:39]
	v_lshl_add_u64 v[44:45], v[24:25], 0, v[44:45]
	v_lshl_add_u64 v[42:43], v[24:25], 0, v[42:43]
	v_lshl_add_u64 v[48:49], v[24:25], 0, v[48:49]
	v_lshl_add_u64 v[46:47], v[24:25], 0, v[46:47]
	v_lshl_add_u64 v[52:53], v[24:25], 0, v[52:53]
	v_lshl_add_u64 v[50:51], v[24:25], 0, v[50:51]
	v_lshl_add_u64 v[56:57], v[24:25], 0, v[56:57]
	v_lshl_add_u64 v[54:55], v[24:25], 0, v[54:55]
	global_load_dword v66, v[28:29], off
	global_load_dword v67, v[26:27], off
	global_load_dword v68, v[32:33], off
	global_load_dword v69, v[30:31], off
	global_load_dword v70, v[36:37], off
	global_load_dword v71, v[34:35], off
	global_load_dword v72, v[40:41], off
	global_load_dword v73, v[38:39], off
	global_load_dword v74, v[44:45], off
	global_load_dword v75, v[42:43], off
	global_load_dword v76, v[48:49], off
	global_load_dword v77, v[46:47], off
	global_load_dword v78, v[52:53], off
	global_load_dword v79, v[50:51], off
	global_load_dword v80, v[56:57], off
	global_load_dword v81, v[54:55], off
	s_add_i32 s19, s19, 16
	s_add_i32 s20, s20, 16
	s_add_i32 s9, s9, -16
	v_mad_u64_u32 v[26:27], s[22:23], v7, s6, v[10:11]
	s_cmp_lg_u32 s9, 0
	v_mad_u64_u32 v[28:29], s[22:23], v5, s6, v[10:11]
	v_mad_u64_u32 v[30:31], s[22:23], v11, s6, v[10:11]
	v_mad_u64_u32 v[32:33], s[22:23], v9, s6, v[10:11]
	v_mad_u64_u32 v[34:35], s[22:23], v15, s6, v[10:11]
	v_mad_u64_u32 v[36:37], s[22:23], v13, s6, v[10:11]
	v_mad_u64_u32 v[38:39], s[22:23], v19, s6, v[10:11]
	v_mad_u64_u32 v[40:41], s[22:23], v17, s6, v[10:11]
	v_mad_u64_u32 v[42:43], s[22:23], v59, s6, v[10:11]
	v_mad_u64_u32 v[44:45], s[22:23], v58, s6, v[10:11]
	v_mad_u64_u32 v[46:47], s[22:23], v61, s6, v[10:11]
	v_mad_u64_u32 v[48:49], s[22:23], v60, s6, v[10:11]
	v_mad_u64_u32 v[50:51], s[22:23], v63, s6, v[10:11]
	v_mad_u64_u32 v[52:53], s[22:23], v62, s6, v[10:11]
	v_mad_u64_u32 v[54:55], s[22:23], v65, s6, v[10:11]
	v_mad_u64_u32 v[56:57], s[22:23], v64, s6, v[10:11]
	s_lshl_b32 s10, s20, 1
	s_lshl_b32 s11, s19, 1
	v_or_b32_e32 v128, s10, v1
	v_or_b32_e32 v129, s11, v8
	s_add_i32 s21, s10, 4
	s_add_i32 s22, s11, 4
	s_add_i32 s23, s10, 8
	s_add_i32 s24, s11, 8
	s_add_i32 s25, s10, 12
	s_add_i32 s27, s11, 12
	s_add_i32 s28, s10, 16
	s_add_i32 s29, s11, 16
	s_add_i32 s30, s10, 20
	s_add_i32 s31, s11, 20
	s_add_i32 s33, s10, 24
	s_add_i32 s34, s11, 24
	s_add_i32 s10, s10, 28
	s_add_i32 s11, s11, 28
	v_add_u32_e32 v98, s18, v129
	v_or_b32_e32 v130, s21, v1
	v_or_b32_e32 v131, s22, v8
	v_or_b32_e32 v132, s23, v1
	v_or_b32_e32 v133, s24, v8
	v_or_b32_e32 v134, s25, v1
	v_or_b32_e32 v135, s27, v8
	v_or_b32_e32 v136, s28, v1
	v_or_b32_e32 v137, s29, v8
	v_or_b32_e32 v138, s30, v1
	v_or_b32_e32 v139, s31, v8
	v_or_b32_e32 v140, s33, v1
	v_or_b32_e32 v141, s34, v8
	v_or_b32_e32 v142, s10, v1
	v_or_b32_e32 v143, s11, v8
	v_add_u32_e32 v96, s8, v128
	v_ashrrev_i32_e32 v99, 31, v98
	v_add_u32_e32 v100, s8, v130
; #define LDS_WAIT() asm volatile("s_waitcnt lgkmcnt(0)" ::: "memory")
; __device__ __forceinline__ void transpose_item(const float* W, int N, bf16_t* WT, int dstK, size_t drow0, int kdst0, int k0, int n0, LAS float* scr, int lane) {
;     ...
;     for (int i = 0; i < 32; ++i) { const int kk = 2 * i + (lane >> 5); scr[kk * 33 + (lane & 31)] = W[(size_t)(k0 + kk) * N + n0 + (lane & 31)]; }
;     LDS_WAIT();
	v_add_u32_e32 v102, s18, v131
	v_add_u32_e32 v104, s8, v132
	v_add_u32_e32 v106, s18, v133
	v_add_u32_e32 v108, s8, v134
	v_add_u32_e32 v110, s18, v135
	v_add_u32_e32 v112, s8, v136
	v_add_u32_e32 v114, s18, v137
	v_add_u32_e32 v116, s8, v138
	v_add_u32_e32 v118, s18, v139
	v_add_u32_e32 v120, s8, v140
	v_add_u32_e32 v122, s18, v141
	v_add_u32_e32 v124, s8, v142
	v_add_u32_e32 v126, s18, v143
	v_ashrrev_i32_e32 v97, 31, v96
	v_lshlrev_b64 v[98:99], 13, v[98:99]
	v_ashrrev_i32_e32 v103, 31, v102
	v_ashrrev_i32_e32 v101, 31, v100
	v_ashrrev_i32_e32 v107, 31, v106
	v_ashrrev_i32_e32 v105, 31, v104
	v_ashrrev_i32_e32 v111, 31, v110
	v_ashrrev_i32_e32 v109, 31, v108
	v_ashrrev_i32_e32 v115, 31, v114
	v_ashrrev_i32_e32 v113, 31, v112
	v_ashrrev_i32_e32 v119, 31, v118
	v_ashrrev_i32_e32 v117, 31, v116
	v_ashrrev_i32_e32 v123, 31, v122
	v_ashrrev_i32_e32 v121, 31, v120
	v_ashrrev_i32_e32 v127, 31, v126
	v_ashrrev_i32_e32 v125, 31, v124
	v_lshlrev_b64 v[96:97], 13, v[96:97]
	v_lshl_add_u64 v[98:99], v[24:25], 0, v[98:99]
	v_lshlrev_b64 v[100:101], 13, v[100:101]
	v_lshlrev_b64 v[102:103], 13, v[102:103]
	v_lshlrev_b64 v[104:105], 13, v[104:105]
	v_lshlrev_b64 v[106:107], 13, v[106:107]
	v_lshlrev_b64 v[108:109], 13, v[108:109]
	v_lshlrev_b64 v[110:111], 13, v[110:111]
	v_lshlrev_b64 v[112:113], 13, v[112:113]
	v_lshlrev_b64 v[114:115], 13, v[114:115]
	v_lshlrev_b64 v[116:117], 13, v[116:117]
	v_lshlrev_b64 v[118:119], 13, v[118:119]
	v_lshlrev_b64 v[120:121], 13, v[120:121]
	v_lshlrev_b64 v[122:123], 13, v[122:123]
	v_lshlrev_b64 v[124:125], 13, v[124:125]
	v_lshlrev_b64 v[126:127], 13, v[126:127]
	v_lshl_add_u64 v[96:97], v[24:25], 0, v[96:97]
	v_lshl_add_u64 v[102:103], v[24:25], 0, v[102:103]
	v_lshl_add_u64 v[100:101], v[24:25], 0, v[100:101]
	v_lshl_add_u64 v[106:107], v[24:25], 0, v[106:107]
	v_lshl_add_u64 v[104:105], v[24:25], 0, v[104:105]
	v_lshl_add_u64 v[110:111], v[24:25], 0, v[110:111]
	v_lshl_add_u64 v[108:109], v[24:25], 0, v[108:109]
	v_lshl_add_u64 v[114:115], v[24:25], 0, v[114:115]
	v_lshl_add_u64 v[112:113], v[24:25], 0, v[112:113]
	v_lshl_add_u64 v[118:119], v[24:25], 0, v[118:119]
	v_lshl_add_u64 v[116:117], v[24:25], 0, v[116:117]
	v_lshl_add_u64 v[122:123], v[24:25], 0, v[122:123]
	v_lshl_add_u64 v[120:121], v[24:25], 0, v[120:121]
	v_lshl_add_u64 v[126:127], v[24:25], 0, v[126:127]
	v_lshl_add_u64 v[124:125], v[24:25], 0, v[124:125]
	global_load_dword v144, v[98:99], off
	global_load_dword v145, v[96:97], off
	global_load_dword v146, v[102:103], off
	global_load_dword v147, v[100:101], off
	global_load_dword v148, v[106:107], off
	global_load_dword v149, v[104:105], off
	global_load_dword v150, v[110:111], off
	global_load_dword v151, v[108:109], off
	global_load_dword v152, v[114:115], off
	global_load_dword v153, v[112:113], off
	global_load_dword v154, v[118:119], off
	global_load_dword v155, v[116:117], off
	global_load_dword v156, v[122:123], off
	global_load_dword v157, v[120:121], off
	global_load_dword v158, v[126:127], off
	global_load_dword v159, v[124:125], off
	s_add_i32 s19, s19, 16
	s_add_i32 s20, s20, 16
	s_add_i32 s9, s9, -16
	v_mad_u64_u32 v[96:97], s[22:23], v129, s6, v[10:11]
	s_cmp_lg_u32 s9, 0
	v_mad_u64_u32 v[98:99], s[22:23], v128, s6, v[10:11]
	v_mad_u64_u32 v[100:101], s[22:23], v131, s6, v[10:11]
	v_mad_u64_u32 v[102:103], s[22:23], v130, s6, v[10:11]
	v_mad_u64_u32 v[104:105], s[22:23], v133, s6, v[10:11]
	v_mad_u64_u32 v[106:107], s[22:23], v132, s6, v[10:11]
	v_mad_u64_u32 v[108:109], s[22:23], v135, s6, v[10:11]
	v_mad_u64_u32 v[110:111], s[22:23], v134, s6, v[10:11]
	v_mad_u64_u32 v[112:113], s[22:23], v137, s6, v[10:11]
	v_mad_u64_u32 v[114:115], s[22:23], v136, s6, v[10:11]
	v_mad_u64_u32 v[116:117], s[22:23], v139, s6, v[10:11]
	v_mad_u64_u32 v[118:119], s[22:23], v138, s6, v[10:11]
	v_mad_u64_u32 v[120:121], s[22:23], v141, s6, v[10:11]
	v_mad_u64_u32 v[122:123], s[22:23], v140, s6, v[10:11]
	v_mad_u64_u32 v[124:125], s[22:23], v143, s6, v[10:11]
	v_mad_u64_u32 v[126:127], s[22:23], v142, s6, v[10:11]
	s_waitcnt vmcnt(31)
; #define LAS __attribute__((address_space(3)))
; __device__ __forceinline__ unsigned cvt_pk_bf16(float lo, float hi) { f32x2_c v = {lo, hi}; bf16x2_c r = __builtin_convertvector(v, bf16x2_c); return __builtin_bit_cast(unsigned, r); }
; #define LDS_WAIT() asm volatile("s_waitcnt lgkmcnt(0)" ::: "memory")
; __device__ __forceinline__ void transpose_item(const float* W, int N, bf16_t* WT, int dstK, size_t drow0, int kdst0, int k0, int n0, LAS float* scr, int lane) {
;     ...
;     for (int i = 0; i < 32; ++i) { const int kk = 2 * i + (lane >> 5); scr[kk * 33 + (lane & 31)] = W[(size_t)(k0 + kk) * N + n0 + (lane & 31)]; }
;     LDS_WAIT();
;     const int c = lane & 7;
; #pragma unroll
;     for (int j = 0; j < 4; ++j) { const int n = (lane >> 3) + 8 * j; const LAS float* s = scr + (8 * c) * 33 + n;
;         u32x4 o; o.x = cvt_pk_bf16(s[0 * 33], s[1 * 33]); o.y = cvt_pk_bf16(s[2 * 33], s[3 * 33]); o.z = cvt_pk_bf16(s[4 * 33], s[5 * 33]); o.w = cvt_pk_bf16(s[6 * 33], s[7 * 33]);
;         *(u32x4*)(WT + (drow0 + n) * dstK + kdst0 + k0 + 8 * c) = o; }
;     LDS_WAIT();
; __device__ __forceinline__ void transpose_matrix(const float* W, int K, int N, bf16_t* WT, int dstK, int kdst0, int mode, LAS float* scr, int gw, int NGW, int lane) {
;     ...
;     for (int it = gw; it < items; it += NGW) {
;         const int kb = it / nblk, nb = it % nblk, n0 = nb * 32;
;         size_t drow0 = (size_t)n0;
;         if (mode == 1) { const int half = n0 >= DFF ? 1 : 0, nn = n0 - half * DFF; drow0 = (size_t)(nn >> 7) * 256 + half * 128 + (nn & 127); }
;         transpose_item(W, N, WT, dstK, drow0, kdst0, kb * 64, n0, scr, lane);
;     }
	ds_write_b32 v26, v66
	s_waitcnt vmcnt(30)
	ds_write_b32 v28, v67
	s_waitcnt vmcnt(29)
	ds_write_b32 v30, v68
	s_waitcnt vmcnt(28)
	ds_write_b32 v32, v69
	s_waitcnt vmcnt(27)
	ds_write_b32 v34, v70
	s_waitcnt vmcnt(26)
	ds_write_b32 v36, v71
	s_waitcnt vmcnt(25)
	ds_write_b32 v38, v72
	s_waitcnt vmcnt(24)
	ds_write_b32 v40, v73
	s_waitcnt vmcnt(23)
	ds_write_b32 v42, v74
	s_waitcnt vmcnt(22)
	ds_write_b32 v44, v75
	s_waitcnt vmcnt(21)
	ds_write_b32 v46, v76
	s_waitcnt vmcnt(20)
	ds_write_b32 v48, v77
	s_waitcnt vmcnt(19)
	ds_write_b32 v50, v78
	s_waitcnt vmcnt(18)
	ds_write_b32 v52, v79
	s_waitcnt vmcnt(17)
	ds_write_b32 v54, v80
	s_waitcnt vmcnt(16)
	ds_write_b32 v56, v81
	s_waitcnt vmcnt(15)
	ds_write_b32 v96, v144
	s_waitcnt vmcnt(14)
	ds_write_b32 v98, v145
	s_waitcnt vmcnt(13)
	ds_write_b32 v100, v146
	s_waitcnt vmcnt(12)
	ds_write_b32 v102, v147
	s_waitcnt vmcnt(11)
	ds_write_b32 v104, v148
	s_waitcnt vmcnt(10)
	ds_write_b32 v106, v149
	s_waitcnt vmcnt(9)
	ds_write_b32 v108, v150
	s_waitcnt vmcnt(8)
	ds_write_b32 v110, v151
	s_waitcnt vmcnt(7)
	ds_write_b32 v112, v152
	s_waitcnt vmcnt(6)
	ds_write_b32 v114, v153
	s_waitcnt vmcnt(5)
	ds_write_b32 v116, v154
	s_waitcnt vmcnt(4)
	ds_write_b32 v118, v155
	s_waitcnt vmcnt(3)
	ds_write_b32 v120, v156
	s_waitcnt vmcnt(2)
	ds_write_b32 v122, v157
	s_waitcnt vmcnt(1)
	ds_write_b32 v124, v158
	s_waitcnt vmcnt(0)
	ds_write_b32 v126, v159
	s_waitcnt lgkmcnt(0)
	ds_read2_b32 v[28:29], v3 offset0:33 offset1:41
	ds_read2_b32 v[30:31], v3 offset1:8
	ds_read2_b32 v[32:33], v3 offset0:66 offset1:74
	ds_read2_b32 v[34:35], v3 offset0:99 offset1:107
	ds_read2_b32 v[36:37], v3 offset0:132 offset1:140
	ds_read2_b32 v[38:39], v3 offset0:165 offset1:173
	ds_read2_b32 v[40:41], v3 offset0:198 offset1:206
	ds_read2_b32 v[42:43], v3 offset0:231 offset1:239
	s_ashr_i32 s19, s18, 31
	v_mov_b32_e32 v47, s3
	v_or_b32_e32 v46, s2, v12
	v_lshl_add_u64 v[44:45], s[18:19], 1, v[22:23]
	v_lshlrev_b64 v[46:47], 12, v[46:47]
	s_waitcnt lgkmcnt(6)
	v_cvt_pk_bf16_f32 v24, v30, v28
	s_waitcnt lgkmcnt(4)
	v_cvt_pk_bf16_f32 v25, v32, v34
	s_waitcnt lgkmcnt(2)
	v_cvt_pk_bf16_f32 v26, v36, v38
	s_waitcnt lgkmcnt(0)
	v_cvt_pk_bf16_f32 v27, v40, v42
	v_lshl_add_u64 v[46:47], v[44:45], 0, v[46:47]
	global_store_dwordx4 v[46:47], v[24:27], off
	v_or_b32_e32 v28, s2, v14
	s_add_i32 s7, s7, s36
	v_cvt_pk_bf16_f32 v24, v31, v29
	v_cvt_pk_bf16_f32 v25, v33, v35
	v_cvt_pk_bf16_f32 v26, v37, v39
	v_cvt_pk_bf16_f32 v27, v41, v43
	v_mov_b32_e32 v29, s3
	ds_read2_b32 v[30:31], v3 offset0:49 offset1:57
	ds_read2_b32 v[32:33], v3 offset0:16 offset1:24
	ds_read2_b32 v[34:35], v3 offset0:82 offset1:90
	ds_read2_b32 v[36:37], v3 offset0:115 offset1:123
	ds_read2_b32 v[38:39], v3 offset0:148 offset1:156
	ds_read2_b32 v[40:41], v3 offset0:181 offset1:189
	ds_read2_b32 v[42:43], v3 offset0:214 offset1:222
	ds_read2_b32 v[46:47], v3 offset0:247 offset1:255
	v_lshlrev_b64 v[28:29], 12, v[28:29]
	v_lshl_add_u64 v[28:29], v[44:45], 0, v[28:29]
	global_store_dwordx4 v[28:29], v[24:27], off
	v_mov_b32_e32 v29, s3
	v_or_b32_e32 v28, s2, v16
	v_lshlrev_b64 v[28:29], 12, v[28:29]
	s_waitcnt lgkmcnt(6)
	v_cvt_pk_bf16_f32 v24, v32, v30
	s_waitcnt lgkmcnt(4)
	v_cvt_pk_bf16_f32 v25, v34, v36
	s_waitcnt lgkmcnt(2)
	v_cvt_pk_bf16_f32 v26, v38, v40
	s_waitcnt lgkmcnt(0)
	v_cvt_pk_bf16_f32 v27, v42, v46
	v_lshl_add_u64 v[28:29], v[44:45], 0, v[28:29]
	global_store_dwordx4 v[28:29], v[24:27], off
	v_mov_b32_e32 v29, s3
	v_or_b32_e32 v28, s2, v18
	v_lshlrev_b64 v[28:29], 12, v[28:29]
	v_cvt_pk_bf16_f32 v24, v33, v31
	v_cvt_pk_bf16_f32 v25, v35, v37
	v_cvt_pk_bf16_f32 v26, v39, v41
	v_cvt_pk_bf16_f32 v27, v43, v47
	v_lshl_add_u64 v[28:29], v[44:45], 0, v[28:29]
	global_store_dwordx4 v[28:29], v[24:27], off
	s_waitcnt lgkmcnt(0)
	s_cmpk_lt_i32 s7, 0x400
	s_cbranch_scc1 .LBB0_29

; __device__ __forceinline__ void transpose_item(const float* W, int N, bf16_t* WT, int dstK, size_t drow0, int kdst0, int k0, int n0, LAS float* scr, int lane) {
; #pragma unroll 8
;     for (int i = 0; i < 32; ++i) { const int kk = 2 * i + (lane >> 5); scr[kk * 33 + (lane & 31)] = W[(size_t)(k0 + kk) * N + n0 + (lane & 31)]; }
.LBB0_35:
	s_lshl_b32 s10, s22, 1
	s_lshl_b32 s11, s21, 1
	v_or_b32_e32 v5, s10, v1
	v_or_b32_e32 v7, s11, v8
	s_add_i32 s23, s10, 4
	s_add_i32 s24, s11, 4
	s_add_i32 s25, s10, 8
	s_add_i32 s27, s11, 8
	s_add_i32 s28, s10, 12
	s_add_i32 s29, s11, 12
	s_add_i32 s30, s10, 16
	s_add_i32 s31, s11, 16
	s_add_i32 s33, s10, 20
	s_add_i32 s34, s11, 20
	s_add_i32 s35, s10, 24
	s_add_i32 s37, s11, 24
	s_add_i32 s10, s10, 28
	s_add_i32 s11, s11, 28
	v_add_u32_e32 v28, s20, v7
	v_or_b32_e32 v9, s23, v1
	v_or_b32_e32 v13, s24, v8
	v_or_b32_e32 v15, s25, v1
	v_or_b32_e32 v19, s27, v8
	v_or_b32_e32 v21, s28, v1
	v_or_b32_e32 v23, s29, v8
	v_or_b32_e32 v58, s30, v1
	v_or_b32_e32 v59, s31, v8
	v_or_b32_e32 v60, s33, v1
	v_or_b32_e32 v61, s34, v8
	v_or_b32_e32 v62, s35, v1
	v_or_b32_e32 v63, s37, v8
	v_or_b32_e32 v64, s10, v1
	v_or_b32_e32 v65, s11, v8
	v_add_u32_e32 v26, s8, v5
	v_ashrrev_i32_e32 v29, 31, v28
	v_add_u32_e32 v30, s8, v9
	v_add_u32_e32 v32, s20, v13
	v_add_u32_e32 v34, s8, v15
	v_add_u32_e32 v36, s20, v19
	v_add_u32_e32 v38, s8, v21
	v_add_u32_e32 v40, s20, v23
	v_add_u32_e32 v42, s8, v58
	v_add_u32_e32 v44, s20, v59
	v_add_u32_e32 v46, s8, v60
	v_add_u32_e32 v48, s20, v61
	v_add_u32_e32 v50, s8, v62
	v_add_u32_e32 v52, s20, v63
	v_add_u32_e32 v54, s8, v64
	v_add_u32_e32 v56, s20, v65
	v_ashrrev_i32_e32 v27, 31, v26
	v_lshlrev_b64 v[28:29], 13, v[28:29]
	v_ashrrev_i32_e32 v33, 31, v32
	v_ashrrev_i32_e32 v31, 31, v30
	v_ashrrev_i32_e32 v37, 31, v36
	v_ashrrev_i32_e32 v35, 31, v34
	v_ashrrev_i32_e32 v41, 31, v40
	v_ashrrev_i32_e32 v39, 31, v38
	v_ashrrev_i32_e32 v45, 31, v44
	v_ashrrev_i32_e32 v43, 31, v42
	v_ashrrev_i32_e32 v49, 31, v48
	v_ashrrev_i32_e32 v47, 31, v46
	v_ashrrev_i32_e32 v53, 31, v52
	v_ashrrev_i32_e32 v51, 31, v50
	v_ashrrev_i32_e32 v57, 31, v56
	v_ashrrev_i32_e32 v55, 31, v54
	v_lshlrev_b64 v[26:27], 13, v[26:27]
	v_lshl_add_u64 v[28:29], v[24:25], 0, v[28:29]
	v_lshlrev_b64 v[30:31], 13, v[30:31]
	v_lshlrev_b64 v[32:33], 13, v[32:33]
	v_lshlrev_b64 v[34:35], 13, v[34:35]
	v_lshlrev_b64 v[36:37], 13, v[36:37]
	v_lshlrev_b64 v[38:39], 13, v[38:39]
	v_lshlrev_b64 v[40:41], 13, v[40:41]
	v_lshlrev_b64 v[42:43], 13, v[42:43]
	v_lshlrev_b64 v[44:45], 13, v[44:45]
	v_lshlrev_b64 v[46:47], 13, v[46:47]
	v_lshlrev_b64 v[48:49], 13, v[48:49]
	v_lshlrev_b64 v[50:51], 13, v[50:51]
	v_lshlrev_b64 v[52:53], 13, v[52:53]
	v_lshlrev_b64 v[54:55], 13, v[54:55]
	v_lshlrev_b64 v[56:57], 13, v[56:57]
	v_lshl_add_u64 v[26:27], v[24:25], 0, v[26:27]
	v_lshl_add_u64 v[32:33], v[24:25], 0, v[32:33]
	v_lshl_add_u64 v[30:31], v[24:25], 0, v[30:31]
	v_lshl_add_u64 v[36:37], v[24:25], 0, v[36:37]
	v_lshl_add_u64 v[34:35], v[24:25], 0, v[34:35]
	v_lshl_add_u64 v[40:41], v[24:25], 0, v[40:41]
	v_lshl_add_u64 v[38:39], v[24:25], 0, v[38:39]
	v_lshl_add_u64 v[44:45], v[24:25], 0, v[44:45]
	v_lshl_add_u64 v[42:43], v[24:25], 0, v[42:43]
	v_lshl_add_u64 v[48:49], v[24:25], 0, v[48:49]
	v_lshl_add_u64 v[46:47], v[24:25], 0, v[46:47]
	v_lshl_add_u64 v[52:53], v[24:25], 0, v[52:53]
	v_lshl_add_u64 v[50:51], v[24:25], 0, v[50:51]
	v_lshl_add_u64 v[56:57], v[24:25], 0, v[56:57]
	v_lshl_add_u64 v[54:55], v[24:25], 0, v[54:55]
	global_load_dword v66, v[28:29], off
	global_load_dword v67, v[26:27], off
	global_load_dword v68, v[32:33], off
	global_load_dword v69, v[30:31], off
	global_load_dword v70, v[36:37], off
	global_load_dword v71, v[34:35], off
	global_load_dword v72, v[40:41], off
	global_load_dword v73, v[38:39], off
	global_load_dword v74, v[44:45], off
	global_load_dword v75, v[42:43], off
	global_load_dword v76, v[48:49], off
	global_load_dword v77, v[46:47], off
	global_load_dword v78, v[52:53], off
	global_load_dword v79, v[50:51], off
	global_load_dword v80, v[56:57], off
	global_load_dword v81, v[54:55], off
	s_add_i32 s21, s21, 16
	s_add_i32 s22, s22, 16
	s_add_i32 s9, s9, -16
	v_mad_u64_u32 v[26:27], s[24:25], v7, s6, v[12:13]
	s_cmp_lg_u32 s9, 0
	v_mad_u64_u32 v[28:29], s[24:25], v5, s6, v[12:13]
	v_mad_u64_u32 v[30:31], s[24:25], v13, s6, v[12:13]
	v_mad_u64_u32 v[32:33], s[24:25], v9, s6, v[12:13]
	v_mad_u64_u32 v[34:35], s[24:25], v19, s6, v[12:13]
	v_mad_u64_u32 v[36:37], s[24:25], v15, s6, v[12:13]
	v_mad_u64_u32 v[38:39], s[24:25], v23, s6, v[12:13]
	v_mad_u64_u32 v[40:41], s[24:25], v21, s6, v[12:13]
	v_mad_u64_u32 v[42:43], s[24:25], v59, s6, v[12:13]
	v_mad_u64_u32 v[44:45], s[24:25], v58, s6, v[12:13]
	v_mad_u64_u32 v[46:47], s[24:25], v61, s6, v[12:13]
	v_mad_u64_u32 v[48:49], s[24:25], v60, s6, v[12:13]
	v_mad_u64_u32 v[50:51], s[24:25], v63, s6, v[12:13]
	v_mad_u64_u32 v[52:53], s[24:25], v62, s6, v[12:13]
	v_mad_u64_u32 v[54:55], s[24:25], v65, s6, v[12:13]
	v_mad_u64_u32 v[56:57], s[24:25], v64, s6, v[12:13]
	s_lshl_b32 s10, s22, 1
	s_lshl_b32 s11, s21, 1
	v_or_b32_e32 v128, s10, v1
	v_or_b32_e32 v129, s11, v8
	s_add_i32 s23, s10, 4
	s_add_i32 s24, s11, 4
	s_add_i32 s25, s10, 8
	s_add_i32 s27, s11, 8
	s_add_i32 s28, s10, 12
	s_add_i32 s29, s11, 12
	s_add_i32 s30, s10, 16
	s_add_i32 s31, s11, 16
	s_add_i32 s33, s10, 20
	s_add_i32 s34, s11, 20
	s_add_i32 s35, s10, 24
	s_add_i32 s37, s11, 24
	s_add_i32 s10, s10, 28
	s_add_i32 s11, s11, 28
	v_add_u32_e32 v98, s20, v129
	v_or_b32_e32 v130, s23, v1
	v_or_b32_e32 v131, s24, v8
	v_or_b32_e32 v132, s25, v1
	v_or_b32_e32 v133, s27, v8
	v_or_b32_e32 v134, s28, v1
	v_or_b32_e32 v135, s29, v8
	v_or_b32_e32 v136, s30, v1
	v_or_b32_e32 v137, s31, v8
	v_or_b32_e32 v138, s33, v1
	v_or_b32_e32 v139, s34, v8
	v_or_b32_e32 v140, s35, v1
	v_or_b32_e32 v141, s37, v8
	v_or_b32_e32 v142, s10, v1
	v_or_b32_e32 v143, s11, v8
	v_add_u32_e32 v96, s8, v128
	v_ashrrev_i32_e32 v99, 31, v98
	v_add_u32_e32 v100, s8, v130
; __device__ __forceinline__ void transpose_item(const float* W, int N, bf16_t* WT, int dstK, size_t drow0, int kdst0, int k0, int n0, LAS float* scr, int lane) {
; #pragma unroll 8
;     for (int i = 0; i < 32; ++i) { const int kk = 2 * i + (lane >> 5); scr[kk * 33 + (lane & 31)] = W[(size_t)(k0 + kk) * N + n0 + (lane & 31)]; }
	v_add_u32_e32 v102, s20, v131
	v_add_u32_e32 v104, s8, v132
	v_add_u32_e32 v106, s20, v133
	v_add_u32_e32 v108, s8, v134
	v_add_u32_e32 v110, s20, v135
	v_add_u32_e32 v112, s8, v136
	v_add_u32_e32 v114, s20, v137
	v_add_u32_e32 v116, s8, v138
	v_add_u32_e32 v118, s20, v139
	v_add_u32_e32 v120, s8, v140
	v_add_u32_e32 v122, s20, v141
	v_add_u32_e32 v124, s8, v142
	v_add_u32_e32 v126, s20, v143
	v_ashrrev_i32_e32 v97, 31, v96
	v_lshlrev_b64 v[98:99], 13, v[98:99]
	v_ashrrev_i32_e32 v103, 31, v102
	v_ashrrev_i32_e32 v101, 31, v100
	v_ashrrev_i32_e32 v107, 31, v106
	v_ashrrev_i32_e32 v105, 31, v104
	v_ashrrev_i32_e32 v111, 31, v110
	v_ashrrev_i32_e32 v109, 31, v108
	v_ashrrev_i32_e32 v115, 31, v114
	v_ashrrev_i32_e32 v113, 31, v112
	v_ashrrev_i32_e32 v119, 31, v118
	v_ashrrev_i32_e32 v117, 31, v116
	v_ashrrev_i32_e32 v123, 31, v122
	v_ashrrev_i32_e32 v121, 31, v120
	v_ashrrev_i32_e32 v127, 31, v126
	v_ashrrev_i32_e32 v125, 31, v124
	v_lshlrev_b64 v[96:97], 13, v[96:97]
	v_lshl_add_u64 v[98:99], v[24:25], 0, v[98:99]
	v_lshlrev_b64 v[100:101], 13, v[100:101]
	v_lshlrev_b64 v[102:103], 13, v[102:103]
	v_lshlrev_b64 v[104:105], 13, v[104:105]
	v_lshlrev_b64 v[106:107], 13, v[106:107]
	v_lshlrev_b64 v[108:109], 13, v[108:109]
	v_lshlrev_b64 v[110:111], 13, v[110:111]
	v_lshlrev_b64 v[112:113], 13, v[112:113]
	v_lshlrev_b64 v[114:115], 13, v[114:115]
	v_lshlrev_b64 v[116:117], 13, v[116:117]
	v_lshlrev_b64 v[118:119], 13, v[118:119]
	v_lshlrev_b64 v[120:121], 13, v[120:121]
	v_lshlrev_b64 v[122:123], 13, v[122:123]
	v_lshlrev_b64 v[124:125], 13, v[124:125]
	v_lshlrev_b64 v[126:127], 13, v[126:127]
	v_lshl_add_u64 v[96:97], v[24:25], 0, v[96:97]
	v_lshl_add_u64 v[102:103], v[24:25], 0, v[102:103]
	v_lshl_add_u64 v[100:101], v[24:25], 0, v[100:101]
	v_lshl_add_u64 v[106:107], v[24:25], 0, v[106:107]
	v_lshl_add_u64 v[104:105], v[24:25], 0, v[104:105]
	v_lshl_add_u64 v[110:111], v[24:25], 0, v[110:111]
	v_lshl_add_u64 v[108:109], v[24:25], 0, v[108:109]
	v_lshl_add_u64 v[114:115], v[24:25], 0, v[114:115]
	v_lshl_add_u64 v[112:113], v[24:25], 0, v[112:113]
	v_lshl_add_u64 v[118:119], v[24:25], 0, v[118:119]
	v_lshl_add_u64 v[116:117], v[24:25], 0, v[116:117]
	v_lshl_add_u64 v[122:123], v[24:25], 0, v[122:123]
	v_lshl_add_u64 v[120:121], v[24:25], 0, v[120:121]
	v_lshl_add_u64 v[126:127], v[24:25], 0, v[126:127]
	v_lshl_add_u64 v[124:125], v[24:25], 0, v[124:125]
	global_load_dword v144, v[98:99], off
	global_load_dword v145, v[96:97], off
	global_load_dword v146, v[102:103], off
	global_load_dword v147, v[100:101], off
	global_load_dword v148, v[106:107], off
	global_load_dword v149, v[104:105], off
	global_load_dword v150, v[110:111], off
	global_load_dword v151, v[108:109], off
	global_load_dword v152, v[114:115], off
	global_load_dword v153, v[112:113], off
	global_load_dword v154, v[118:119], off
	global_load_dword v155, v[116:117], off
	global_load_dword v156, v[122:123], off
	global_load_dword v157, v[120:121], off
	global_load_dword v158, v[126:127], off
	global_load_dword v159, v[124:125], off
	s_add_i32 s21, s21, 16
	s_add_i32 s22, s22, 16
	s_add_i32 s9, s9, -16
	v_mad_u64_u32 v[96:97], s[24:25], v129, s6, v[12:13]
	s_cmp_lg_u32 s9, 0
	v_mad_u64_u32 v[98:99], s[24:25], v128, s6, v[12:13]
	v_mad_u64_u32 v[100:101], s[24:25], v131, s6, v[12:13]
	v_mad_u64_u32 v[102:103], s[24:25], v130, s6, v[12:13]
	v_mad_u64_u32 v[104:105], s[24:25], v133, s6, v[12:13]
	v_mad_u64_u32 v[106:107], s[24:25], v132, s6, v[12:13]
	v_mad_u64_u32 v[108:109], s[24:25], v135, s6, v[12:13]
	v_mad_u64_u32 v[110:111], s[24:25], v134, s6, v[12:13]
	v_mad_u64_u32 v[112:113], s[24:25], v137, s6, v[12:13]
	v_mad_u64_u32 v[114:115], s[24:25], v136, s6, v[12:13]
	v_mad_u64_u32 v[116:117], s[24:25], v139, s6, v[12:13]
	v_mad_u64_u32 v[118:119], s[24:25], v138, s6, v[12:13]
	v_mad_u64_u32 v[120:121], s[24:25], v141, s6, v[12:13]
	v_mad_u64_u32 v[122:123], s[24:25], v140, s6, v[12:13]
	v_mad_u64_u32 v[124:125], s[24:25], v143, s6, v[12:13]
	v_mad_u64_u32 v[126:127], s[24:25], v142, s6, v[12:13]
	s_waitcnt vmcnt(31)
	ds_write_b32 v26, v66
	s_waitcnt vmcnt(30)
	ds_write_b32 v28, v67
	s_waitcnt vmcnt(29)
	ds_write_b32 v30, v68
	s_waitcnt vmcnt(28)
; #define LAS __attribute__((address_space(3)))
; __device__ __forceinline__ unsigned cvt_pk_bf16(float lo, float hi) { f32x2_c v = {lo, hi}; bf16x2_c r = __builtin_convertvector(v, bf16x2_c); return __builtin_bit_cast(unsigned, r); }
; #define LDS_WAIT() asm volatile("s_waitcnt lgkmcnt(0)" ::: "memory")
; __device__ __forceinline__ void transpose_item(const float* W, int N, bf16_t* WT, int dstK, size_t drow0, int kdst0, int k0, int n0, LAS float* scr, int lane) {
;     ...
;     for (int i = 0; i < 32; ++i) { const int kk = 2 * i + (lane >> 5); scr[kk * 33 + (lane & 31)] = W[(size_t)(k0 + kk) * N + n0 + (lane & 31)]; }
;     LDS_WAIT();
;     const int c = lane & 7;
; #pragma unroll
;     for (int j = 0; j < 4; ++j) { const int n = (lane >> 3) + 8 * j; const LAS float* s = scr + (8 * c) * 33 + n;
;         u32x4 o; o.x = cvt_pk_bf16(s[0 * 33], s[1 * 33]); o.y = cvt_pk_bf16(s[2 * 33], s[3 * 33]); o.z = cvt_pk_bf16(s[4 * 33], s[5 * 33]); o.w = cvt_pk_bf16(s[6 * 33], s[7 * 33]);
;         *(u32x4*)(WT + (drow0 + n) * dstK + kdst0 + k0 + 8 * c) = o; }
;     LDS_WAIT();
; }
; __device__ __forceinline__ void transpose_matrix(const float* W, int K, int N, bf16_t* WT, int dstK, int kdst0, int mode, LAS float* scr, int gw, int NGW, int lane) {
;     const int nblk = N / 32, items = (K / 64) * nblk;
;     for (int it = gw; it < items; it += NGW) {
;         const int kb = it / nblk, nb = it % nblk, n0 = nb * 32;
;         size_t drow0 = (size_t)n0;
;         if (mode == 1) { const int half = n0 >= DFF ? 1 : 0, nn = n0 - half * DFF; drow0 = (size_t)(nn >> 7) * 256 + half * 128 + (nn & 127); }
;         transpose_item(W, N, WT, dstK, drow0, kdst0, kb * 64, n0, scr, lane);
;     }
	ds_write_b32 v32, v69
	s_waitcnt vmcnt(27)
	ds_write_b32 v34, v70
	s_waitcnt vmcnt(26)
	ds_write_b32 v36, v71
	s_waitcnt vmcnt(25)
	ds_write_b32 v38, v72
	s_waitcnt vmcnt(24)
	ds_write_b32 v40, v73
	s_waitcnt vmcnt(23)
	ds_write_b32 v42, v74
	s_waitcnt vmcnt(22)
	ds_write_b32 v44, v75
	s_waitcnt vmcnt(21)
	ds_write_b32 v46, v76
	s_waitcnt vmcnt(20)
	ds_write_b32 v48, v77
	s_waitcnt vmcnt(19)
	ds_write_b32 v50, v78
	s_waitcnt vmcnt(18)
	ds_write_b32 v52, v79
	s_waitcnt vmcnt(17)
	ds_write_b32 v54, v80
	s_waitcnt vmcnt(16)
	ds_write_b32 v56, v81
	s_waitcnt vmcnt(15)
	ds_write_b32 v96, v144
	s_waitcnt vmcnt(14)
	ds_write_b32 v98, v145
	s_waitcnt vmcnt(13)
	ds_write_b32 v100, v146
	s_waitcnt vmcnt(12)
	ds_write_b32 v102, v147
	s_waitcnt vmcnt(11)
	ds_write_b32 v104, v148
	s_waitcnt vmcnt(10)
	ds_write_b32 v106, v149
	s_waitcnt vmcnt(9)
	ds_write_b32 v108, v150
	s_waitcnt vmcnt(8)
	ds_write_b32 v110, v151
	s_waitcnt vmcnt(7)
	ds_write_b32 v112, v152
	s_waitcnt vmcnt(6)
	ds_write_b32 v114, v153
	s_waitcnt vmcnt(5)
	ds_write_b32 v116, v154
	s_waitcnt vmcnt(4)
	ds_write_b32 v118, v155
	s_waitcnt vmcnt(3)
	ds_write_b32 v120, v156
	s_waitcnt vmcnt(2)
	ds_write_b32 v122, v157
	s_waitcnt vmcnt(1)
	ds_write_b32 v124, v158
	s_waitcnt vmcnt(0)
	ds_write_b32 v126, v159
	s_waitcnt lgkmcnt(0)
	ds_read2_b32 v[28:29], v3 offset0:33 offset1:41
	ds_read2_b32 v[30:31], v3 offset1:8
	ds_read2_b32 v[32:33], v3 offset0:66 offset1:74
	ds_read2_b32 v[34:35], v3 offset0:99 offset1:107
	ds_read2_b32 v[36:37], v3 offset0:132 offset1:140
	ds_read2_b32 v[38:39], v3 offset0:165 offset1:173
	ds_read2_b32 v[40:41], v3 offset0:198 offset1:206
	ds_read2_b32 v[42:43], v3 offset0:231 offset1:239
	s_ashr_i32 s21, s20, 31
	v_mov_b32_e32 v47, s3
	v_or_b32_e32 v46, s2, v14
	v_lshl_add_u64 v[44:45], s[20:21], 1, v[16:17]
	v_lshlrev_b64 v[46:47], 12, v[46:47]
	s_waitcnt lgkmcnt(6)
	v_cvt_pk_bf16_f32 v24, v30, v28
	s_waitcnt lgkmcnt(4)
	v_cvt_pk_bf16_f32 v25, v32, v34
	s_waitcnt lgkmcnt(2)
	v_cvt_pk_bf16_f32 v26, v36, v38
	s_waitcnt lgkmcnt(0)
	v_cvt_pk_bf16_f32 v27, v40, v42
	v_lshl_add_u64 v[46:47], v[44:45], 0, v[46:47]
	global_store_dwordx4 v[46:47], v[24:27], off
	v_or_b32_e32 v28, s2, v18
	s_add_i32 s7, s7, s36
	v_cvt_pk_bf16_f32 v24, v31, v29
	v_cvt_pk_bf16_f32 v25, v33, v35
	v_cvt_pk_bf16_f32 v26, v37, v39
	v_cvt_pk_bf16_f32 v27, v41, v43
	v_mov_b32_e32 v29, s3
	ds_read2_b32 v[30:31], v3 offset0:49 offset1:57
	ds_read2_b32 v[32:33], v3 offset0:16 offset1:24
	ds_read2_b32 v[34:35], v3 offset0:82 offset1:90
	ds_read2_b32 v[36:37], v3 offset0:115 offset1:123
	ds_read2_b32 v[38:39], v3 offset0:148 offset1:156
	ds_read2_b32 v[40:41], v3 offset0:181 offset1:189
	ds_read2_b32 v[42:43], v3 offset0:214 offset1:222
	ds_read2_b32 v[46:47], v3 offset0:247 offset1:255
	v_lshlrev_b64 v[28:29], 12, v[28:29]
	v_lshl_add_u64 v[28:29], v[44:45], 0, v[28:29]
	global_store_dwordx4 v[28:29], v[24:27], off
	v_mov_b32_e32 v29, s3
	v_or_b32_e32 v28, s2, v20
	v_lshlrev_b64 v[28:29], 12, v[28:29]
	s_waitcnt lgkmcnt(6)
	v_cvt_pk_bf16_f32 v24, v32, v30
	s_waitcnt lgkmcnt(4)
	v_cvt_pk_bf16_f32 v25, v34, v36
	s_waitcnt lgkmcnt(2)
	v_cvt_pk_bf16_f32 v26, v38, v40
	s_waitcnt lgkmcnt(0)
	v_cvt_pk_bf16_f32 v27, v42, v46
	v_lshl_add_u64 v[28:29], v[44:45], 0, v[28:29]
	global_store_dwordx4 v[28:29], v[24:27], off
	v_mov_b32_e32 v29, s3
	v_or_b32_e32 v28, s2, v22
	v_lshlrev_b64 v[28:29], 12, v[28:29]
	v_cvt_pk_bf16_f32 v24, v33, v31
	v_cvt_pk_bf16_f32 v25, v35, v37
	v_cvt_pk_bf16_f32 v26, v39, v41
	v_cvt_pk_bf16_f32 v27, v43, v47
	v_lshl_add_u64 v[28:29], v[44:45], 0, v[28:29]
	global_store_dwordx4 v[28:29], v[24:27], off
	s_waitcnt lgkmcnt(0)
	s_cmpk_lt_i32 s7, 0x800
	s_cbranch_scc1 .LBB0_34
	v_readlane_b32 s48, v245, 24
	v_readlane_b32 s49, v245, 25
	v_readlane_b32 s56, v245, 32
	v_readlane_b32 s57, v245, 33
	v_readlane_b32 s60, v245, 36
	v_readlane_b32 s61, v245, 37
	v_readlane_b32 s50, v245, 26
	v_readlane_b32 s51, v245, 27
	v_readlane_b32 s52, v245, 28
	v_readlane_b32 s53, v245, 29
	v_readlane_b32 s54, v245, 30
	v_readlane_b32 s55, v245, 31
	v_readlane_b32 s58, v245, 34
	v_readlane_b32 s59, v245, 35
	v_readlane_b32 s62, v245, 38
	v_readlane_b32 s63, v245, 39

; __device__ __forceinline__ void transpose_item(const float* W, int N, bf16_t* WT, int dstK, size_t drow0, int kdst0, int k0, int n0, LAS float* scr, int lane) {
; #pragma unroll 8
;     for (int i = 0; i < 32; ++i) { const int kk = 2 * i + (lane >> 5); scr[kk * 33 + (lane & 31)] = W[(size_t)(k0 + kk) * N + n0 + (lane & 31)]; }
.LBB0_46:
	s_lshl_b32 s10, s22, 1
	s_lshl_b32 s11, s21, 1
	v_or_b32_e32 v5, s10, v1
	v_or_b32_e32 v7, s11, v10
	s_add_i32 s23, s10, 4
	s_add_i32 s24, s11, 4
	s_add_i32 s25, s10, 8
	s_add_i32 s27, s11, 8
	s_add_i32 s28, s10, 12
	s_add_i32 s29, s11, 12
	s_add_i32 s30, s10, 16
	s_add_i32 s31, s11, 16
	s_add_i32 s33, s10, 20
	s_add_i32 s34, s11, 20
	s_add_i32 s35, s10, 24
	s_add_i32 s37, s11, 24
	s_add_i32 s10, s10, 28
	s_add_i32 s11, s11, 28
	v_add_u32_e32 v30, s20, v7
	v_or_b32_e32 v9, s23, v1
	v_or_b32_e32 v11, s24, v10
	v_or_b32_e32 v15, s25, v1
	v_or_b32_e32 v17, s27, v10
	v_or_b32_e32 v21, s28, v1
	v_or_b32_e32 v23, s29, v10
	v_or_b32_e32 v25, s30, v1
	v_or_b32_e32 v51, s31, v10
	v_or_b32_e32 v62, s33, v1
	v_or_b32_e32 v63, s34, v10
	v_or_b32_e32 v64, s35, v1
	v_or_b32_e32 v65, s37, v10
	v_or_b32_e32 v66, s10, v1
	v_or_b32_e32 v67, s11, v10
	v_add_u32_e32 v28, s8, v5
	v_ashrrev_i32_e32 v31, 31, v30
	v_add_u32_e32 v32, s8, v9
	v_add_u32_e32 v34, s20, v11
	v_add_u32_e32 v36, s8, v15
	v_add_u32_e32 v38, s20, v17
	v_add_u32_e32 v40, s8, v21
	v_add_u32_e32 v42, s20, v23
	v_add_u32_e32 v44, s8, v25
	v_add_u32_e32 v46, s20, v51
	v_add_u32_e32 v48, s8, v62
	v_add_u32_e32 v52, s20, v63
	v_add_u32_e32 v54, s8, v64
	v_add_u32_e32 v56, s20, v65
	v_add_u32_e32 v58, s8, v66
	v_add_u32_e32 v60, s20, v67
	v_ashrrev_i32_e32 v29, 31, v28
	v_lshlrev_b64 v[30:31], 14, v[30:31]
	v_ashrrev_i32_e32 v35, 31, v34
	v_ashrrev_i32_e32 v33, 31, v32
	v_ashrrev_i32_e32 v39, 31, v38
	v_ashrrev_i32_e32 v37, 31, v36
	v_ashrrev_i32_e32 v43, 31, v42
	v_ashrrev_i32_e32 v41, 31, v40
	v_ashrrev_i32_e32 v47, 31, v46
	v_ashrrev_i32_e32 v45, 31, v44
	v_ashrrev_i32_e32 v53, 31, v52
	v_ashrrev_i32_e32 v49, 31, v48
	v_ashrrev_i32_e32 v57, 31, v56
	v_ashrrev_i32_e32 v55, 31, v54
	v_ashrrev_i32_e32 v61, 31, v60
	v_ashrrev_i32_e32 v59, 31, v58
	v_lshlrev_b64 v[28:29], 14, v[28:29]
	v_lshl_add_u64 v[30:31], v[26:27], 0, v[30:31]
	v_lshlrev_b64 v[32:33], 14, v[32:33]
	v_lshlrev_b64 v[34:35], 14, v[34:35]
	v_lshlrev_b64 v[36:37], 14, v[36:37]
	v_lshlrev_b64 v[38:39], 14, v[38:39]
	v_lshlrev_b64 v[40:41], 14, v[40:41]
	v_lshlrev_b64 v[42:43], 14, v[42:43]
	v_lshlrev_b64 v[44:45], 14, v[44:45]
	v_lshlrev_b64 v[46:47], 14, v[46:47]
	v_lshlrev_b64 v[48:49], 14, v[48:49]
	v_lshlrev_b64 v[52:53], 14, v[52:53]
	v_lshlrev_b64 v[54:55], 14, v[54:55]
	v_lshlrev_b64 v[56:57], 14, v[56:57]
	v_lshlrev_b64 v[58:59], 14, v[58:59]
	v_lshlrev_b64 v[60:61], 14, v[60:61]
	v_lshl_add_u64 v[28:29], v[26:27], 0, v[28:29]
	v_lshl_add_u64 v[34:35], v[26:27], 0, v[34:35]
	v_lshl_add_u64 v[32:33], v[26:27], 0, v[32:33]
	v_lshl_add_u64 v[38:39], v[26:27], 0, v[38:39]
	v_lshl_add_u64 v[36:37], v[26:27], 0, v[36:37]
	v_lshl_add_u64 v[42:43], v[26:27], 0, v[42:43]
	v_lshl_add_u64 v[40:41], v[26:27], 0, v[40:41]
	v_lshl_add_u64 v[46:47], v[26:27], 0, v[46:47]
	v_lshl_add_u64 v[44:45], v[26:27], 0, v[44:45]
	v_lshl_add_u64 v[52:53], v[26:27], 0, v[52:53]
	v_lshl_add_u64 v[48:49], v[26:27], 0, v[48:49]
	v_lshl_add_u64 v[56:57], v[26:27], 0, v[56:57]
	v_lshl_add_u64 v[54:55], v[26:27], 0, v[54:55]
	v_lshl_add_u64 v[60:61], v[26:27], 0, v[60:61]
	v_lshl_add_u64 v[58:59], v[26:27], 0, v[58:59]
	global_load_dword v68, v[30:31], off
	global_load_dword v69, v[28:29], off
	global_load_dword v70, v[34:35], off
	global_load_dword v71, v[32:33], off
	global_load_dword v72, v[38:39], off
	global_load_dword v73, v[36:37], off
	global_load_dword v74, v[42:43], off
	global_load_dword v75, v[40:41], off
	global_load_dword v76, v[46:47], off
	global_load_dword v77, v[44:45], off
	global_load_dword v78, v[52:53], off
	global_load_dword v79, v[48:49], off
	global_load_dword v80, v[56:57], off
	global_load_dword v81, v[54:55], off
	global_load_dword v82, v[60:61], off
	global_load_dword v83, v[58:59], off
	s_add_i32 s21, s21, 16
	s_add_i32 s22, s22, 16
	s_add_i32 s9, s9, -16
	v_mad_u64_u32 v[28:29], s[24:25], v7, s6, v[14:15]
	s_cmp_lg_u32 s9, 0
	v_mad_u64_u32 v[30:31], s[24:25], v5, s6, v[14:15]
	v_mad_u64_u32 v[32:33], s[24:25], v11, s6, v[14:15]
	v_mad_u64_u32 v[34:35], s[24:25], v9, s6, v[14:15]
	v_mad_u64_u32 v[36:37], s[24:25], v17, s6, v[14:15]
	v_mad_u64_u32 v[38:39], s[24:25], v15, s6, v[14:15]
	v_mad_u64_u32 v[40:41], s[24:25], v23, s6, v[14:15]
	v_mad_u64_u32 v[42:43], s[24:25], v21, s6, v[14:15]
	v_mad_u64_u32 v[44:45], s[24:25], v51, s6, v[14:15]
	v_mad_u64_u32 v[46:47], s[24:25], v25, s6, v[14:15]
	v_mad_u64_u32 v[48:49], s[24:25], v63, s6, v[14:15]
	v_mad_u64_u32 v[52:53], s[24:25], v62, s6, v[14:15]
	v_mad_u64_u32 v[54:55], s[24:25], v65, s6, v[14:15]
	v_mad_u64_u32 v[56:57], s[24:25], v64, s6, v[14:15]
	v_mad_u64_u32 v[58:59], s[24:25], v67, s6, v[14:15]
	v_mad_u64_u32 v[60:61], s[24:25], v66, s6, v[14:15]
	s_lshl_b32 s10, s22, 1
	s_lshl_b32 s11, s21, 1
	v_or_b32_e32 v128, s10, v1
	v_or_b32_e32 v129, s11, v10
	s_add_i32 s23, s10, 4
	s_add_i32 s24, s11, 4
	s_add_i32 s25, s10, 8
	s_add_i32 s27, s11, 8
	s_add_i32 s28, s10, 12
	s_add_i32 s29, s11, 12
	s_add_i32 s30, s10, 16
	s_add_i32 s31, s11, 16
	s_add_i32 s33, s10, 20
	s_add_i32 s34, s11, 20
	s_add_i32 s35, s10, 24
	s_add_i32 s37, s11, 24
	s_add_i32 s10, s10, 28
	s_add_i32 s11, s11, 28
	v_add_u32_e32 v98, s20, v129
	v_or_b32_e32 v130, s23, v1
	v_or_b32_e32 v131, s24, v10
	v_or_b32_e32 v132, s25, v1
	v_or_b32_e32 v133, s27, v10
	v_or_b32_e32 v134, s28, v1
	v_or_b32_e32 v135, s29, v10
	v_or_b32_e32 v136, s30, v1
	v_or_b32_e32 v137, s31, v10
	v_or_b32_e32 v138, s33, v1
	v_or_b32_e32 v139, s34, v10
	v_or_b32_e32 v140, s35, v1
	v_or_b32_e32 v141, s37, v10
	v_or_b32_e32 v142, s10, v1
	v_or_b32_e32 v143, s11, v10
	v_add_u32_e32 v96, s8, v128
	v_ashrrev_i32_e32 v99, 31, v98
; __device__ __forceinline__ void transpose_item(const float* W, int N, bf16_t* WT, int dstK, size_t drow0, int kdst0, int k0, int n0, LAS float* scr, int lane) {
; #pragma unroll 8
;     for (int i = 0; i < 32; ++i) { const int kk = 2 * i + (lane >> 5); scr[kk * 33 + (lane & 31)] = W[(size_t)(k0 + kk) * N + n0 + (lane & 31)]; }
	v_add_u32_e32 v100, s8, v130
	v_add_u32_e32 v102, s20, v131
	v_add_u32_e32 v104, s8, v132
	v_add_u32_e32 v106, s20, v133
	v_add_u32_e32 v108, s8, v134
	v_add_u32_e32 v110, s20, v135
	v_add_u32_e32 v112, s8, v136
	v_add_u32_e32 v114, s20, v137
	v_add_u32_e32 v116, s8, v138
	v_add_u32_e32 v118, s20, v139
	v_add_u32_e32 v120, s8, v140
	v_add_u32_e32 v122, s20, v141
	v_add_u32_e32 v124, s8, v142
	v_add_u32_e32 v126, s20, v143
	v_ashrrev_i32_e32 v97, 31, v96
	v_lshlrev_b64 v[98:99], 14, v[98:99]
	v_ashrrev_i32_e32 v103, 31, v102
	v_ashrrev_i32_e32 v101, 31, v100
	v_ashrrev_i32_e32 v107, 31, v106
	v_ashrrev_i32_e32 v105, 31, v104
	v_ashrrev_i32_e32 v111, 31, v110
	v_ashrrev_i32_e32 v109, 31, v108
	v_ashrrev_i32_e32 v115, 31, v114
	v_ashrrev_i32_e32 v113, 31, v112
	v_ashrrev_i32_e32 v119, 31, v118
	v_ashrrev_i32_e32 v117, 31, v116
	v_ashrrev_i32_e32 v123, 31, v122
	v_ashrrev_i32_e32 v121, 31, v120
	v_ashrrev_i32_e32 v127, 31, v126
	v_ashrrev_i32_e32 v125, 31, v124
	v_lshlrev_b64 v[96:97], 14, v[96:97]
	v_lshl_add_u64 v[98:99], v[26:27], 0, v[98:99]
	v_lshlrev_b64 v[100:101], 14, v[100:101]
	v_lshlrev_b64 v[102:103], 14, v[102:103]
	v_lshlrev_b64 v[104:105], 14, v[104:105]
	v_lshlrev_b64 v[106:107], 14, v[106:107]
	v_lshlrev_b64 v[108:109], 14, v[108:109]
	v_lshlrev_b64 v[110:111], 14, v[110:111]
	v_lshlrev_b64 v[112:113], 14, v[112:113]
	v_lshlrev_b64 v[114:115], 14, v[114:115]
	v_lshlrev_b64 v[116:117], 14, v[116:117]
	v_lshlrev_b64 v[118:119], 14, v[118:119]
	v_lshlrev_b64 v[120:121], 14, v[120:121]
	v_lshlrev_b64 v[122:123], 14, v[122:123]
	v_lshlrev_b64 v[124:125], 14, v[124:125]
	v_lshlrev_b64 v[126:127], 14, v[126:127]
	v_lshl_add_u64 v[96:97], v[26:27], 0, v[96:97]
	v_lshl_add_u64 v[102:103], v[26:27], 0, v[102:103]
	v_lshl_add_u64 v[100:101], v[26:27], 0, v[100:101]
	v_lshl_add_u64 v[106:107], v[26:27], 0, v[106:107]
	v_lshl_add_u64 v[104:105], v[26:27], 0, v[104:105]
	v_lshl_add_u64 v[110:111], v[26:27], 0, v[110:111]
	v_lshl_add_u64 v[108:109], v[26:27], 0, v[108:109]
	v_lshl_add_u64 v[114:115], v[26:27], 0, v[114:115]
	v_lshl_add_u64 v[112:113], v[26:27], 0, v[112:113]
	v_lshl_add_u64 v[118:119], v[26:27], 0, v[118:119]
	v_lshl_add_u64 v[116:117], v[26:27], 0, v[116:117]
	v_lshl_add_u64 v[122:123], v[26:27], 0, v[122:123]
	v_lshl_add_u64 v[120:121], v[26:27], 0, v[120:121]
	v_lshl_add_u64 v[126:127], v[26:27], 0, v[126:127]
	v_lshl_add_u64 v[124:125], v[26:27], 0, v[124:125]
	global_load_dword v144, v[98:99], off
	global_load_dword v145, v[96:97], off
	global_load_dword v146, v[102:103], off
	global_load_dword v147, v[100:101], off
	global_load_dword v148, v[106:107], off
	global_load_dword v149, v[104:105], off
	global_load_dword v150, v[110:111], off
	global_load_dword v151, v[108:109], off
	global_load_dword v152, v[114:115], off
	global_load_dword v153, v[112:113], off
	global_load_dword v154, v[118:119], off
	global_load_dword v155, v[116:117], off
	global_load_dword v156, v[122:123], off
	global_load_dword v157, v[120:121], off
	global_load_dword v158, v[126:127], off
	global_load_dword v159, v[124:125], off
	s_add_i32 s21, s21, 16
	s_add_i32 s22, s22, 16
	s_add_i32 s9, s9, -16
	v_mad_u64_u32 v[96:97], s[24:25], v129, s6, v[14:15]
	s_cmp_lg_u32 s9, 0
	v_mad_u64_u32 v[98:99], s[24:25], v128, s6, v[14:15]
	v_mad_u64_u32 v[100:101], s[24:25], v131, s6, v[14:15]
	v_mad_u64_u32 v[102:103], s[24:25], v130, s6, v[14:15]
	v_mad_u64_u32 v[104:105], s[24:25], v133, s6, v[14:15]
	v_mad_u64_u32 v[106:107], s[24:25], v132, s6, v[14:15]
	v_mad_u64_u32 v[108:109], s[24:25], v135, s6, v[14:15]
	v_mad_u64_u32 v[110:111], s[24:25], v134, s6, v[14:15]
	v_mad_u64_u32 v[112:113], s[24:25], v137, s6, v[14:15]
	v_mad_u64_u32 v[114:115], s[24:25], v136, s6, v[14:15]
	v_mad_u64_u32 v[116:117], s[24:25], v139, s6, v[14:15]
	v_mad_u64_u32 v[118:119], s[24:25], v138, s6, v[14:15]
	v_mad_u64_u32 v[120:121], s[24:25], v141, s6, v[14:15]
	v_mad_u64_u32 v[122:123], s[24:25], v140, s6, v[14:15]
	v_mad_u64_u32 v[124:125], s[24:25], v143, s6, v[14:15]
	v_mad_u64_u32 v[126:127], s[24:25], v142, s6, v[14:15]
	s_waitcnt vmcnt(31)
	ds_write_b32 v28, v68
	s_waitcnt vmcnt(30)
	ds_write_b32 v30, v69
	s_waitcnt vmcnt(29)
	ds_write_b32 v32, v70
	s_waitcnt vmcnt(28)
	ds_write_b32 v34, v71
	s_waitcnt vmcnt(27)
; #define LAS __attribute__((address_space(3)))
; __device__ __forceinline__ unsigned cvt_pk_bf16(float lo, float hi) { f32x2_c v = {lo, hi}; bf16x2_c r = __builtin_convertvector(v, bf16x2_c); return __builtin_bit_cast(unsigned, r); }
; #define LDS_WAIT() asm volatile("s_waitcnt lgkmcnt(0)" ::: "memory")
; __device__ __forceinline__ void transpose_item(const float* W, int N, bf16_t* WT, int dstK, size_t drow0, int kdst0, int k0, int n0, LAS float* scr, int lane) {
;     ...
;     for (int i = 0; i < 32; ++i) { const int kk = 2 * i + (lane >> 5); scr[kk * 33 + (lane & 31)] = W[(size_t)(k0 + kk) * N + n0 + (lane & 31)]; }
;     LDS_WAIT();
;     const int c = lane & 7;
; #pragma unroll
;     for (int j = 0; j < 4; ++j) { const int n = (lane >> 3) + 8 * j; const LAS float* s = scr + (8 * c) * 33 + n;
;         u32x4 o; o.x = cvt_pk_bf16(s[0 * 33], s[1 * 33]); o.y = cvt_pk_bf16(s[2 * 33], s[3 * 33]); o.z = cvt_pk_bf16(s[4 * 33], s[5 * 33]); o.w = cvt_pk_bf16(s[6 * 33], s[7 * 33]);
;         *(u32x4*)(WT + (drow0 + n) * dstK + kdst0 + k0 + 8 * c) = o; }
;     LDS_WAIT();
; }
; __device__ __forceinline__ void transpose_matrix(const float* W, int K, int N, bf16_t* WT, int dstK, int kdst0, int mode, LAS float* scr, int gw, int NGW, int lane) {
;     const int nblk = N / 32, items = (K / 64) * nblk;
;     for (int it = gw; it < items; it += NGW) {
;         const int kb = it / nblk, nb = it % nblk, n0 = nb * 32;
;         size_t drow0 = (size_t)n0;
;         if (mode == 1) { const int half = n0 >= DFF ? 1 : 0, nn = n0 - half * DFF; drow0 = (size_t)(nn >> 7) * 256 + half * 128 + (nn & 127); }
;         transpose_item(W, N, WT, dstK, drow0, kdst0, kb * 64, n0, scr, lane);
	ds_write_b32 v36, v72
	s_waitcnt vmcnt(26)
	ds_write_b32 v38, v73
	s_waitcnt vmcnt(25)
	ds_write_b32 v40, v74
	s_waitcnt vmcnt(24)
	ds_write_b32 v42, v75
	s_waitcnt vmcnt(23)
	ds_write_b32 v44, v76
	s_waitcnt vmcnt(22)
	ds_write_b32 v46, v77
	s_waitcnt vmcnt(21)
	ds_write_b32 v48, v78
	s_waitcnt vmcnt(20)
	ds_write_b32 v52, v79
	s_waitcnt vmcnt(19)
	ds_write_b32 v54, v80
	s_waitcnt vmcnt(18)
	ds_write_b32 v56, v81
	s_waitcnt vmcnt(17)
	ds_write_b32 v58, v82
	s_waitcnt vmcnt(16)
	ds_write_b32 v60, v83
	s_waitcnt vmcnt(15)
	ds_write_b32 v96, v144
	s_waitcnt vmcnt(14)
	ds_write_b32 v98, v145
	s_waitcnt vmcnt(13)
	ds_write_b32 v100, v146
	s_waitcnt vmcnt(12)
	ds_write_b32 v102, v147
	s_waitcnt vmcnt(11)
	ds_write_b32 v104, v148
	s_waitcnt vmcnt(10)
	ds_write_b32 v106, v149
	s_waitcnt vmcnt(9)
	ds_write_b32 v108, v150
	s_waitcnt vmcnt(8)
	ds_write_b32 v110, v151
	s_waitcnt vmcnt(7)
	ds_write_b32 v112, v152
	s_waitcnt vmcnt(6)
	ds_write_b32 v114, v153
	s_waitcnt vmcnt(5)
	ds_write_b32 v116, v154
	s_waitcnt vmcnt(4)
	ds_write_b32 v118, v155
	s_waitcnt vmcnt(3)
	ds_write_b32 v120, v156
	s_waitcnt vmcnt(2)
	ds_write_b32 v122, v157
	s_waitcnt vmcnt(1)
	ds_write_b32 v124, v158
	s_waitcnt vmcnt(0)
	ds_write_b32 v126, v159
	s_waitcnt lgkmcnt(0)
	ds_read2_b32 v[30:31], v3 offset0:33 offset1:41
	ds_read2_b32 v[32:33], v3 offset1:8
	ds_read2_b32 v[34:35], v3 offset0:66 offset1:74
	ds_read2_b32 v[36:37], v3 offset0:99 offset1:107
	ds_read2_b32 v[38:39], v3 offset0:132 offset1:140
	ds_read2_b32 v[40:41], v3 offset0:165 offset1:173
	ds_read2_b32 v[42:43], v3 offset0:198 offset1:206
	ds_read2_b32 v[44:45], v3 offset0:231 offset1:239
	s_ashr_i32 s21, s20, 31
	v_mov_b32_e32 v49, s3
	v_or_b32_e32 v48, s2, v16
	v_lshl_add_u64 v[46:47], s[20:21], 1, v[18:19]
	v_lshlrev_b64 v[48:49], 12, v[48:49]
	s_waitcnt lgkmcnt(6)
	v_cvt_pk_bf16_f32 v26, v32, v30
	s_waitcnt lgkmcnt(4)
	v_cvt_pk_bf16_f32 v27, v34, v36
	s_waitcnt lgkmcnt(2)
	v_cvt_pk_bf16_f32 v28, v38, v40
	s_waitcnt lgkmcnt(0)
	v_cvt_pk_bf16_f32 v29, v42, v44
	v_lshl_add_u64 v[48:49], v[46:47], 0, v[48:49]
	global_store_dwordx4 v[48:49], v[26:29], off
	v_or_b32_e32 v30, s2, v20
	s_add_i32 s7, s7, s36
	v_cvt_pk_bf16_f32 v26, v33, v31
	v_cvt_pk_bf16_f32 v27, v35, v37
	v_cvt_pk_bf16_f32 v28, v39, v41
	v_cvt_pk_bf16_f32 v29, v43, v45
	v_mov_b32_e32 v31, s3
	ds_read2_b32 v[32:33], v3 offset0:49 offset1:57
	ds_read2_b32 v[34:35], v3 offset0:16 offset1:24
	ds_read2_b32 v[36:37], v3 offset0:82 offset1:90
	ds_read2_b32 v[38:39], v3 offset0:115 offset1:123
	ds_read2_b32 v[40:41], v3 offset0:148 offset1:156
	ds_read2_b32 v[42:43], v3 offset0:181 offset1:189
	ds_read2_b32 v[44:45], v3 offset0:214 offset1:222
	ds_read2_b32 v[48:49], v3 offset0:247 offset1:255
	v_lshlrev_b64 v[30:31], 12, v[30:31]
	v_lshl_add_u64 v[30:31], v[46:47], 0, v[30:31]
	global_store_dwordx4 v[30:31], v[26:29], off
	v_mov_b32_e32 v31, s3
	v_or_b32_e32 v30, s2, v22
	v_lshlrev_b64 v[30:31], 12, v[30:31]
	s_waitcnt lgkmcnt(6)
	v_cvt_pk_bf16_f32 v26, v34, v32
	s_waitcnt lgkmcnt(4)
	v_cvt_pk_bf16_f32 v27, v36, v38
	s_waitcnt lgkmcnt(2)
	v_cvt_pk_bf16_f32 v28, v40, v42
	s_waitcnt lgkmcnt(0)
	v_cvt_pk_bf16_f32 v29, v44, v48
	v_lshl_add_u64 v[30:31], v[46:47], 0, v[30:31]
	global_store_dwordx4 v[30:31], v[26:29], off
	v_mov_b32_e32 v31, s3
	v_or_b32_e32 v30, s2, v24
	v_lshlrev_b64 v[30:31], 12, v[30:31]
	v_cvt_pk_bf16_f32 v26, v35, v33
	v_cvt_pk_bf16_f32 v27, v37, v39
	v_cvt_pk_bf16_f32 v28, v41, v43
	v_cvt_pk_bf16_f32 v29, v45, v49
	v_lshl_add_u64 v[30:31], v[46:47], 0, v[30:31]
	global_store_dwordx4 v[30:31], v[26:29], off
	s_waitcnt lgkmcnt(0)
	s_cmpk_lt_i32 s7, 0x1000
	s_cbranch_scc1 .LBB0_45
	v_readlane_b32 s48, v245, 24
	v_readlane_b32 s49, v245, 25
	v_readlane_b32 s56, v245, 32
	v_readlane_b32 s57, v245, 33
	v_readlane_b32 s60, v245, 36
	v_readlane_b32 s61, v245, 37
	v_readlane_b32 s50, v245, 26
	v_readlane_b32 s51, v245, 27
	v_readlane_b32 s52, v245, 28
	v_readlane_b32 s53, v245, 29
	v_readlane_b32 s54, v245, 30
	v_readlane_b32 s55, v245, 31
	v_readlane_b32 s58, v245, 34
	v_readlane_b32 s59, v245, 35
	v_readlane_b32 s62, v245, 38
	v_readlane_b32 s63, v245, 39
	v_cndmask_b32_e64 v1, 0, 1, s[18:19]
	v_cmp_ne_u32_e64 s[2:3], 1, v1
	s_andn2_b64 vcc, exec, s[18:19]
	s_cbranch_vccnz .LBB0_53

; __device__ __forceinline__ void transpose_item(const float* W, int N, bf16_t* WT, int dstK, size_t drow0, int kdst0, int k0, int n0, LAS float* scr, int lane) {
; #pragma unroll 8
;     for (int i = 0; i < 32; ++i) { const int kk = 2 * i + (lane >> 5); scr[kk * 33 + (lane & 31)] = W[(size_t)(k0 + kk) * N + n0 + (lane & 31)]; }
.LBB0_51:
	s_lshl_b32 s10, s9, 1
	s_lshl_b32 s11, s22, 1
	v_or_b32_e32 v5, s10, v1
	v_or_b32_e32 v7, s11, v10
	s_add_i32 s23, s10, 4
	s_add_i32 s24, s11, 4
	s_add_i32 s25, s10, 8
	s_add_i32 s27, s11, 8
	s_add_i32 s28, s10, 12
	s_add_i32 s29, s11, 12
	s_add_i32 s30, s10, 16
	s_add_i32 s31, s11, 16
	s_add_i32 s33, s10, 20
	s_add_i32 s34, s11, 20
	s_add_i32 s35, s10, 24
	s_add_i32 s37, s11, 24
	s_add_i32 s10, s10, 28
	s_add_i32 s11, s11, 28
	v_add_u32_e32 v30, s20, v7
	v_or_b32_e32 v9, s23, v1
	v_or_b32_e32 v11, s24, v10
	v_or_b32_e32 v15, s25, v1
	v_or_b32_e32 v17, s27, v10
	v_or_b32_e32 v21, s28, v1
	v_or_b32_e32 v23, s29, v10
	v_or_b32_e32 v25, s30, v1
	v_or_b32_e32 v51, s31, v10
	v_or_b32_e32 v62, s33, v1
	v_or_b32_e32 v63, s34, v10
	v_or_b32_e32 v64, s35, v1
	v_or_b32_e32 v65, s37, v10
	v_or_b32_e32 v66, s10, v1
	v_or_b32_e32 v67, s11, v10
	v_add_u32_e32 v28, s8, v5
	v_ashrrev_i32_e32 v31, 31, v30
	v_add_u32_e32 v32, s8, v9
	v_add_u32_e32 v34, s20, v11
	v_add_u32_e32 v36, s8, v15
	v_add_u32_e32 v38, s20, v17
	v_add_u32_e32 v40, s8, v21
	v_add_u32_e32 v42, s20, v23
	v_add_u32_e32 v44, s8, v25
	v_add_u32_e32 v46, s20, v51
	v_add_u32_e32 v48, s8, v62
	v_add_u32_e32 v52, s20, v63
	v_add_u32_e32 v54, s8, v64
	v_add_u32_e32 v56, s20, v65
	v_add_u32_e32 v58, s8, v66
	v_add_u32_e32 v60, s20, v67
	v_ashrrev_i32_e32 v29, 31, v28
	v_lshlrev_b64 v[30:31], 13, v[30:31]
	v_ashrrev_i32_e32 v35, 31, v34
	v_ashrrev_i32_e32 v33, 31, v32
	v_ashrrev_i32_e32 v39, 31, v38
	v_ashrrev_i32_e32 v37, 31, v36
	v_ashrrev_i32_e32 v43, 31, v42
	v_ashrrev_i32_e32 v41, 31, v40
	v_ashrrev_i32_e32 v47, 31, v46
	v_ashrrev_i32_e32 v45, 31, v44
	v_ashrrev_i32_e32 v53, 31, v52
	v_ashrrev_i32_e32 v49, 31, v48
	v_ashrrev_i32_e32 v57, 31, v56
	v_ashrrev_i32_e32 v55, 31, v54
	v_ashrrev_i32_e32 v61, 31, v60
	v_ashrrev_i32_e32 v59, 31, v58
	v_lshlrev_b64 v[28:29], 13, v[28:29]
	v_lshl_add_u64 v[30:31], v[26:27], 0, v[30:31]
	v_lshlrev_b64 v[32:33], 13, v[32:33]
	v_lshlrev_b64 v[34:35], 13, v[34:35]
	v_lshlrev_b64 v[36:37], 13, v[36:37]
	v_lshlrev_b64 v[38:39], 13, v[38:39]
	v_lshlrev_b64 v[40:41], 13, v[40:41]
	v_lshlrev_b64 v[42:43], 13, v[42:43]
	v_lshlrev_b64 v[44:45], 13, v[44:45]
	v_lshlrev_b64 v[46:47], 13, v[46:47]
	v_lshlrev_b64 v[48:49], 13, v[48:49]
	v_lshlrev_b64 v[52:53], 13, v[52:53]
	v_lshlrev_b64 v[54:55], 13, v[54:55]
	v_lshlrev_b64 v[56:57], 13, v[56:57]
	v_lshlrev_b64 v[58:59], 13, v[58:59]
	v_lshlrev_b64 v[60:61], 13, v[60:61]
	v_lshl_add_u64 v[28:29], v[26:27], 0, v[28:29]
	v_lshl_add_u64 v[34:35], v[26:27], 0, v[34:35]
	v_lshl_add_u64 v[32:33], v[26:27], 0, v[32:33]
	v_lshl_add_u64 v[38:39], v[26:27], 0, v[38:39]
	v_lshl_add_u64 v[36:37], v[26:27], 0, v[36:37]
	v_lshl_add_u64 v[42:43], v[26:27], 0, v[42:43]
	v_lshl_add_u64 v[40:41], v[26:27], 0, v[40:41]
	v_lshl_add_u64 v[46:47], v[26:27], 0, v[46:47]
	v_lshl_add_u64 v[44:45], v[26:27], 0, v[44:45]
	v_lshl_add_u64 v[52:53], v[26:27], 0, v[52:53]
	v_lshl_add_u64 v[48:49], v[26:27], 0, v[48:49]
	v_lshl_add_u64 v[56:57], v[26:27], 0, v[56:57]
	v_lshl_add_u64 v[54:55], v[26:27], 0, v[54:55]
	v_lshl_add_u64 v[60:61], v[26:27], 0, v[60:61]
	v_lshl_add_u64 v[58:59], v[26:27], 0, v[58:59]
	global_load_dword v68, v[30:31], off
	global_load_dword v69, v[28:29], off
	global_load_dword v70, v[34:35], off
	global_load_dword v71, v[32:33], off
	global_load_dword v72, v[38:39], off
	global_load_dword v73, v[36:37], off
	global_load_dword v74, v[42:43], off
	global_load_dword v75, v[40:41], off
	global_load_dword v76, v[46:47], off
	global_load_dword v77, v[44:45], off
	global_load_dword v78, v[52:53], off
	global_load_dword v79, v[48:49], off
	global_load_dword v80, v[56:57], off
	global_load_dword v81, v[54:55], off
	global_load_dword v82, v[60:61], off
	global_load_dword v83, v[58:59], off
	s_add_i32 s22, s22, 16
	s_add_i32 s9, s9, 16
	s_add_i32 s21, s21, -16
	v_mad_u64_u32 v[28:29], s[24:25], v7, s6, v[14:15]
	s_cmp_lg_u32 s21, 0
	v_mad_u64_u32 v[30:31], s[24:25], v5, s6, v[14:15]
	v_mad_u64_u32 v[32:33], s[24:25], v11, s6, v[14:15]
	v_mad_u64_u32 v[34:35], s[24:25], v9, s6, v[14:15]
	v_mad_u64_u32 v[36:37], s[24:25], v17, s6, v[14:15]
	v_mad_u64_u32 v[38:39], s[24:25], v15, s6, v[14:15]
	v_mad_u64_u32 v[40:41], s[24:25], v23, s6, v[14:15]
	v_mad_u64_u32 v[42:43], s[24:25], v21, s6, v[14:15]
	v_mad_u64_u32 v[44:45], s[24:25], v51, s6, v[14:15]
	v_mad_u64_u32 v[46:47], s[24:25], v25, s6, v[14:15]
	v_mad_u64_u32 v[48:49], s[24:25], v63, s6, v[14:15]
	v_mad_u64_u32 v[52:53], s[24:25], v62, s6, v[14:15]
	v_mad_u64_u32 v[54:55], s[24:25], v65, s6, v[14:15]
	v_mad_u64_u32 v[56:57], s[24:25], v64, s6, v[14:15]
	v_mad_u64_u32 v[58:59], s[24:25], v67, s6, v[14:15]
	v_mad_u64_u32 v[60:61], s[24:25], v66, s6, v[14:15]
	s_lshl_b32 s10, s9, 1
	s_lshl_b32 s11, s22, 1
	v_or_b32_e32 v128, s10, v1
	v_or_b32_e32 v129, s11, v10
	s_add_i32 s23, s10, 4
	s_add_i32 s24, s11, 4
	s_add_i32 s25, s10, 8
	s_add_i32 s27, s11, 8
	s_add_i32 s28, s10, 12
	s_add_i32 s29, s11, 12
	s_add_i32 s30, s10, 16
	s_add_i32 s31, s11, 16
	s_add_i32 s33, s10, 20
	s_add_i32 s34, s11, 20
	s_add_i32 s35, s10, 24
	s_add_i32 s37, s11, 24
	s_add_i32 s10, s10, 28
	s_add_i32 s11, s11, 28
	v_add_u32_e32 v98, s20, v129
	v_or_b32_e32 v130, s23, v1
	v_or_b32_e32 v131, s24, v10
	v_or_b32_e32 v132, s25, v1
	v_or_b32_e32 v133, s27, v10
	v_or_b32_e32 v134, s28, v1
	v_or_b32_e32 v135, s29, v10
	v_or_b32_e32 v136, s30, v1
	v_or_b32_e32 v137, s31, v10
	v_or_b32_e32 v138, s33, v1
	v_or_b32_e32 v139, s34, v10
	v_or_b32_e32 v140, s35, v1
	v_or_b32_e32 v141, s37, v10
	v_or_b32_e32 v142, s10, v1
	v_or_b32_e32 v143, s11, v10
	v_add_u32_e32 v96, s8, v128
	v_ashrrev_i32_e32 v99, 31, v98
; __device__ __forceinline__ void transpose_item(const float* W, int N, bf16_t* WT, int dstK, size_t drow0, int kdst0, int k0, int n0, LAS float* scr, int lane) {
; #pragma unroll 8
;     for (int i = 0; i < 32; ++i) { const int kk = 2 * i + (lane >> 5); scr[kk * 33 + (lane & 31)] = W[(size_t)(k0 + kk) * N + n0 + (lane & 31)]; }
	v_add_u32_e32 v100, s8, v130
	v_add_u32_e32 v102, s20, v131
	v_add_u32_e32 v104, s8, v132
	v_add_u32_e32 v106, s20, v133
	v_add_u32_e32 v108, s8, v134
	v_add_u32_e32 v110, s20, v135
	v_add_u32_e32 v112, s8, v136
	v_add_u32_e32 v114, s20, v137
	v_add_u32_e32 v116, s8, v138
	v_add_u32_e32 v118, s20, v139
	v_add_u32_e32 v120, s8, v140
	v_add_u32_e32 v122, s20, v141
	v_add_u32_e32 v124, s8, v142
	v_add_u32_e32 v126, s20, v143
	v_ashrrev_i32_e32 v97, 31, v96
	v_lshlrev_b64 v[98:99], 13, v[98:99]
	v_ashrrev_i32_e32 v103, 31, v102
	v_ashrrev_i32_e32 v101, 31, v100
	v_ashrrev_i32_e32 v107, 31, v106
	v_ashrrev_i32_e32 v105, 31, v104
	v_ashrrev_i32_e32 v111, 31, v110
	v_ashrrev_i32_e32 v109, 31, v108
	v_ashrrev_i32_e32 v115, 31, v114
	v_ashrrev_i32_e32 v113, 31, v112
	v_ashrrev_i32_e32 v119, 31, v118
	v_ashrrev_i32_e32 v117, 31, v116
	v_ashrrev_i32_e32 v123, 31, v122
	v_ashrrev_i32_e32 v121, 31, v120
	v_ashrrev_i32_e32 v127, 31, v126
	v_ashrrev_i32_e32 v125, 31, v124
	v_lshlrev_b64 v[96:97], 13, v[96:97]
	v_lshl_add_u64 v[98:99], v[26:27], 0, v[98:99]
	v_lshlrev_b64 v[100:101], 13, v[100:101]
	v_lshlrev_b64 v[102:103], 13, v[102:103]
	v_lshlrev_b64 v[104:105], 13, v[104:105]
	v_lshlrev_b64 v[106:107], 13, v[106:107]
	v_lshlrev_b64 v[108:109], 13, v[108:109]
	v_lshlrev_b64 v[110:111], 13, v[110:111]
	v_lshlrev_b64 v[112:113], 13, v[112:113]
	v_lshlrev_b64 v[114:115], 13, v[114:115]
	v_lshlrev_b64 v[116:117], 13, v[116:117]
	v_lshlrev_b64 v[118:119], 13, v[118:119]
	v_lshlrev_b64 v[120:121], 13, v[120:121]
	v_lshlrev_b64 v[122:123], 13, v[122:123]
	v_lshlrev_b64 v[124:125], 13, v[124:125]
	v_lshlrev_b64 v[126:127], 13, v[126:127]
	v_lshl_add_u64 v[96:97], v[26:27], 0, v[96:97]
	v_lshl_add_u64 v[102:103], v[26:27], 0, v[102:103]
	v_lshl_add_u64 v[100:101], v[26:27], 0, v[100:101]
	v_lshl_add_u64 v[106:107], v[26:27], 0, v[106:107]
	v_lshl_add_u64 v[104:105], v[26:27], 0, v[104:105]
	v_lshl_add_u64 v[110:111], v[26:27], 0, v[110:111]
	v_lshl_add_u64 v[108:109], v[26:27], 0, v[108:109]
	v_lshl_add_u64 v[114:115], v[26:27], 0, v[114:115]
	v_lshl_add_u64 v[112:113], v[26:27], 0, v[112:113]
	v_lshl_add_u64 v[118:119], v[26:27], 0, v[118:119]
	v_lshl_add_u64 v[116:117], v[26:27], 0, v[116:117]
	v_lshl_add_u64 v[122:123], v[26:27], 0, v[122:123]
	v_lshl_add_u64 v[120:121], v[26:27], 0, v[120:121]
	v_lshl_add_u64 v[126:127], v[26:27], 0, v[126:127]
	v_lshl_add_u64 v[124:125], v[26:27], 0, v[124:125]
	global_load_dword v144, v[98:99], off
	global_load_dword v145, v[96:97], off
	global_load_dword v146, v[102:103], off
	global_load_dword v147, v[100:101], off
	global_load_dword v148, v[106:107], off
	global_load_dword v149, v[104:105], off
	global_load_dword v150, v[110:111], off
	global_load_dword v151, v[108:109], off
	global_load_dword v152, v[114:115], off
	global_load_dword v153, v[112:113], off
	global_load_dword v154, v[118:119], off
	global_load_dword v155, v[116:117], off
	global_load_dword v156, v[122:123], off
	global_load_dword v157, v[120:121], off
	global_load_dword v158, v[126:127], off
	global_load_dword v159, v[124:125], off
	s_add_i32 s22, s22, 16
	s_add_i32 s9, s9, 16
	s_add_i32 s21, s21, -16
	v_mad_u64_u32 v[96:97], s[24:25], v129, s6, v[14:15]
	s_cmp_lg_u32 s21, 0
	v_mad_u64_u32 v[98:99], s[24:25], v128, s6, v[14:15]
	v_mad_u64_u32 v[100:101], s[24:25], v131, s6, v[14:15]
	v_mad_u64_u32 v[102:103], s[24:25], v130, s6, v[14:15]
	v_mad_u64_u32 v[104:105], s[24:25], v133, s6, v[14:15]
	v_mad_u64_u32 v[106:107], s[24:25], v132, s6, v[14:15]
	v_mad_u64_u32 v[108:109], s[24:25], v135, s6, v[14:15]
	v_mad_u64_u32 v[110:111], s[24:25], v134, s6, v[14:15]
	v_mad_u64_u32 v[112:113], s[24:25], v137, s6, v[14:15]
	v_mad_u64_u32 v[114:115], s[24:25], v136, s6, v[14:15]
	v_mad_u64_u32 v[116:117], s[24:25], v139, s6, v[14:15]
	v_mad_u64_u32 v[118:119], s[24:25], v138, s6, v[14:15]
	v_mad_u64_u32 v[120:121], s[24:25], v141, s6, v[14:15]
	v_mad_u64_u32 v[122:123], s[24:25], v140, s6, v[14:15]
	v_mad_u64_u32 v[124:125], s[24:25], v143, s6, v[14:15]
	v_mad_u64_u32 v[126:127], s[24:25], v142, s6, v[14:15]
	s_waitcnt vmcnt(31)
; #define LAS __attribute__((address_space(3)))
; __device__ __forceinline__ unsigned cvt_pk_bf16(float lo, float hi) { f32x2_c v = {lo, hi}; bf16x2_c r = __builtin_convertvector(v, bf16x2_c); return __builtin_bit_cast(unsigned, r); }
; #define LDS_WAIT() asm volatile("s_waitcnt lgkmcnt(0)" ::: "memory")
; __device__ __forceinline__ void transpose_item(const float* W, int N, bf16_t* WT, int dstK, size_t drow0, int kdst0, int k0, int n0, LAS float* scr, int lane) {
;     ...
;     for (int i = 0; i < 32; ++i) { const int kk = 2 * i + (lane >> 5); scr[kk * 33 + (lane & 31)] = W[(size_t)(k0 + kk) * N + n0 + (lane & 31)]; }
;     LDS_WAIT();
;     const int c = lane & 7;
; #pragma unroll
;     for (int j = 0; j < 4; ++j) { const int n = (lane >> 3) + 8 * j; const LAS float* s = scr + (8 * c) * 33 + n;
;         u32x4 o; o.x = cvt_pk_bf16(s[0 * 33], s[1 * 33]); o.y = cvt_pk_bf16(s[2 * 33], s[3 * 33]); o.z = cvt_pk_bf16(s[4 * 33], s[5 * 33]); o.w = cvt_pk_bf16(s[6 * 33], s[7 * 33]);
;         *(u32x4*)(WT + (drow0 + n) * dstK + kdst0 + k0 + 8 * c) = o; }
;     LDS_WAIT();
; }
; __device__ __forceinline__ void transpose_matrix(const float* W, int K, int N, bf16_t* WT, int dstK, int kdst0, int mode, LAS float* scr, int gw, int NGW, int lane) {
;     const int nblk = N / 32, items = (K / 64) * nblk;
;     for (int it = gw; it < items; it += NGW) {
;         const int kb = it / nblk, nb = it % nblk, n0 = nb * 32;
;         size_t drow0 = (size_t)n0;
;         if (mode == 1) { const int half = n0 >= DFF ? 1 : 0, nn = n0 - half * DFF; drow0 = (size_t)(nn >> 7) * 256 + half * 128 + (nn & 127); }
;         transpose_item(W, N, WT, dstK, drow0, kdst0, kb * 64, n0, scr, lane);
;     }
	ds_write_b32 v28, v68
	s_waitcnt vmcnt(30)
	ds_write_b32 v30, v69
	s_waitcnt vmcnt(29)
	ds_write_b32 v32, v70
	s_waitcnt vmcnt(28)
	ds_write_b32 v34, v71
	s_waitcnt vmcnt(27)
	ds_write_b32 v36, v72
	s_waitcnt vmcnt(26)
	ds_write_b32 v38, v73
	s_waitcnt vmcnt(25)
	ds_write_b32 v40, v74
	s_waitcnt vmcnt(24)
	ds_write_b32 v42, v75
	s_waitcnt vmcnt(23)
	ds_write_b32 v44, v76
	s_waitcnt vmcnt(22)
	ds_write_b32 v46, v77
	s_waitcnt vmcnt(21)
	ds_write_b32 v48, v78
	s_waitcnt vmcnt(20)
	ds_write_b32 v52, v79
	s_waitcnt vmcnt(19)
	ds_write_b32 v54, v80
	s_waitcnt vmcnt(18)
	ds_write_b32 v56, v81
	s_waitcnt vmcnt(17)
	ds_write_b32 v58, v82
	s_waitcnt vmcnt(16)
	ds_write_b32 v60, v83
	s_waitcnt vmcnt(15)
	ds_write_b32 v96, v144
	s_waitcnt vmcnt(14)
	ds_write_b32 v98, v145
	s_waitcnt vmcnt(13)
	ds_write_b32 v100, v146
	s_waitcnt vmcnt(12)
	ds_write_b32 v102, v147
	s_waitcnt vmcnt(11)
	ds_write_b32 v104, v148
	s_waitcnt vmcnt(10)
	ds_write_b32 v106, v149
	s_waitcnt vmcnt(9)
	ds_write_b32 v108, v150
	s_waitcnt vmcnt(8)
	ds_write_b32 v110, v151
	s_waitcnt vmcnt(7)
	ds_write_b32 v112, v152
	s_waitcnt vmcnt(6)
	ds_write_b32 v114, v153
	s_waitcnt vmcnt(5)
	ds_write_b32 v116, v154
	s_waitcnt vmcnt(4)
	ds_write_b32 v118, v155
	s_waitcnt vmcnt(3)
	ds_write_b32 v120, v156
	s_waitcnt vmcnt(2)
	ds_write_b32 v122, v157
	s_waitcnt vmcnt(1)
	ds_write_b32 v124, v158
	s_waitcnt vmcnt(0)
	ds_write_b32 v126, v159
	s_waitcnt lgkmcnt(0)
	ds_read2_b32 v[30:31], v3 offset0:33 offset1:41
	ds_read2_b32 v[32:33], v3 offset1:8
	ds_read2_b32 v[34:35], v3 offset0:66 offset1:74
	ds_read2_b32 v[36:37], v3 offset0:99 offset1:107
	ds_read2_b32 v[38:39], v3 offset0:132 offset1:140
	ds_read2_b32 v[40:41], v3 offset0:165 offset1:173
	ds_read2_b32 v[42:43], v3 offset0:198 offset1:206
	ds_read2_b32 v[44:45], v3 offset0:231 offset1:239
	s_ashr_i32 s21, s20, 31
	v_mov_b32_e32 v49, s19
	v_or_b32_e32 v48, s18, v16
	v_lshl_add_u64 v[46:47], s[20:21], 1, v[18:19]
	v_lshlrev_b64 v[48:49], 12, v[48:49]
	s_waitcnt lgkmcnt(6)
	v_cvt_pk_bf16_f32 v26, v32, v30
	s_waitcnt lgkmcnt(4)
	v_cvt_pk_bf16_f32 v27, v34, v36
	s_waitcnt lgkmcnt(2)
	v_cvt_pk_bf16_f32 v28, v38, v40
	s_waitcnt lgkmcnt(0)
	v_cvt_pk_bf16_f32 v29, v42, v44
	v_lshl_add_u64 v[48:49], v[46:47], 0, v[48:49]
	global_store_dwordx4 v[48:49], v[26:29], off
	v_or_b32_e32 v30, s18, v20
	s_add_i32 s7, s7, s36
	v_cvt_pk_bf16_f32 v26, v33, v31
	v_cvt_pk_bf16_f32 v27, v35, v37
	v_cvt_pk_bf16_f32 v28, v39, v41
	v_cvt_pk_bf16_f32 v29, v43, v45
	v_mov_b32_e32 v31, s19
	ds_read2_b32 v[32:33], v3 offset0:49 offset1:57
	ds_read2_b32 v[34:35], v3 offset0:16 offset1:24
	ds_read2_b32 v[36:37], v3 offset0:82 offset1:90
	ds_read2_b32 v[38:39], v3 offset0:115 offset1:123
	ds_read2_b32 v[40:41], v3 offset0:148 offset1:156
	ds_read2_b32 v[42:43], v3 offset0:181 offset1:189
	ds_read2_b32 v[44:45], v3 offset0:214 offset1:222
	ds_read2_b32 v[48:49], v3 offset0:247 offset1:255
	v_lshlrev_b64 v[30:31], 12, v[30:31]
	v_lshl_add_u64 v[30:31], v[46:47], 0, v[30:31]
	global_store_dwordx4 v[30:31], v[26:29], off
	v_mov_b32_e32 v31, s19
	v_or_b32_e32 v30, s18, v22
	v_lshlrev_b64 v[30:31], 12, v[30:31]
	s_waitcnt lgkmcnt(6)
	v_cvt_pk_bf16_f32 v26, v34, v32
	s_waitcnt lgkmcnt(4)
	v_cvt_pk_bf16_f32 v27, v36, v38
	s_waitcnt lgkmcnt(2)
	v_cvt_pk_bf16_f32 v28, v40, v42
	s_waitcnt lgkmcnt(0)
	v_cvt_pk_bf16_f32 v29, v44, v48
	v_lshl_add_u64 v[30:31], v[46:47], 0, v[30:31]
	global_store_dwordx4 v[30:31], v[26:29], off
	v_mov_b32_e32 v31, s19
	v_or_b32_e32 v30, s18, v24
	v_lshlrev_b64 v[30:31], 12, v[30:31]
	v_cvt_pk_bf16_f32 v26, v35, v33
	v_cvt_pk_bf16_f32 v27, v37, v39
	v_cvt_pk_bf16_f32 v28, v41, v43
	v_cvt_pk_bf16_f32 v29, v45, v49
	v_lshl_add_u64 v[30:31], v[46:47], 0, v[30:31]
	global_store_dwordx4 v[30:31], v[26:29], off
	s_waitcnt lgkmcnt(0)
	s_cmpk_lt_i32 s7, 0x800
	s_cbranch_scc1 .LBB0_50

; __device__ __forceinline__ void transpose_item(const float* W, int N, bf16_t* WT, int dstK, size_t drow0, int kdst0, int k0, int n0, LAS float* scr, int lane) {
; #pragma unroll 8
;     for (int i = 0; i < 32; ++i) { const int kk = 2 * i + (lane >> 5); scr[kk * 33 + (lane & 31)] = W[(size_t)(k0 + kk) * N + n0 + (lane & 31)]; }
; __device__ __forceinline__ void transpose_matrix(const float* W, int K, int N, bf16_t* WT, int dstK, int kdst0, int mode, LAS float* scr, int gw, int NGW, int lane) {
;     ...
;         if (mode == 1) { const int half = n0 >= DFF ? 1 : 0, nn = n0 - half * DFF; drow0 = (size_t)(nn >> 7) * 256 + half * 128 + (nn & 127); }
.LBB0_60:
	s_lshl_b32 s10, s19, 1
	s_lshl_b32 s11, s22, 1
	v_or_b32_e32 v5, s10, v1
	v_or_b32_e32 v7, s11, v4
	s_add_i32 s23, s10, 4
	s_add_i32 s24, s11, 4
	s_add_i32 s25, s10, 8
	s_add_i32 s27, s11, 8
	s_add_i32 s28, s10, 12
	s_add_i32 s29, s11, 12
	s_add_i32 s30, s10, 16
	s_add_i32 s31, s11, 16
	s_add_i32 s33, s10, 20
	s_add_i32 s34, s11, 20
	s_add_i32 s35, s10, 24
	s_add_i32 s37, s11, 24
	s_add_i32 s10, s10, 28
	s_add_i32 s11, s11, 28
	v_add_u32_e32 v9, s9, v5
	v_add_u32_e32 v13, s18, v7
	v_or_b32_e32 v15, s23, v1
	v_or_b32_e32 v21, s24, v4
	v_or_b32_e32 v23, s25, v1
	v_or_b32_e32 v25, s27, v4
	v_or_b32_e32 v51, s28, v1
	v_or_b32_e32 v62, s29, v4
	v_or_b32_e32 v63, s30, v1
	v_or_b32_e32 v64, s31, v4
	v_or_b32_e32 v65, s33, v1
	v_or_b32_e32 v66, s34, v4
	v_or_b32_e32 v67, s35, v1
	v_or_b32_e32 v68, s37, v4
	v_or_b32_e32 v69, s10, v1
	v_or_b32_e32 v70, s11, v4
	v_mad_i64_i32 v[28:29], s[24:25], v13, s7, v[26:27]
	v_mad_i64_i32 v[30:31], s[24:25], v9, s7, v[26:27]
	v_add_u32_e32 v9, s9, v15
	v_add_u32_e32 v13, s18, v21
	v_add_u32_e32 v38, s9, v23
	v_add_u32_e32 v36, s18, v25
	v_add_u32_e32 v42, s9, v51
	v_add_u32_e32 v40, s18, v62
	v_add_u32_e32 v46, s9, v63
	v_add_u32_e32 v44, s18, v64
	v_add_u32_e32 v52, s9, v65
	v_add_u32_e32 v48, s18, v66
	v_add_u32_e32 v56, s9, v67
	v_add_u32_e32 v54, s18, v68
	v_add_u32_e32 v60, s9, v69
	v_add_u32_e32 v58, s18, v70
	v_mad_i64_i32 v[32:33], s[24:25], v13, s7, v[26:27]
	v_mad_i64_i32 v[34:35], s[24:25], v9, s7, v[26:27]
	v_mad_i64_i32 v[36:37], s[24:25], v36, s7, v[26:27]
	v_mad_i64_i32 v[38:39], s[24:25], v38, s7, v[26:27]
	v_mad_i64_i32 v[40:41], s[24:25], v40, s7, v[26:27]
	v_mad_i64_i32 v[42:43], s[24:25], v42, s7, v[26:27]
	v_mad_i64_i32 v[44:45], s[24:25], v44, s7, v[26:27]
	v_mad_i64_i32 v[46:47], s[24:25], v46, s7, v[26:27]
	v_mad_i64_i32 v[48:49], s[24:25], v48, s7, v[26:27]
	v_mad_i64_i32 v[52:53], s[24:25], v52, s7, v[26:27]
	v_mad_i64_i32 v[54:55], s[24:25], v54, s7, v[26:27]
	v_mad_i64_i32 v[56:57], s[24:25], v56, s7, v[26:27]
	v_mad_i64_i32 v[58:59], s[24:25], v58, s7, v[26:27]
	v_mad_i64_i32 v[60:61], s[24:25], v60, s7, v[26:27]
	global_load_dword v9, v[28:29], off
	global_load_dword v13, v[30:31], off
	global_load_dword v71, v[32:33], off
	global_load_dword v72, v[34:35], off
	global_load_dword v73, v[36:37], off
	global_load_dword v74, v[38:39], off
	global_load_dword v75, v[40:41], off
	global_load_dword v76, v[42:43], off
	global_load_dword v77, v[44:45], off
	global_load_dword v78, v[46:47], off
	global_load_dword v79, v[48:49], off
	global_load_dword v80, v[52:53], off
	global_load_dword v81, v[54:55], off
	global_load_dword v82, v[56:57], off
	global_load_dword v83, v[58:59], off
	global_load_dword v84, v[60:61], off
	s_add_i32 s22, s22, 16
	s_add_i32 s19, s19, 16
	s_add_i32 s21, s21, -16
	s_cmp_lg_u32 s21, 0
	s_lshl_b32 s10, s19, 1
	s_lshl_b32 s11, s22, 1
	v_or_b32_e32 v128, s10, v1
	v_or_b32_e32 v129, s11, v4
	s_add_i32 s23, s10, 4
	s_add_i32 s24, s11, 4
	s_add_i32 s25, s10, 8
	s_add_i32 s27, s11, 8
	s_add_i32 s28, s10, 12
	s_add_i32 s29, s11, 12
	s_add_i32 s30, s10, 16
	s_add_i32 s31, s11, 16
	s_add_i32 s33, s10, 20
	s_add_i32 s34, s11, 20
	s_add_i32 s35, s10, 24
	s_add_i32 s37, s11, 24
	s_add_i32 s10, s10, 28
	s_add_i32 s11, s11, 28
	v_add_u32_e32 v130, s9, v128
	v_add_u32_e32 v131, s18, v129
	v_or_b32_e32 v132, s23, v1
	v_or_b32_e32 v133, s24, v4
	v_or_b32_e32 v134, s25, v1
	v_or_b32_e32 v135, s27, v4
	v_or_b32_e32 v136, s28, v1
	v_or_b32_e32 v137, s29, v4
	v_or_b32_e32 v138, s30, v1
	v_or_b32_e32 v139, s31, v4
	v_or_b32_e32 v140, s33, v1
	v_or_b32_e32 v141, s34, v4
	v_or_b32_e32 v142, s35, v1
	v_or_b32_e32 v143, s37, v4
	v_or_b32_e32 v144, s10, v1
	v_or_b32_e32 v145, s11, v4
	v_mad_i64_i32 v[96:97], s[24:25], v131, s7, v[26:27]
	v_mad_i64_i32 v[98:99], s[24:25], v130, s7, v[26:27]
	v_add_u32_e32 v130, s9, v132
	v_add_u32_e32 v131, s18, v133
	v_add_u32_e32 v106, s9, v134
	v_add_u32_e32 v104, s18, v135
	v_add_u32_e32 v110, s9, v136
	v_add_u32_e32 v108, s18, v137
	v_add_u32_e32 v114, s9, v138
	v_add_u32_e32 v112, s18, v139
	v_add_u32_e32 v118, s9, v140
	v_add_u32_e32 v116, s18, v141
	v_add_u32_e32 v122, s9, v142
	v_add_u32_e32 v120, s18, v143
	v_add_u32_e32 v126, s9, v144
	v_add_u32_e32 v124, s18, v145
	v_mad_i64_i32 v[100:101], s[24:25], v131, s7, v[26:27]
	v_mad_i64_i32 v[102:103], s[24:25], v130, s7, v[26:27]
	v_mad_i64_i32 v[104:105], s[24:25], v104, s7, v[26:27]
	v_mad_i64_i32 v[106:107], s[24:25], v106, s7, v[26:27]
	v_mad_i64_i32 v[108:109], s[24:25], v108, s7, v[26:27]
	v_mad_i64_i32 v[110:111], s[24:25], v110, s7, v[26:27]
	v_mad_i64_i32 v[112:113], s[24:25], v112, s7, v[26:27]
	v_mad_i64_i32 v[114:115], s[24:25], v114, s7, v[26:27]
	v_mad_i64_i32 v[116:117], s[24:25], v116, s7, v[26:27]
	v_mad_i64_i32 v[118:119], s[24:25], v118, s7, v[26:27]
	v_mad_i64_i32 v[120:121], s[24:25], v120, s7, v[26:27]
	v_mad_i64_i32 v[122:123], s[24:25], v122, s7, v[26:27]
	v_mad_i64_i32 v[124:125], s[24:25], v124, s7, v[26:27]
	v_mad_i64_i32 v[126:127], s[24:25], v126, s7, v[26:27]
	global_load_dword v130, v[96:97], off
	global_load_dword v131, v[98:99], off
	global_load_dword v146, v[100:101], off
	global_load_dword v147, v[102:103], off
	global_load_dword v148, v[104:105], off
	global_load_dword v149, v[106:107], off
	global_load_dword v150, v[108:109], off
	global_load_dword v151, v[110:111], off
	global_load_dword v152, v[112:113], off
	global_load_dword v153, v[114:115], off
	global_load_dword v154, v[116:117], off
	global_load_dword v155, v[118:119], off
	global_load_dword v156, v[120:121], off
	global_load_dword v157, v[122:123], off
	global_load_dword v158, v[124:125], off
	global_load_dword v159, v[126:127], off
	s_add_i32 s22, s22, 16
	s_add_i32 s19, s19, 16
	s_add_i32 s21, s21, -16
	s_cmp_lg_u32 s21, 0
	s_waitcnt vmcnt(30)
; #define LAS __attribute__((address_space(3)))
; __device__ __forceinline__ unsigned cvt_pk_bf16(float lo, float hi) { f32x2_c v = {lo, hi}; bf16x2_c r = __builtin_convertvector(v, bf16x2_c); return __builtin_bit_cast(unsigned, r); }
; #define LDS_WAIT() asm volatile("s_waitcnt lgkmcnt(0)" ::: "memory")
; __device__ __forceinline__ void transpose_item(const float* W, int N, bf16_t* WT, int dstK, size_t drow0, int kdst0, int k0, int n0, LAS float* scr, int lane) {
;     ...
;     for (int i = 0; i < 32; ++i) { const int kk = 2 * i + (lane >> 5); scr[kk * 33 + (lane & 31)] = W[(size_t)(k0 + kk) * N + n0 + (lane & 31)]; }
;     LDS_WAIT();
;     const int c = lane & 7;
; #pragma unroll
;     for (int j = 0; j < 4; ++j) { const int n = (lane >> 3) + 8 * j; const LAS float* s = scr + (8 * c) * 33 + n;
;         u32x4 o; o.x = cvt_pk_bf16(s[0 * 33], s[1 * 33]); o.y = cvt_pk_bf16(s[2 * 33], s[3 * 33]); o.z = cvt_pk_bf16(s[4 * 33], s[5 * 33]); o.w = cvt_pk_bf16(s[6 * 33], s[7 * 33]);
;         *(u32x4*)(WT + (drow0 + n) * dstK + kdst0 + k0 + 8 * c) = o; }
;     LDS_WAIT();
; }
; __device__ __forceinline__ void transpose_matrix(const float* W, int K, int N, bf16_t* WT, int dstK, int kdst0, int mode, LAS float* scr, int gw, int NGW, int lane) {
;     const int nblk = N / 32, items = (K / 64) * nblk;
;     for (int it = gw; it < items; it += NGW) {
;         const int kb = it / nblk, nb = it % nblk, n0 = nb * 32;
;         size_t drow0 = (size_t)n0;
;         if (mode == 1) { const int half = n0 >= DFF ? 1 : 0, nn = n0 - half * DFF; drow0 = (size_t)(nn >> 7) * 256 + half * 128 + (nn & 127); }
;         transpose_item(W, N, WT, dstK, drow0, kdst0, kb * 64, n0, scr, lane);
;     }
	v_mad_u64_u32 v[28:29], s[24:25], v7, s6, v[12:13]
	v_mad_u64_u32 v[30:31], s[24:25], v5, s6, v[12:13]
	v_mad_u64_u32 v[32:33], s[24:25], v21, s6, v[12:13]
	v_mad_u64_u32 v[34:35], s[24:25], v15, s6, v[12:13]
	v_mad_u64_u32 v[36:37], s[24:25], v25, s6, v[12:13]
	v_mad_u64_u32 v[38:39], s[24:25], v23, s6, v[12:13]
	v_mad_u64_u32 v[40:41], s[24:25], v62, s6, v[12:13]
	v_mad_u64_u32 v[42:43], s[24:25], v51, s6, v[12:13]
	v_mad_u64_u32 v[44:45], s[24:25], v64, s6, v[12:13]
	v_mad_u64_u32 v[46:47], s[24:25], v63, s6, v[12:13]
	v_mad_u64_u32 v[48:49], s[24:25], v66, s6, v[12:13]
	v_mad_u64_u32 v[52:53], s[24:25], v65, s6, v[12:13]
	v_mad_u64_u32 v[54:55], s[24:25], v68, s6, v[12:13]
	v_mad_u64_u32 v[56:57], s[24:25], v67, s6, v[12:13]
	v_mad_u64_u32 v[58:59], s[24:25], v70, s6, v[12:13]
	v_mad_u64_u32 v[60:61], s[24:25], v69, s6, v[12:13]
	ds_write_b32 v28, v9
	ds_write_b32 v30, v13
	s_waitcnt vmcnt(29)
	ds_write_b32 v32, v71
	s_waitcnt vmcnt(28)
	ds_write_b32 v34, v72
	s_waitcnt vmcnt(27)
	ds_write_b32 v36, v73
	s_waitcnt vmcnt(26)
	ds_write_b32 v38, v74
	s_waitcnt vmcnt(25)
	ds_write_b32 v40, v75
	s_waitcnt vmcnt(24)
	ds_write_b32 v42, v76
	s_waitcnt vmcnt(23)
	ds_write_b32 v44, v77
	s_waitcnt vmcnt(22)
	ds_write_b32 v46, v78
	s_waitcnt vmcnt(21)
	ds_write_b32 v48, v79
	s_waitcnt vmcnt(20)
	ds_write_b32 v52, v80
	s_waitcnt vmcnt(19)
	ds_write_b32 v54, v81
	s_waitcnt vmcnt(18)
	ds_write_b32 v56, v82
	s_waitcnt vmcnt(17)
	ds_write_b32 v58, v83
	s_waitcnt vmcnt(16)
	ds_write_b32 v60, v84
	s_waitcnt vmcnt(14)
	v_mad_u64_u32 v[96:97], s[24:25], v129, s6, v[12:13]
	v_mad_u64_u32 v[98:99], s[24:25], v128, s6, v[12:13]
	v_mad_u64_u32 v[100:101], s[24:25], v133, s6, v[12:13]
	v_mad_u64_u32 v[102:103], s[24:25], v132, s6, v[12:13]
	v_mad_u64_u32 v[104:105], s[24:25], v135, s6, v[12:13]
	v_mad_u64_u32 v[106:107], s[24:25], v134, s6, v[12:13]
	v_mad_u64_u32 v[108:109], s[24:25], v137, s6, v[12:13]
	v_mad_u64_u32 v[110:111], s[24:25], v136, s6, v[12:13]
	v_mad_u64_u32 v[112:113], s[24:25], v139, s6, v[12:13]
	v_mad_u64_u32 v[114:115], s[24:25], v138, s6, v[12:13]
	v_mad_u64_u32 v[116:117], s[24:25], v141, s6, v[12:13]
	v_mad_u64_u32 v[118:119], s[24:25], v140, s6, v[12:13]
	v_mad_u64_u32 v[120:121], s[24:25], v143, s6, v[12:13]
	v_mad_u64_u32 v[122:123], s[24:25], v142, s6, v[12:13]
	v_mad_u64_u32 v[124:125], s[24:25], v145, s6, v[12:13]
	v_mad_u64_u32 v[126:127], s[24:25], v144, s6, v[12:13]
	ds_write_b32 v96, v130
	ds_write_b32 v98, v131
	s_waitcnt vmcnt(13)
	ds_write_b32 v100, v146
	s_waitcnt vmcnt(12)
	ds_write_b32 v102, v147
	s_waitcnt vmcnt(11)
	ds_write_b32 v104, v148
	s_waitcnt vmcnt(10)
	ds_write_b32 v106, v149
	s_waitcnt vmcnt(9)
	ds_write_b32 v108, v150
	s_waitcnt vmcnt(8)
	ds_write_b32 v110, v151
	s_waitcnt vmcnt(7)
	ds_write_b32 v112, v152
	s_waitcnt vmcnt(6)
	ds_write_b32 v114, v153
	s_waitcnt vmcnt(5)
	ds_write_b32 v116, v154
	s_waitcnt vmcnt(4)
	ds_write_b32 v118, v155
	s_waitcnt vmcnt(3)
	ds_write_b32 v120, v156
	s_waitcnt vmcnt(2)
	ds_write_b32 v122, v157
	s_waitcnt vmcnt(1)
	ds_write_b32 v124, v158
	s_waitcnt vmcnt(0)
	ds_write_b32 v126, v159
	s_cmpk_gt_i32 s4, 0xaf
	s_cselect_b32 s9, 0xffffea00, 0
	s_cselect_b32 s4, 0x80, 0
	s_add_i32 s9, s9, s20
	s_ashr_i32 s22, s9, 7
	s_ashr_i32 s23, s22, 31
	s_waitcnt lgkmcnt(0)
	s_and_b32 s9, s20, 0x60
	s_lshl_b64 s[20:21], s[22:23], 8
	ds_read2_b32 v[30:31], v3 offset0:33 offset1:41
	ds_read2_b32 v[32:33], v3 offset1:8
	ds_read2_b32 v[34:35], v3 offset0:66 offset1:74
	ds_read2_b32 v[36:37], v3 offset0:99 offset1:107
	ds_read2_b32 v[38:39], v3 offset0:132 offset1:140
	ds_read2_b32 v[40:41], v3 offset0:165 offset1:173
	ds_read2_b32 v[42:43], v3 offset0:198 offset1:206
	ds_read2_b32 v[44:45], v3 offset0:231 offset1:239
	s_or_b64 s[20:21], s[20:21], s[4:5]
	s_or_b32 s4, s20, s9
	s_ashr_i32 s19, s18, 31
	v_mov_b32_e32 v49, s21
	v_or_b32_e32 v48, s4, v14
	v_lshl_add_u64 v[46:47], s[18:19], 1, v[16:17]
	v_lshlrev_b64 v[48:49], 12, v[48:49]
	s_waitcnt lgkmcnt(6)
	v_cvt_pk_bf16_f32 v26, v32, v30
	s_waitcnt lgkmcnt(4)
	v_cvt_pk_bf16_f32 v27, v34, v36
	s_waitcnt lgkmcnt(2)
	v_cvt_pk_bf16_f32 v28, v38, v40
	s_waitcnt lgkmcnt(0)
	v_cvt_pk_bf16_f32 v29, v42, v44
	v_lshl_add_u64 v[48:49], v[46:47], 0, v[48:49]
	global_store_dwordx4 v[48:49], v[26:29], off
	v_or_b32_e32 v30, s4, v20
	s_add_i32 s8, s8, s36
	v_cvt_pk_bf16_f32 v26, v33, v31
	v_cvt_pk_bf16_f32 v27, v35, v37
	v_cvt_pk_bf16_f32 v28, v39, v41
	v_cvt_pk_bf16_f32 v29, v43, v45
	v_mov_b32_e32 v31, s21
	ds_read2_b32 v[32:33], v3 offset0:49 offset1:57
	ds_read2_b32 v[34:35], v3 offset0:16 offset1:24
	ds_read2_b32 v[36:37], v3 offset0:82 offset1:90
	ds_read2_b32 v[38:39], v3 offset0:115 offset1:123
	ds_read2_b32 v[40:41], v3 offset0:148 offset1:156
	ds_read2_b32 v[42:43], v3 offset0:181 offset1:189
	ds_read2_b32 v[44:45], v3 offset0:214 offset1:222
	ds_read2_b32 v[48:49], v3 offset0:247 offset1:255
	v_lshlrev_b64 v[30:31], 12, v[30:31]
	v_lshl_add_u64 v[30:31], v[46:47], 0, v[30:31]
	global_store_dwordx4 v[30:31], v[26:29], off
	v_mov_b32_e32 v31, s21
	v_or_b32_e32 v30, s4, v22
	v_lshlrev_b64 v[30:31], 12, v[30:31]
	s_waitcnt lgkmcnt(6)
	v_cvt_pk_bf16_f32 v26, v34, v32
	s_waitcnt lgkmcnt(4)
	v_cvt_pk_bf16_f32 v27, v36, v38
	s_waitcnt lgkmcnt(2)
	v_cvt_pk_bf16_f32 v28, v40, v42
	s_waitcnt lgkmcnt(0)
	v_cvt_pk_bf16_f32 v29, v44, v48
	v_lshl_add_u64 v[30:31], v[46:47], 0, v[30:31]
	global_store_dwordx4 v[30:31], v[26:29], off
	v_mov_b32_e32 v31, s21
	v_or_b32_e32 v30, s4, v24
	v_lshlrev_b64 v[30:31], 12, v[30:31]
	v_cvt_pk_bf16_f32 v26, v35, v33
	v_cvt_pk_bf16_f32 v27, v37, v39
	v_cvt_pk_bf16_f32 v28, v41, v43
	v_cvt_pk_bf16_f32 v29, v45, v49
	v_lshl_add_u64 v[30:31], v[46:47], 0, v[30:31]
	global_store_dwordx4 v[30:31], v[26:29], off
	s_waitcnt lgkmcnt(0)
	s_cmpk_lt_i32 s8, 0x2c00
	s_cbranch_scc1 .LBB0_59
	v_mov_b32_e32 v10, v4
	v_mov_b32_e32 v14, v6
	s_andn2_b64 vcc, exec, s[0:1]
	s_cbranch_vccz .LBB0_56

; __device__ __forceinline__ void transpose_item(const float* W, int N, bf16_t* WT, int dstK, size_t drow0, int kdst0, int k0, int n0, LAS float* scr, int lane) {
; #pragma unroll 8
;     for (int i = 0; i < 32; ++i) { const int kk = 2 * i + (lane >> 5); scr[kk * 33 + (lane & 31)] = W[(size_t)(k0 + kk) * N + n0 + (lane & 31)]; }
.LBB0_66:
	s_lshl_b32 s10, s18, 1
	s_lshl_b32 s11, s9, 1
	v_or_b32_e32 v51, s10, v11
	v_or_b32_e32 v58, s11, v10
	s_add_i32 s19, s10, 4
	s_add_i32 s20, s11, 4
	s_add_i32 s21, s10, 8
	s_add_i32 s22, s11, 8
	s_add_i32 s23, s10, 12
	s_add_i32 s24, s11, 12
	s_add_i32 s25, s10, 16
	s_add_i32 s27, s11, 16
	s_add_i32 s28, s10, 20
	s_add_i32 s29, s11, 20
	s_add_i32 s30, s10, 24
	s_add_i32 s31, s11, 24
	s_add_i32 s10, s10, 28
	s_add_i32 s11, s11, 28
	v_add_u32_e32 v26, s4, v58
	v_or_b32_e32 v59, s19, v11
	v_or_b32_e32 v60, s20, v10
	v_or_b32_e32 v61, s21, v11
	v_or_b32_e32 v62, s22, v10
	v_or_b32_e32 v63, s23, v11
	v_or_b32_e32 v64, s24, v10
	v_or_b32_e32 v65, s25, v11
	v_or_b32_e32 v66, s27, v10
	v_or_b32_e32 v67, s28, v11
	v_or_b32_e32 v68, s29, v10
	v_or_b32_e32 v69, s30, v11
	v_or_b32_e32 v70, s31, v10
	v_or_b32_e32 v71, s10, v11
	v_or_b32_e32 v72, s11, v10
	v_add_u32_e32 v24, s1, v51
	v_ashrrev_i32_e32 v27, 31, v26
	v_add_u32_e32 v28, s1, v59
	v_add_u32_e32 v30, s4, v60
	v_add_u32_e32 v32, s1, v61
	v_add_u32_e32 v34, s4, v62
	v_add_u32_e32 v36, s1, v63
	v_add_u32_e32 v38, s4, v64
	v_add_u32_e32 v40, s1, v65
	v_add_u32_e32 v42, s4, v66
	v_add_u32_e32 v44, s1, v67
	v_add_u32_e32 v46, s4, v68
	v_add_u32_e32 v48, s1, v69
	v_add_u32_e32 v52, s4, v70
	v_add_u32_e32 v54, s1, v71
	v_add_u32_e32 v56, s4, v72
	v_ashrrev_i32_e32 v25, 31, v24
	v_lshlrev_b64 v[26:27], 13, v[26:27]
	v_ashrrev_i32_e32 v31, 31, v30
	v_ashrrev_i32_e32 v29, 31, v28
	v_ashrrev_i32_e32 v35, 31, v34
	v_ashrrev_i32_e32 v33, 31, v32
	v_ashrrev_i32_e32 v39, 31, v38
	v_ashrrev_i32_e32 v37, 31, v36
	v_ashrrev_i32_e32 v43, 31, v42
	v_ashrrev_i32_e32 v41, 31, v40
	v_ashrrev_i32_e32 v47, 31, v46
	v_ashrrev_i32_e32 v45, 31, v44
	v_ashrrev_i32_e32 v53, 31, v52
	v_ashrrev_i32_e32 v49, 31, v48
	v_ashrrev_i32_e32 v57, 31, v56
	v_ashrrev_i32_e32 v55, 31, v54
	v_lshlrev_b64 v[24:25], 13, v[24:25]
	v_lshl_add_u64 v[26:27], v[22:23], 0, v[26:27]
	v_lshlrev_b64 v[28:29], 13, v[28:29]
	v_lshlrev_b64 v[30:31], 13, v[30:31]
	v_lshlrev_b64 v[32:33], 13, v[32:33]
	v_lshlrev_b64 v[34:35], 13, v[34:35]
	v_lshlrev_b64 v[36:37], 13, v[36:37]
	v_lshlrev_b64 v[38:39], 13, v[38:39]
	v_lshlrev_b64 v[40:41], 13, v[40:41]
	v_lshlrev_b64 v[42:43], 13, v[42:43]
	v_lshlrev_b64 v[44:45], 13, v[44:45]
	v_lshlrev_b64 v[46:47], 13, v[46:47]
	v_lshlrev_b64 v[48:49], 13, v[48:49]
	v_lshlrev_b64 v[52:53], 13, v[52:53]
	v_lshlrev_b64 v[54:55], 13, v[54:55]
	v_lshlrev_b64 v[56:57], 13, v[56:57]
	v_lshl_add_u64 v[24:25], v[22:23], 0, v[24:25]
	v_lshl_add_u64 v[30:31], v[22:23], 0, v[30:31]
	v_lshl_add_u64 v[28:29], v[22:23], 0, v[28:29]
	v_lshl_add_u64 v[34:35], v[22:23], 0, v[34:35]
	v_lshl_add_u64 v[32:33], v[22:23], 0, v[32:33]
	v_lshl_add_u64 v[38:39], v[22:23], 0, v[38:39]
	v_lshl_add_u64 v[36:37], v[22:23], 0, v[36:37]
	v_lshl_add_u64 v[42:43], v[22:23], 0, v[42:43]
	v_lshl_add_u64 v[40:41], v[22:23], 0, v[40:41]
	v_lshl_add_u64 v[46:47], v[22:23], 0, v[46:47]
	v_lshl_add_u64 v[44:45], v[22:23], 0, v[44:45]
	v_lshl_add_u64 v[52:53], v[22:23], 0, v[52:53]
	v_lshl_add_u64 v[48:49], v[22:23], 0, v[48:49]
	v_lshl_add_u64 v[56:57], v[22:23], 0, v[56:57]
	v_lshl_add_u64 v[54:55], v[22:23], 0, v[54:55]
	global_load_dword v73, v[26:27], off
	global_load_dword v74, v[24:25], off
	global_load_dword v75, v[30:31], off
	global_load_dword v76, v[28:29], off
	global_load_dword v77, v[34:35], off
	global_load_dword v78, v[32:33], off
	global_load_dword v79, v[38:39], off
	global_load_dword v80, v[36:37], off
	global_load_dword v81, v[42:43], off
	global_load_dword v82, v[40:41], off
	global_load_dword v83, v[46:47], off
	global_load_dword v84, v[44:45], off
	global_load_dword v85, v[52:53], off
	global_load_dword v86, v[48:49], off
	global_load_dword v87, v[56:57], off
	global_load_dword v88, v[54:55], off
	s_add_i32 s9, s9, 16
	s_add_i32 s18, s18, 16
	s_add_i32 s5, s5, -16
	v_mad_u64_u32 v[24:25], s[20:21], v58, s6, v[14:15]
	s_cmp_lg_u32 s5, 0
	v_mad_u64_u32 v[26:27], s[20:21], v51, s6, v[14:15]
	v_mad_u64_u32 v[28:29], s[20:21], v60, s6, v[14:15]
	v_mad_u64_u32 v[30:31], s[20:21], v59, s6, v[14:15]
	v_mad_u64_u32 v[32:33], s[20:21], v62, s6, v[14:15]
	v_mad_u64_u32 v[34:35], s[20:21], v61, s6, v[14:15]
	v_mad_u64_u32 v[36:37], s[20:21], v64, s6, v[14:15]
	v_mad_u64_u32 v[38:39], s[20:21], v63, s6, v[14:15]
	v_mad_u64_u32 v[40:41], s[20:21], v66, s6, v[14:15]
	v_mad_u64_u32 v[42:43], s[20:21], v65, s6, v[14:15]
	v_mad_u64_u32 v[44:45], s[20:21], v68, s6, v[14:15]
	v_mad_u64_u32 v[46:47], s[20:21], v67, s6, v[14:15]
	v_mad_u64_u32 v[48:49], s[20:21], v70, s6, v[14:15]
	v_mad_u64_u32 v[52:53], s[20:21], v69, s6, v[14:15]
	v_mad_u64_u32 v[54:55], s[20:21], v72, s6, v[14:15]
	v_mad_u64_u32 v[56:57], s[20:21], v71, s6, v[14:15]
	s_lshl_b32 s10, s18, 1
	s_lshl_b32 s11, s9, 1
	v_or_b32_e32 v128, s10, v11
	v_or_b32_e32 v129, s11, v10
	s_add_i32 s19, s10, 4
	s_add_i32 s20, s11, 4
	s_add_i32 s21, s10, 8
	s_add_i32 s22, s11, 8
	s_add_i32 s23, s10, 12
	s_add_i32 s24, s11, 12
	s_add_i32 s25, s10, 16
	s_add_i32 s27, s11, 16
	s_add_i32 s28, s10, 20
	s_add_i32 s29, s11, 20
	s_add_i32 s30, s10, 24
	s_add_i32 s31, s11, 24
	s_add_i32 s10, s10, 28
	s_add_i32 s11, s11, 28
	v_add_u32_e32 v98, s4, v129
	v_or_b32_e32 v130, s19, v11
	v_or_b32_e32 v131, s20, v10
	v_or_b32_e32 v132, s21, v11
	v_or_b32_e32 v133, s22, v10
	v_or_b32_e32 v134, s23, v11
	v_or_b32_e32 v135, s24, v10
	v_or_b32_e32 v136, s25, v11
	v_or_b32_e32 v137, s27, v10
	v_or_b32_e32 v138, s28, v11
	v_or_b32_e32 v139, s29, v10
	v_or_b32_e32 v140, s30, v11
	v_or_b32_e32 v141, s31, v10
	v_or_b32_e32 v142, s10, v11
	v_or_b32_e32 v143, s11, v10
	v_add_u32_e32 v96, s1, v128
	v_ashrrev_i32_e32 v99, 31, v98
; __device__ __forceinline__ void transpose_item(const float* W, int N, bf16_t* WT, int dstK, size_t drow0, int kdst0, int k0, int n0, LAS float* scr, int lane) {
; #pragma unroll 8
;     for (int i = 0; i < 32; ++i) { const int kk = 2 * i + (lane >> 5); scr[kk * 33 + (lane & 31)] = W[(size_t)(k0 + kk) * N + n0 + (lane & 31)]; }
	v_add_u32_e32 v100, s1, v130
	v_add_u32_e32 v102, s4, v131
	v_add_u32_e32 v104, s1, v132
	v_add_u32_e32 v106, s4, v133
	v_add_u32_e32 v108, s1, v134
	v_add_u32_e32 v110, s4, v135
	v_add_u32_e32 v112, s1, v136
	v_add_u32_e32 v114, s4, v137
	v_add_u32_e32 v116, s1, v138
	v_add_u32_e32 v118, s4, v139
	v_add_u32_e32 v120, s1, v140
	v_add_u32_e32 v122, s4, v141
	v_add_u32_e32 v124, s1, v142
	v_add_u32_e32 v126, s4, v143
	v_ashrrev_i32_e32 v97, 31, v96
	v_lshlrev_b64 v[98:99], 13, v[98:99]
	v_ashrrev_i32_e32 v103, 31, v102
	v_ashrrev_i32_e32 v101, 31, v100
	v_ashrrev_i32_e32 v107, 31, v106
	v_ashrrev_i32_e32 v105, 31, v104
	v_ashrrev_i32_e32 v111, 31, v110
	v_ashrrev_i32_e32 v109, 31, v108
	v_ashrrev_i32_e32 v115, 31, v114
	v_ashrrev_i32_e32 v113, 31, v112
	v_ashrrev_i32_e32 v119, 31, v118
	v_ashrrev_i32_e32 v117, 31, v116
	v_ashrrev_i32_e32 v123, 31, v122
	v_ashrrev_i32_e32 v121, 31, v120
	v_ashrrev_i32_e32 v127, 31, v126
	v_ashrrev_i32_e32 v125, 31, v124
	v_lshlrev_b64 v[96:97], 13, v[96:97]
	v_lshl_add_u64 v[98:99], v[22:23], 0, v[98:99]
	v_lshlrev_b64 v[100:101], 13, v[100:101]
	v_lshlrev_b64 v[102:103], 13, v[102:103]
	v_lshlrev_b64 v[104:105], 13, v[104:105]
	v_lshlrev_b64 v[106:107], 13, v[106:107]
	v_lshlrev_b64 v[108:109], 13, v[108:109]
	v_lshlrev_b64 v[110:111], 13, v[110:111]
	v_lshlrev_b64 v[112:113], 13, v[112:113]
	v_lshlrev_b64 v[114:115], 13, v[114:115]
	v_lshlrev_b64 v[116:117], 13, v[116:117]
	v_lshlrev_b64 v[118:119], 13, v[118:119]
	v_lshlrev_b64 v[120:121], 13, v[120:121]
	v_lshlrev_b64 v[122:123], 13, v[122:123]
	v_lshlrev_b64 v[124:125], 13, v[124:125]
	v_lshlrev_b64 v[126:127], 13, v[126:127]
	v_lshl_add_u64 v[96:97], v[22:23], 0, v[96:97]
	v_lshl_add_u64 v[102:103], v[22:23], 0, v[102:103]
	v_lshl_add_u64 v[100:101], v[22:23], 0, v[100:101]
	v_lshl_add_u64 v[106:107], v[22:23], 0, v[106:107]
	v_lshl_add_u64 v[104:105], v[22:23], 0, v[104:105]
	v_lshl_add_u64 v[110:111], v[22:23], 0, v[110:111]
	v_lshl_add_u64 v[108:109], v[22:23], 0, v[108:109]
	v_lshl_add_u64 v[114:115], v[22:23], 0, v[114:115]
	v_lshl_add_u64 v[112:113], v[22:23], 0, v[112:113]
	v_lshl_add_u64 v[118:119], v[22:23], 0, v[118:119]
	v_lshl_add_u64 v[116:117], v[22:23], 0, v[116:117]
	v_lshl_add_u64 v[122:123], v[22:23], 0, v[122:123]
	v_lshl_add_u64 v[120:121], v[22:23], 0, v[120:121]
	v_lshl_add_u64 v[126:127], v[22:23], 0, v[126:127]
	v_lshl_add_u64 v[124:125], v[22:23], 0, v[124:125]
	global_load_dword v144, v[98:99], off
	global_load_dword v145, v[96:97], off
	global_load_dword v146, v[102:103], off
	global_load_dword v147, v[100:101], off
	global_load_dword v148, v[106:107], off
	global_load_dword v149, v[104:105], off
	global_load_dword v150, v[110:111], off
	global_load_dword v151, v[108:109], off
	global_load_dword v152, v[114:115], off
	global_load_dword v153, v[112:113], off
	global_load_dword v154, v[118:119], off
	global_load_dword v155, v[116:117], off
	global_load_dword v156, v[122:123], off
	global_load_dword v157, v[120:121], off
	global_load_dword v158, v[126:127], off
	global_load_dword v159, v[124:125], off
	s_add_i32 s9, s9, 16
	s_add_i32 s18, s18, 16
	s_add_i32 s5, s5, -16
	v_mad_u64_u32 v[96:97], s[20:21], v129, s6, v[14:15]
	s_cmp_lg_u32 s5, 0
	v_mad_u64_u32 v[98:99], s[20:21], v128, s6, v[14:15]
	v_mad_u64_u32 v[100:101], s[20:21], v131, s6, v[14:15]
	v_mad_u64_u32 v[102:103], s[20:21], v130, s6, v[14:15]
	v_mad_u64_u32 v[104:105], s[20:21], v133, s6, v[14:15]
	v_mad_u64_u32 v[106:107], s[20:21], v132, s6, v[14:15]
	v_mad_u64_u32 v[108:109], s[20:21], v135, s6, v[14:15]
	v_mad_u64_u32 v[110:111], s[20:21], v134, s6, v[14:15]
	v_mad_u64_u32 v[112:113], s[20:21], v137, s6, v[14:15]
	v_mad_u64_u32 v[114:115], s[20:21], v136, s6, v[14:15]
	v_mad_u64_u32 v[116:117], s[20:21], v139, s6, v[14:15]
	v_mad_u64_u32 v[118:119], s[20:21], v138, s6, v[14:15]
	v_mad_u64_u32 v[120:121], s[20:21], v141, s6, v[14:15]
	v_mad_u64_u32 v[122:123], s[20:21], v140, s6, v[14:15]
	v_mad_u64_u32 v[124:125], s[20:21], v143, s6, v[14:15]
	v_mad_u64_u32 v[126:127], s[20:21], v142, s6, v[14:15]
	s_waitcnt vmcnt(31)
; #define LAS __attribute__((address_space(3)))
; __device__ __forceinline__ unsigned cvt_pk_bf16(float lo, float hi) { f32x2_c v = {lo, hi}; bf16x2_c r = __builtin_convertvector(v, bf16x2_c); return __builtin_bit_cast(unsigned, r); }
; #define LDS_WAIT() asm volatile("s_waitcnt lgkmcnt(0)" ::: "memory")
; __device__ __forceinline__ void transpose_item(const float* W, int N, bf16_t* WT, int dstK, size_t drow0, int kdst0, int k0, int n0, LAS float* scr, int lane) {
;     ...
;     for (int i = 0; i < 32; ++i) { const int kk = 2 * i + (lane >> 5); scr[kk * 33 + (lane & 31)] = W[(size_t)(k0 + kk) * N + n0 + (lane & 31)]; }
;     LDS_WAIT();
;     const int c = lane & 7;
; #pragma unroll
;     for (int j = 0; j < 4; ++j) { const int n = (lane >> 3) + 8 * j; const LAS float* s = scr + (8 * c) * 33 + n;
;         u32x4 o; o.x = cvt_pk_bf16(s[0 * 33], s[1 * 33]); o.y = cvt_pk_bf16(s[2 * 33], s[3 * 33]); o.z = cvt_pk_bf16(s[4 * 33], s[5 * 33]); o.w = cvt_pk_bf16(s[6 * 33], s[7 * 33]);
;         *(u32x4*)(WT + (drow0 + n) * dstK + kdst0 + k0 + 8 * c) = o; }
;     LDS_WAIT();
; }
; __device__ __forceinline__ void transpose_matrix(const float* W, int K, int N, bf16_t* WT, int dstK, int kdst0, int mode, LAS float* scr, int gw, int NGW, int lane) {
;     const int nblk = N / 32, items = (K / 64) * nblk;
;     for (int it = gw; it < items; it += NGW) {
;         const int kb = it / nblk, nb = it % nblk, n0 = nb * 32;
;         size_t drow0 = (size_t)n0;
;         if (mode == 1) { const int half = n0 >= DFF ? 1 : 0, nn = n0 - half * DFF; drow0 = (size_t)(nn >> 7) * 256 + half * 128 + (nn & 127); }
;         transpose_item(W, N, WT, dstK, drow0, kdst0, kb * 64, n0, scr, lane);
;     }
	ds_write_b32 v24, v73
	s_waitcnt vmcnt(30)
	ds_write_b32 v26, v74
	s_waitcnt vmcnt(29)
	ds_write_b32 v28, v75
	s_waitcnt vmcnt(28)
	ds_write_b32 v30, v76
	s_waitcnt vmcnt(27)
	ds_write_b32 v32, v77
	s_waitcnt vmcnt(26)
	ds_write_b32 v34, v78
	s_waitcnt vmcnt(25)
	ds_write_b32 v36, v79
	s_waitcnt vmcnt(24)
	ds_write_b32 v38, v80
	s_waitcnt vmcnt(23)
	ds_write_b32 v40, v81
	s_waitcnt vmcnt(22)
	ds_write_b32 v42, v82
	s_waitcnt vmcnt(21)
	ds_write_b32 v44, v83
	s_waitcnt vmcnt(20)
	ds_write_b32 v46, v84
	s_waitcnt vmcnt(19)
	ds_write_b32 v48, v85
	s_waitcnt vmcnt(18)
	ds_write_b32 v52, v86
	s_waitcnt vmcnt(17)
	ds_write_b32 v54, v87
	s_waitcnt vmcnt(16)
	ds_write_b32 v56, v88
	s_waitcnt vmcnt(15)
	ds_write_b32 v96, v144
	s_waitcnt vmcnt(14)
	ds_write_b32 v98, v145
	s_waitcnt vmcnt(13)
	ds_write_b32 v100, v146
	s_waitcnt vmcnt(12)
	ds_write_b32 v102, v147
	s_waitcnt vmcnt(11)
	ds_write_b32 v104, v148
	s_waitcnt vmcnt(10)
	ds_write_b32 v106, v149
	s_waitcnt vmcnt(9)
	ds_write_b32 v108, v150
	s_waitcnt vmcnt(8)
	ds_write_b32 v110, v151
	s_waitcnt vmcnt(7)
	ds_write_b32 v112, v152
	s_waitcnt vmcnt(6)
	ds_write_b32 v114, v153
	s_waitcnt vmcnt(5)
	ds_write_b32 v116, v154
	s_waitcnt vmcnt(4)
	ds_write_b32 v118, v155
	s_waitcnt vmcnt(3)
	ds_write_b32 v120, v156
	s_waitcnt vmcnt(2)
	ds_write_b32 v122, v157
	s_waitcnt vmcnt(1)
	ds_write_b32 v124, v158
	s_waitcnt vmcnt(0)
	ds_write_b32 v126, v159
	s_waitcnt lgkmcnt(0)
	ds_read2_b32 v[26:27], v15 offset0:33 offset1:41
	ds_read2_b32 v[28:29], v15 offset1:8
	ds_read2_b32 v[30:31], v15 offset0:66 offset1:74
	ds_read2_b32 v[32:33], v15 offset0:99 offset1:107
	ds_read2_b32 v[34:35], v15 offset0:132 offset1:140
	ds_read2_b32 v[36:37], v15 offset0:165 offset1:173
	ds_read2_b32 v[38:39], v15 offset0:198 offset1:206
	ds_read2_b32 v[40:41], v15 offset0:231 offset1:239
	s_ashr_i32 s5, s4, 31
	v_lshl_add_u64 v[42:43], s[4:5], 1, v[20:21]
	s_waitcnt lgkmcnt(6)
	v_cvt_pk_bf16_f32 v22, v28, v26
	v_or_b32_e32 v26, s0, v2
	s_waitcnt lgkmcnt(4)
	v_cvt_pk_bf16_f32 v23, v30, v32
	s_waitcnt lgkmcnt(2)
	v_cvt_pk_bf16_f32 v24, v34, v36
	s_waitcnt lgkmcnt(0)
	v_cvt_pk_bf16_f32 v25, v38, v40
	v_mad_i64_i32 v[44:45], s[4:5], v26, s7, v[42:43]
	global_store_dwordx4 v[44:45], v[22:25], off
	v_or_b32_e32 v26, s0, v4
	s_add_i32 s8, s8, s36
	v_cvt_pk_bf16_f32 v22, v29, v27
	v_cvt_pk_bf16_f32 v23, v31, v33
	v_cvt_pk_bf16_f32 v24, v35, v37
	v_cvt_pk_bf16_f32 v25, v39, v41
	ds_read2_b32 v[28:29], v15 offset0:49 offset1:57
	ds_read2_b32 v[30:31], v15 offset0:16 offset1:24
	ds_read2_b32 v[32:33], v15 offset0:82 offset1:90
	ds_read2_b32 v[34:35], v15 offset0:115 offset1:123
	ds_read2_b32 v[36:37], v15 offset0:148 offset1:156
	ds_read2_b32 v[38:39], v15 offset0:181 offset1:189
	ds_read2_b32 v[40:41], v15 offset0:214 offset1:222
	ds_read2_b32 v[44:45], v15 offset0:247 offset1:255
	v_mad_i64_i32 v[26:27], s[4:5], v26, s7, v[42:43]
	global_store_dwordx4 v[26:27], v[22:25], off
	v_or_b32_e32 v26, s0, v6
	v_mad_i64_i32 v[26:27], s[4:5], v26, s7, v[42:43]
	s_waitcnt lgkmcnt(6)
	v_cvt_pk_bf16_f32 v22, v30, v28
	s_waitcnt lgkmcnt(4)
	v_cvt_pk_bf16_f32 v23, v32, v34
	s_waitcnt lgkmcnt(2)
	v_cvt_pk_bf16_f32 v24, v36, v38
	s_waitcnt lgkmcnt(0)
	v_cvt_pk_bf16_f32 v25, v40, v44
	global_store_dwordx4 v[26:27], v[22:25], off
	v_or_b32_e32 v26, s0, v12
	v_mad_i64_i32 v[26:27], s[0:1], v26, s7, v[42:43]
	v_cvt_pk_bf16_f32 v22, v31, v29
	v_cvt_pk_bf16_f32 v23, v33, v35
	v_cvt_pk_bf16_f32 v24, v37, v39
	v_cvt_pk_bf16_f32 v25, v41, v45
	global_store_dwordx4 v[26:27], v[22:25], off
	s_waitcnt lgkmcnt(0)
	s_cmpk_lt_i32 s8, 0x1600
	s_cbranch_scc1 .LBB0_65
	v_mov_b32_e32 v20, v2
	v_mov_b64_e32 v[16:17], v[2:3]

; __device__ __forceinline__ void transpose_item(const float* W, int N, bf16_t* WT, int dstK, size_t drow0, int kdst0, int k0, int n0, LAS float* scr, int lane) {
; #pragma unroll 8
;     for (int i = 0; i < 32; ++i) { const int kk = 2 * i + (lane >> 5); scr[kk * 33 + (lane & 31)] = W[(size_t)(k0 + kk) * N + n0 + (lane & 31)]; }
; __global__ void __launch_bounds__(NTHREADS, 2) fwd_kernel(Args args) {
;     ...
;             transpose_matrix(lru_wa + nb * 16384, 128, 128, WLA + nb * 16384, 128, 0, 0, scr, gw, NGW, lane);
.LBB0_74:
	s_lshl_b32 s10, s21, 1
	s_lshl_b32 s11, s22, 1
	v_or_b32_e32 v51, s10, v3
	v_or_b32_e32 v64, s11, v10
	s_add_i32 s24, s10, 4
	s_add_i32 s25, s11, 4
	s_add_i32 s26, s10, 8
	s_add_i32 s27, s11, 8
	s_add_i32 s28, s10, 12
	s_add_i32 s29, s11, 12
	s_add_i32 s30, s10, 16
	s_add_i32 s31, s11, 16
	s_add_i32 s33, s10, 20
	s_add_i32 s34, s11, 20
	s_add_i32 s35, s10, 24
	s_add_i32 s37, s11, 24
	s_add_i32 s10, s10, 28
	s_add_i32 s11, s11, 28
	v_add_u32_e32 v32, s20, v64
	v_or_b32_e32 v65, s24, v3
	v_or_b32_e32 v66, s25, v10
	v_or_b32_e32 v67, s26, v3
	v_or_b32_e32 v68, s27, v10
	v_or_b32_e32 v69, s28, v3
	v_or_b32_e32 v70, s29, v10
	v_or_b32_e32 v71, s30, v3
	v_or_b32_e32 v72, s31, v10
	v_or_b32_e32 v73, s33, v3
	v_or_b32_e32 v74, s34, v10
	v_or_b32_e32 v75, s35, v3
	v_or_b32_e32 v76, s37, v10
	v_or_b32_e32 v77, s10, v3
	v_or_b32_e32 v78, s11, v10
	v_add_u32_e32 v30, s9, v51
	v_ashrrev_i32_e32 v33, 31, v32
	v_add_u32_e32 v34, s9, v65
	v_add_u32_e32 v36, s20, v66
	v_add_u32_e32 v38, s9, v67
	v_add_u32_e32 v40, s20, v68
	v_add_u32_e32 v42, s9, v69
	v_add_u32_e32 v44, s20, v70
	v_add_u32_e32 v46, s9, v71
	v_add_u32_e32 v48, s20, v72
	v_add_u32_e32 v52, s9, v73
	v_add_u32_e32 v54, s20, v74
	v_add_u32_e32 v56, s9, v75
	v_add_u32_e32 v58, s20, v76
	v_add_u32_e32 v60, s9, v77
	v_add_u32_e32 v62, s20, v78
	v_ashrrev_i32_e32 v31, 31, v30
	v_lshlrev_b64 v[32:33], 9, v[32:33]
	v_ashrrev_i32_e32 v37, 31, v36
	v_ashrrev_i32_e32 v35, 31, v34
	v_ashrrev_i32_e32 v41, 31, v40
	v_ashrrev_i32_e32 v39, 31, v38
	v_ashrrev_i32_e32 v45, 31, v44
	v_ashrrev_i32_e32 v43, 31, v42
	v_ashrrev_i32_e32 v49, 31, v48
	v_ashrrev_i32_e32 v47, 31, v46
	v_ashrrev_i32_e32 v55, 31, v54
	v_ashrrev_i32_e32 v53, 31, v52
	v_ashrrev_i32_e32 v59, 31, v58
	v_ashrrev_i32_e32 v57, 31, v56
	v_ashrrev_i32_e32 v63, 31, v62
	v_ashrrev_i32_e32 v61, 31, v60
	v_lshlrev_b64 v[30:31], 9, v[30:31]
	v_lshl_add_u64 v[32:33], v[28:29], 0, v[32:33]
	v_lshlrev_b64 v[34:35], 9, v[34:35]
	v_lshlrev_b64 v[36:37], 9, v[36:37]
	v_lshlrev_b64 v[38:39], 9, v[38:39]
	v_lshlrev_b64 v[40:41], 9, v[40:41]
	v_lshlrev_b64 v[42:43], 9, v[42:43]
	v_lshlrev_b64 v[44:45], 9, v[44:45]
	v_lshlrev_b64 v[46:47], 9, v[46:47]
	v_lshlrev_b64 v[48:49], 9, v[48:49]
	v_lshlrev_b64 v[52:53], 9, v[52:53]
	v_lshlrev_b64 v[54:55], 9, v[54:55]
	v_lshlrev_b64 v[56:57], 9, v[56:57]
	v_lshlrev_b64 v[58:59], 9, v[58:59]
	v_lshlrev_b64 v[60:61], 9, v[60:61]
	v_lshlrev_b64 v[62:63], 9, v[62:63]
	v_lshl_add_u64 v[30:31], v[28:29], 0, v[30:31]
	v_lshl_add_u64 v[36:37], v[28:29], 0, v[36:37]
	v_lshl_add_u64 v[34:35], v[28:29], 0, v[34:35]
	v_lshl_add_u64 v[40:41], v[28:29], 0, v[40:41]
	v_lshl_add_u64 v[38:39], v[28:29], 0, v[38:39]
	v_lshl_add_u64 v[44:45], v[28:29], 0, v[44:45]
	v_lshl_add_u64 v[42:43], v[28:29], 0, v[42:43]
	v_lshl_add_u64 v[48:49], v[28:29], 0, v[48:49]
	v_lshl_add_u64 v[46:47], v[28:29], 0, v[46:47]
	v_lshl_add_u64 v[54:55], v[28:29], 0, v[54:55]
	v_lshl_add_u64 v[52:53], v[28:29], 0, v[52:53]
	v_lshl_add_u64 v[58:59], v[28:29], 0, v[58:59]
	v_lshl_add_u64 v[56:57], v[28:29], 0, v[56:57]
	v_lshl_add_u64 v[62:63], v[28:29], 0, v[62:63]
	v_lshl_add_u64 v[60:61], v[28:29], 0, v[60:61]
	global_load_dword v79, v[32:33], off
	global_load_dword v80, v[30:31], off
	global_load_dword v81, v[36:37], off
	global_load_dword v82, v[34:35], off
	global_load_dword v83, v[40:41], off
	global_load_dword v84, v[38:39], off
	global_load_dword v85, v[44:45], off
	global_load_dword v86, v[42:43], off
	global_load_dword v87, v[48:49], off
	global_load_dword v88, v[46:47], off
	global_load_dword v89, v[54:55], off
	global_load_dword v90, v[52:53], off
	global_load_dword v91, v[58:59], off
	global_load_dword v92, v[56:57], off
	global_load_dword v93, v[62:63], off
	global_load_dword v94, v[60:61], off
	s_add_i32 s22, s22, 16
	s_add_i32 s21, s21, 16
	s_add_i32 s23, s23, -16
	v_mad_u64_u32 v[30:31], s[24:25], v64, s6, v[14:15]
	s_cmp_lg_u32 s23, 0
	v_mad_u64_u32 v[32:33], s[24:25], v51, s6, v[14:15]
	v_mad_u64_u32 v[34:35], s[24:25], v66, s6, v[14:15]
	v_mad_u64_u32 v[36:37], s[24:25], v65, s6, v[14:15]
	v_mad_u64_u32 v[38:39], s[24:25], v68, s6, v[14:15]
	v_mad_u64_u32 v[40:41], s[24:25], v67, s6, v[14:15]
	v_mad_u64_u32 v[42:43], s[24:25], v70, s6, v[14:15]
	v_mad_u64_u32 v[44:45], s[24:25], v69, s6, v[14:15]
	v_mad_u64_u32 v[46:47], s[24:25], v72, s6, v[14:15]
	v_mad_u64_u32 v[48:49], s[24:25], v71, s6, v[14:15]
	v_mad_u64_u32 v[52:53], s[24:25], v74, s6, v[14:15]
	v_mad_u64_u32 v[54:55], s[24:25], v73, s6, v[14:15]
	v_mad_u64_u32 v[56:57], s[24:25], v76, s6, v[14:15]
	v_mad_u64_u32 v[58:59], s[24:25], v75, s6, v[14:15]
	v_mad_u64_u32 v[60:61], s[24:25], v78, s6, v[14:15]
	v_mad_u64_u32 v[62:63], s[24:25], v77, s6, v[14:15]
	s_lshl_b32 s10, s21, 1
	s_lshl_b32 s11, s22, 1
	v_or_b32_e32 v128, s10, v3
	v_or_b32_e32 v129, s11, v10
	s_add_i32 s24, s10, 4
	s_add_i32 s25, s11, 4
	s_add_i32 s26, s10, 8
	s_add_i32 s27, s11, 8
	s_add_i32 s28, s10, 12
	s_add_i32 s29, s11, 12
	s_add_i32 s30, s10, 16
	s_add_i32 s31, s11, 16
	s_add_i32 s33, s10, 20
	s_add_i32 s34, s11, 20
	s_add_i32 s35, s10, 24
	s_add_i32 s37, s11, 24
	s_add_i32 s10, s10, 28
	s_add_i32 s11, s11, 28
	v_add_u32_e32 v98, s20, v129
	v_or_b32_e32 v130, s24, v3
	v_or_b32_e32 v131, s25, v10
	v_or_b32_e32 v132, s26, v3
	v_or_b32_e32 v133, s27, v10
	v_or_b32_e32 v134, s28, v3
	v_or_b32_e32 v135, s29, v10
	v_or_b32_e32 v136, s30, v3
	v_or_b32_e32 v137, s31, v10
	v_or_b32_e32 v138, s33, v3
	v_or_b32_e32 v139, s34, v10
	v_or_b32_e32 v140, s35, v3
	v_or_b32_e32 v141, s37, v10
	v_or_b32_e32 v142, s10, v3
	v_or_b32_e32 v143, s11, v10
	v_add_u32_e32 v96, s9, v128
	v_ashrrev_i32_e32 v99, 31, v98
; __device__ __forceinline__ void transpose_item(const float* W, int N, bf16_t* WT, int dstK, size_t drow0, int kdst0, int k0, int n0, LAS float* scr, int lane) {
; #pragma unroll 8
;     for (int i = 0; i < 32; ++i) { const int kk = 2 * i + (lane >> 5); scr[kk * 33 + (lane & 31)] = W[(size_t)(k0 + kk) * N + n0 + (lane & 31)]; }
	v_add_u32_e32 v100, s9, v130
	v_add_u32_e32 v102, s20, v131
	v_add_u32_e32 v104, s9, v132
	v_add_u32_e32 v106, s20, v133
	v_add_u32_e32 v108, s9, v134
	v_add_u32_e32 v110, s20, v135
	v_add_u32_e32 v112, s9, v136
	v_add_u32_e32 v114, s20, v137
	v_add_u32_e32 v116, s9, v138
	v_add_u32_e32 v118, s20, v139
	v_add_u32_e32 v120, s9, v140
	v_add_u32_e32 v122, s20, v141
	v_add_u32_e32 v124, s9, v142
	v_add_u32_e32 v126, s20, v143
	v_ashrrev_i32_e32 v97, 31, v96
	v_lshlrev_b64 v[98:99], 9, v[98:99]
	v_ashrrev_i32_e32 v103, 31, v102
	v_ashrrev_i32_e32 v101, 31, v100
	v_ashrrev_i32_e32 v107, 31, v106
	v_ashrrev_i32_e32 v105, 31, v104
	v_ashrrev_i32_e32 v111, 31, v110
	v_ashrrev_i32_e32 v109, 31, v108
	v_ashrrev_i32_e32 v115, 31, v114
	v_ashrrev_i32_e32 v113, 31, v112
	v_ashrrev_i32_e32 v119, 31, v118
	v_ashrrev_i32_e32 v117, 31, v116
	v_ashrrev_i32_e32 v123, 31, v122
	v_ashrrev_i32_e32 v121, 31, v120
	v_ashrrev_i32_e32 v127, 31, v126
	v_ashrrev_i32_e32 v125, 31, v124
	v_lshlrev_b64 v[96:97], 9, v[96:97]
	v_lshl_add_u64 v[98:99], v[28:29], 0, v[98:99]
	v_lshlrev_b64 v[100:101], 9, v[100:101]
	v_lshlrev_b64 v[102:103], 9, v[102:103]
	v_lshlrev_b64 v[104:105], 9, v[104:105]
	v_lshlrev_b64 v[106:107], 9, v[106:107]
	v_lshlrev_b64 v[108:109], 9, v[108:109]
	v_lshlrev_b64 v[110:111], 9, v[110:111]
	v_lshlrev_b64 v[112:113], 9, v[112:113]
	v_lshlrev_b64 v[114:115], 9, v[114:115]
	v_lshlrev_b64 v[116:117], 9, v[116:117]
	v_lshlrev_b64 v[118:119], 9, v[118:119]
	v_lshlrev_b64 v[120:121], 9, v[120:121]
	v_lshlrev_b64 v[122:123], 9, v[122:123]
	v_lshlrev_b64 v[124:125], 9, v[124:125]
	v_lshlrev_b64 v[126:127], 9, v[126:127]
	v_lshl_add_u64 v[96:97], v[28:29], 0, v[96:97]
	v_lshl_add_u64 v[102:103], v[28:29], 0, v[102:103]
	v_lshl_add_u64 v[100:101], v[28:29], 0, v[100:101]
	v_lshl_add_u64 v[106:107], v[28:29], 0, v[106:107]
	v_lshl_add_u64 v[104:105], v[28:29], 0, v[104:105]
	v_lshl_add_u64 v[110:111], v[28:29], 0, v[110:111]
	v_lshl_add_u64 v[108:109], v[28:29], 0, v[108:109]
	v_lshl_add_u64 v[114:115], v[28:29], 0, v[114:115]
	v_lshl_add_u64 v[112:113], v[28:29], 0, v[112:113]
	v_lshl_add_u64 v[118:119], v[28:29], 0, v[118:119]
	v_lshl_add_u64 v[116:117], v[28:29], 0, v[116:117]
	v_lshl_add_u64 v[122:123], v[28:29], 0, v[122:123]
	v_lshl_add_u64 v[120:121], v[28:29], 0, v[120:121]
	v_lshl_add_u64 v[126:127], v[28:29], 0, v[126:127]
	v_lshl_add_u64 v[124:125], v[28:29], 0, v[124:125]
	global_load_dword v144, v[98:99], off
	global_load_dword v145, v[96:97], off
	global_load_dword v146, v[102:103], off
	global_load_dword v147, v[100:101], off
	global_load_dword v148, v[106:107], off
	global_load_dword v149, v[104:105], off
	global_load_dword v150, v[110:111], off
	global_load_dword v151, v[108:109], off
	global_load_dword v152, v[114:115], off
	global_load_dword v153, v[112:113], off
	global_load_dword v154, v[118:119], off
	global_load_dword v155, v[116:117], off
	global_load_dword v156, v[122:123], off
	global_load_dword v157, v[120:121], off
	global_load_dword v158, v[126:127], off
	global_load_dword v159, v[124:125], off
	s_add_i32 s22, s22, 16
	s_add_i32 s21, s21, 16
	s_add_i32 s23, s23, -16
	v_mad_u64_u32 v[96:97], s[24:25], v129, s6, v[14:15]
	s_cmp_lg_u32 s23, 0
	v_mad_u64_u32 v[98:99], s[24:25], v128, s6, v[14:15]
	v_mad_u64_u32 v[100:101], s[24:25], v131, s6, v[14:15]
	v_mad_u64_u32 v[102:103], s[24:25], v130, s6, v[14:15]
	v_mad_u64_u32 v[104:105], s[24:25], v133, s6, v[14:15]
	v_mad_u64_u32 v[106:107], s[24:25], v132, s6, v[14:15]
	v_mad_u64_u32 v[108:109], s[24:25], v135, s6, v[14:15]
	v_mad_u64_u32 v[110:111], s[24:25], v134, s6, v[14:15]
	v_mad_u64_u32 v[112:113], s[24:25], v137, s6, v[14:15]
	v_mad_u64_u32 v[114:115], s[24:25], v136, s6, v[14:15]
	v_mad_u64_u32 v[116:117], s[24:25], v139, s6, v[14:15]
	v_mad_u64_u32 v[118:119], s[24:25], v138, s6, v[14:15]
	v_mad_u64_u32 v[120:121], s[24:25], v141, s6, v[14:15]
	v_mad_u64_u32 v[122:123], s[24:25], v140, s6, v[14:15]
	v_mad_u64_u32 v[124:125], s[24:25], v143, s6, v[14:15]
	v_mad_u64_u32 v[126:127], s[24:25], v142, s6, v[14:15]
	s_waitcnt vmcnt(31)
	ds_write_b32 v30, v79
	s_waitcnt vmcnt(30)
; #define LAS __attribute__((address_space(3)))
; __device__ __forceinline__ unsigned cvt_pk_bf16(float lo, float hi) { f32x2_c v = {lo, hi}; bf16x2_c r = __builtin_convertvector(v, bf16x2_c); return __builtin_bit_cast(unsigned, r); }
; #define LDS_WAIT() asm volatile("s_waitcnt lgkmcnt(0)" ::: "memory")
; __device__ __forceinline__ void transpose_item(const float* W, int N, bf16_t* WT, int dstK, size_t drow0, int kdst0, int k0, int n0, LAS float* scr, int lane) {
;     ...
;     for (int i = 0; i < 32; ++i) { const int kk = 2 * i + (lane >> 5); scr[kk * 33 + (lane & 31)] = W[(size_t)(k0 + kk) * N + n0 + (lane & 31)]; }
;     LDS_WAIT();
;     const int c = lane & 7;
; #pragma unroll
;     for (int j = 0; j < 4; ++j) { const int n = (lane >> 3) + 8 * j; const LAS float* s = scr + (8 * c) * 33 + n;
;         u32x4 o; o.x = cvt_pk_bf16(s[0 * 33], s[1 * 33]); o.y = cvt_pk_bf16(s[2 * 33], s[3 * 33]); o.z = cvt_pk_bf16(s[4 * 33], s[5 * 33]); o.w = cvt_pk_bf16(s[6 * 33], s[7 * 33]);
;         *(u32x4*)(WT + (drow0 + n) * dstK + kdst0 + k0 + 8 * c) = o; }
;     LDS_WAIT();
; }
; __device__ __forceinline__ void transpose_matrix(const float* W, int K, int N, bf16_t* WT, int dstK, int kdst0, int mode, LAS float* scr, int gw, int NGW, int lane) {
;     const int nblk = N / 32, items = (K / 64) * nblk;
;     for (int it = gw; it < items; it += NGW) {
;         const int kb = it / nblk, nb = it % nblk, n0 = nb * 32;
;         size_t drow0 = (size_t)n0;
;         if (mode == 1) { const int half = n0 >= DFF ? 1 : 0, nn = n0 - half * DFF; drow0 = (size_t)(nn >> 7) * 256 + half * 128 + (nn & 127); }
;         transpose_item(W, N, WT, dstK, drow0, kdst0, kb * 64, n0, scr, lane);
;     }
; __global__ void __launch_bounds__(NTHREADS, 2) fwd_kernel(Args args) {
;     ...
;             transpose_matrix(lru_wa + nb * 16384, 128, 128, WLA + nb * 16384, 128, 0, 0, scr, gw, NGW, lane);
;             transpose_matrix(lru_wx + nb * 16384, 128, 128, WLX + nb * 16384, 128, 0, 0, scr, gw, NGW, lane);
	ds_write_b32 v32, v80
	s_waitcnt vmcnt(29)
	ds_write_b32 v34, v81
	s_waitcnt vmcnt(28)
	ds_write_b32 v36, v82
	s_waitcnt vmcnt(27)
	ds_write_b32 v38, v83
	s_waitcnt vmcnt(26)
	ds_write_b32 v40, v84
	s_waitcnt vmcnt(25)
	ds_write_b32 v42, v85
	s_waitcnt vmcnt(24)
	ds_write_b32 v44, v86
	s_waitcnt vmcnt(23)
	ds_write_b32 v46, v87
	s_waitcnt vmcnt(22)
	ds_write_b32 v48, v88
	s_waitcnt vmcnt(21)
	ds_write_b32 v52, v89
	s_waitcnt vmcnt(20)
	ds_write_b32 v54, v90
	s_waitcnt vmcnt(19)
	ds_write_b32 v56, v91
	s_waitcnt vmcnt(18)
	ds_write_b32 v58, v92
	s_waitcnt vmcnt(17)
	ds_write_b32 v60, v93
	s_waitcnt vmcnt(16)
	ds_write_b32 v62, v94
	s_waitcnt vmcnt(15)
	ds_write_b32 v96, v144
	s_waitcnt vmcnt(14)
	ds_write_b32 v98, v145
	s_waitcnt vmcnt(13)
	ds_write_b32 v100, v146
	s_waitcnt vmcnt(12)
	ds_write_b32 v102, v147
	s_waitcnt vmcnt(11)
	ds_write_b32 v104, v148
	s_waitcnt vmcnt(10)
	ds_write_b32 v106, v149
	s_waitcnt vmcnt(9)
	ds_write_b32 v108, v150
	s_waitcnt vmcnt(8)
	ds_write_b32 v110, v151
	s_waitcnt vmcnt(7)
	ds_write_b32 v112, v152
	s_waitcnt vmcnt(6)
	ds_write_b32 v114, v153
	s_waitcnt vmcnt(5)
	ds_write_b32 v116, v154
	s_waitcnt vmcnt(4)
	ds_write_b32 v118, v155
	s_waitcnt vmcnt(3)
	ds_write_b32 v120, v156
	s_waitcnt vmcnt(2)
	ds_write_b32 v122, v157
	s_waitcnt vmcnt(1)
	ds_write_b32 v124, v158
	s_waitcnt vmcnt(0)
	ds_write_b32 v126, v159
	s_waitcnt lgkmcnt(0)
	ds_read2_b32 v[28:29], v2 offset1:33
	ds_read2_b32 v[30:31], v2 offset0:66 offset1:99
	ds_read2_b32 v[32:33], v2 offset0:132 offset1:165
	ds_read2_b32 v[34:35], v2 offset0:198 offset1:231
	s_ashr_i32 s21, s20, 31
	s_waitcnt lgkmcnt(3)
	v_cvt_pk_bf16_f32 v28, v28, v29
	s_waitcnt lgkmcnt(2)
	v_cvt_pk_bf16_f32 v29, v30, v31
	s_waitcnt lgkmcnt(1)
	v_cvt_pk_bf16_f32 v30, v32, v33
	s_waitcnt lgkmcnt(0)
	v_cvt_pk_bf16_f32 v31, v34, v35
	ds_read2_b32 v[34:35], v11 offset1:33
	ds_read2_b32 v[38:39], v11 offset0:66 offset1:99
	ds_read2_b32 v[40:41], v11 offset0:132 offset1:165
	ds_read2_b32 v[42:43], v11 offset0:198 offset1:231
	v_or_b32_e32 v33, s19, v17
	v_or_b32_e32 v32, s18, v16
	v_lshl_add_u64 v[36:37], s[20:21], 1, v[26:27]
	v_lshlrev_b64 v[32:33], 8, v[32:33]
	v_lshl_add_u64 v[32:33], v[36:37], 0, v[32:33]
	global_store_dwordx4 v[32:33], v[28:31], off
	v_or_b32_e32 v33, s19, v1
	v_or_b32_e32 v32, s18, v4
	s_waitcnt lgkmcnt(3)
	v_cvt_pk_bf16_f32 v28, v34, v35
	s_waitcnt lgkmcnt(2)
	v_cvt_pk_bf16_f32 v29, v38, v39
	s_waitcnt lgkmcnt(1)
	v_cvt_pk_bf16_f32 v30, v40, v41
	s_waitcnt lgkmcnt(0)
	v_cvt_pk_bf16_f32 v31, v42, v43
	ds_read2_b32 v[34:35], v13 offset1:33
	ds_read2_b32 v[38:39], v13 offset0:66 offset1:99
	ds_read2_b32 v[40:41], v13 offset0:132 offset1:165
	ds_read2_b32 v[42:43], v13 offset0:198 offset1:231
	v_lshlrev_b64 v[32:33], 8, v[32:33]
	v_lshl_add_u64 v[32:33], v[36:37], 0, v[32:33]
	global_store_dwordx4 v[32:33], v[28:31], off
	v_or_b32_e32 v33, s19, v5
	v_or_b32_e32 v32, s18, v6
	s_waitcnt lgkmcnt(3)
	v_cvt_pk_bf16_f32 v28, v34, v35
	s_waitcnt lgkmcnt(2)
	v_cvt_pk_bf16_f32 v29, v38, v39
	s_waitcnt lgkmcnt(1)
	v_cvt_pk_bf16_f32 v30, v40, v41
	s_waitcnt lgkmcnt(0)
	v_cvt_pk_bf16_f32 v31, v42, v43
	ds_read2_b32 v[34:35], v15 offset1:33
	ds_read2_b32 v[38:39], v15 offset0:66 offset1:99
	ds_read2_b32 v[40:41], v15 offset0:132 offset1:165
	ds_read2_b32 v[42:43], v15 offset0:198 offset1:231
	v_lshlrev_b64 v[32:33], 8, v[32:33]
	v_lshl_add_u64 v[32:33], v[36:37], 0, v[32:33]
	global_store_dwordx4 v[32:33], v[28:31], off
	v_or_b32_e32 v33, s19, v7
	v_or_b32_e32 v32, s18, v12
	v_lshlrev_b64 v[32:33], 8, v[32:33]
	s_waitcnt lgkmcnt(3)
	v_cvt_pk_bf16_f32 v28, v34, v35
	s_waitcnt lgkmcnt(2)
	v_cvt_pk_bf16_f32 v29, v38, v39
	s_waitcnt lgkmcnt(1)
	v_cvt_pk_bf16_f32 v30, v40, v41
	s_waitcnt lgkmcnt(0)
	v_cvt_pk_bf16_f32 v31, v42, v43
	v_lshl_add_u64 v[32:33], v[36:37], 0, v[32:33]
	global_store_dwordx4 v[32:33], v[28:31], off
	s_waitcnt lgkmcnt(0)
	s_add_i32 s8, s8, s36
	s_cmp_lt_i32 s8, 8
	s_cbranch_scc1 .LBB0_73
	v_lshl_add_u64 v[24:25], s[0:1], 2, v[20:21]
	s_lshl_b32 s0, s0, 1
	v_lshl_add_u64 v[26:27], v[22:23], 0, s[0:1]
	s_mov_b32 s0, s38

; __device__ __forceinline__ void transpose_item(const float* W, int N, bf16_t* WT, int dstK, size_t drow0, int kdst0, int k0, int n0, LAS float* scr, int lane) {
; #pragma unroll 8
;     for (int i = 0; i < 32; ++i) { const int kk = 2 * i + (lane >> 5); scr[kk * 33 + (lane & 31)] = W[(size_t)(k0 + kk) * N + n0 + (lane & 31)]; }
; __global__ void __launch_bounds__(NTHREADS, 2) fwd_kernel(Args args) {
;     ...
;             transpose_matrix(lru_wx + nb * 16384, 128, 128, WLX + nb * 16384, 128, 0, 0, scr, gw, NGW, lane);
.LBB0_78:
	s_lshl_b32 s10, s9, 1
	s_lshl_b32 s11, s21, 1
	v_or_b32_e32 v51, s10, v3
	v_or_b32_e32 v64, s11, v10
	s_add_i32 s23, s10, 4
	s_add_i32 s24, s11, 4
	s_add_i32 s25, s10, 8
	s_add_i32 s26, s11, 8
	s_add_i32 s27, s10, 12
	s_add_i32 s28, s11, 12
	s_add_i32 s29, s10, 16
	s_add_i32 s30, s11, 16
	s_add_i32 s31, s10, 20
	s_add_i32 s33, s11, 20
	s_add_i32 s34, s10, 24
	s_add_i32 s35, s11, 24
	s_add_i32 s10, s10, 28
	s_add_i32 s11, s11, 28
	v_add_u32_e32 v32, s20, v64
	v_or_b32_e32 v65, s23, v3
	v_or_b32_e32 v66, s24, v10
	v_or_b32_e32 v67, s25, v3
	v_or_b32_e32 v68, s26, v10
	v_or_b32_e32 v69, s27, v3
	v_or_b32_e32 v70, s28, v10
	v_or_b32_e32 v71, s29, v3
	v_or_b32_e32 v72, s30, v10
	v_or_b32_e32 v73, s31, v3
	v_or_b32_e32 v74, s33, v10
	v_or_b32_e32 v75, s34, v3
	v_or_b32_e32 v76, s35, v10
	v_or_b32_e32 v77, s10, v3
	v_or_b32_e32 v78, s11, v10
	v_add_u32_e32 v30, s8, v51
	v_ashrrev_i32_e32 v33, 31, v32
	v_add_u32_e32 v34, s8, v65
	v_add_u32_e32 v36, s20, v66
	v_add_u32_e32 v38, s8, v67
	v_add_u32_e32 v40, s20, v68
	v_add_u32_e32 v42, s8, v69
	v_add_u32_e32 v44, s20, v70
	v_add_u32_e32 v46, s8, v71
	v_add_u32_e32 v48, s20, v72
	v_add_u32_e32 v52, s8, v73
	v_add_u32_e32 v54, s20, v74
	v_add_u32_e32 v56, s8, v75
	v_add_u32_e32 v58, s20, v76
	v_add_u32_e32 v60, s8, v77
	v_add_u32_e32 v62, s20, v78
	v_ashrrev_i32_e32 v31, 31, v30
	v_lshlrev_b64 v[32:33], 9, v[32:33]
	v_ashrrev_i32_e32 v37, 31, v36
	v_ashrrev_i32_e32 v35, 31, v34
	v_ashrrev_i32_e32 v41, 31, v40
	v_ashrrev_i32_e32 v39, 31, v38
	v_ashrrev_i32_e32 v45, 31, v44
	v_ashrrev_i32_e32 v43, 31, v42
	v_ashrrev_i32_e32 v49, 31, v48
	v_ashrrev_i32_e32 v47, 31, v46
	v_ashrrev_i32_e32 v55, 31, v54
	v_ashrrev_i32_e32 v53, 31, v52
	v_ashrrev_i32_e32 v59, 31, v58
	v_ashrrev_i32_e32 v57, 31, v56
	v_ashrrev_i32_e32 v63, 31, v62
	v_ashrrev_i32_e32 v61, 31, v60
	v_lshlrev_b64 v[30:31], 9, v[30:31]
	v_lshl_add_u64 v[32:33], v[28:29], 0, v[32:33]
	v_lshlrev_b64 v[34:35], 9, v[34:35]
	v_lshlrev_b64 v[36:37], 9, v[36:37]
	v_lshlrev_b64 v[38:39], 9, v[38:39]
	v_lshlrev_b64 v[40:41], 9, v[40:41]
	v_lshlrev_b64 v[42:43], 9, v[42:43]
	v_lshlrev_b64 v[44:45], 9, v[44:45]
	v_lshlrev_b64 v[46:47], 9, v[46:47]
	v_lshlrev_b64 v[48:49], 9, v[48:49]
	v_lshlrev_b64 v[52:53], 9, v[52:53]
	v_lshlrev_b64 v[54:55], 9, v[54:55]
	v_lshlrev_b64 v[56:57], 9, v[56:57]
	v_lshlrev_b64 v[58:59], 9, v[58:59]
	v_lshlrev_b64 v[60:61], 9, v[60:61]
	v_lshlrev_b64 v[62:63], 9, v[62:63]
	v_lshl_add_u64 v[30:31], v[28:29], 0, v[30:31]
	v_lshl_add_u64 v[36:37], v[28:29], 0, v[36:37]
	v_lshl_add_u64 v[34:35], v[28:29], 0, v[34:35]
	v_lshl_add_u64 v[40:41], v[28:29], 0, v[40:41]
	v_lshl_add_u64 v[38:39], v[28:29], 0, v[38:39]
	v_lshl_add_u64 v[44:45], v[28:29], 0, v[44:45]
	v_lshl_add_u64 v[42:43], v[28:29], 0, v[42:43]
	v_lshl_add_u64 v[48:49], v[28:29], 0, v[48:49]
	v_lshl_add_u64 v[46:47], v[28:29], 0, v[46:47]
	v_lshl_add_u64 v[54:55], v[28:29], 0, v[54:55]
	v_lshl_add_u64 v[52:53], v[28:29], 0, v[52:53]
	v_lshl_add_u64 v[58:59], v[28:29], 0, v[58:59]
	v_lshl_add_u64 v[56:57], v[28:29], 0, v[56:57]
	v_lshl_add_u64 v[62:63], v[28:29], 0, v[62:63]
	v_lshl_add_u64 v[60:61], v[28:29], 0, v[60:61]
	global_load_dword v79, v[32:33], off
	global_load_dword v80, v[30:31], off
	global_load_dword v81, v[36:37], off
	global_load_dword v82, v[34:35], off
	global_load_dword v83, v[40:41], off
	global_load_dword v84, v[38:39], off
	global_load_dword v85, v[44:45], off
	global_load_dword v86, v[42:43], off
	global_load_dword v87, v[48:49], off
	global_load_dword v88, v[46:47], off
	global_load_dword v89, v[54:55], off
	global_load_dword v90, v[52:53], off
	global_load_dword v91, v[58:59], off
	global_load_dword v92, v[56:57], off
	global_load_dword v93, v[62:63], off
	global_load_dword v94, v[60:61], off
	s_add_i32 s21, s21, 16
	s_add_i32 s9, s9, 16
	s_add_i32 s22, s22, -16
	v_mad_u64_u32 v[30:31], s[24:25], v64, s6, v[14:15]
	s_cmp_lg_u32 s22, 0
	v_mad_u64_u32 v[32:33], s[24:25], v51, s6, v[14:15]
	v_mad_u64_u32 v[34:35], s[24:25], v66, s6, v[14:15]
	v_mad_u64_u32 v[36:37], s[24:25], v65, s6, v[14:15]
	v_mad_u64_u32 v[38:39], s[24:25], v68, s6, v[14:15]
	v_mad_u64_u32 v[40:41], s[24:25], v67, s6, v[14:15]
	v_mad_u64_u32 v[42:43], s[24:25], v70, s6, v[14:15]
	v_mad_u64_u32 v[44:45], s[24:25], v69, s6, v[14:15]
	v_mad_u64_u32 v[46:47], s[24:25], v72, s6, v[14:15]
	v_mad_u64_u32 v[48:49], s[24:25], v71, s6, v[14:15]
	v_mad_u64_u32 v[52:53], s[24:25], v74, s6, v[14:15]
	v_mad_u64_u32 v[54:55], s[24:25], v73, s6, v[14:15]
	v_mad_u64_u32 v[56:57], s[24:25], v76, s6, v[14:15]
	v_mad_u64_u32 v[58:59], s[24:25], v75, s6, v[14:15]
	v_mad_u64_u32 v[60:61], s[24:25], v78, s6, v[14:15]
	v_mad_u64_u32 v[62:63], s[24:25], v77, s6, v[14:15]
	s_lshl_b32 s10, s9, 1
	s_lshl_b32 s11, s21, 1
	v_or_b32_e32 v128, s10, v3
	v_or_b32_e32 v129, s11, v10
	s_add_i32 s23, s10, 4
	s_add_i32 s24, s11, 4
	s_add_i32 s25, s10, 8
	s_add_i32 s26, s11, 8
	s_add_i32 s27, s10, 12
	s_add_i32 s28, s11, 12
	s_add_i32 s29, s10, 16
	s_add_i32 s30, s11, 16
	s_add_i32 s31, s10, 20
	s_add_i32 s33, s11, 20
	s_add_i32 s34, s10, 24
	s_add_i32 s35, s11, 24
	s_add_i32 s10, s10, 28
	s_add_i32 s11, s11, 28
	v_add_u32_e32 v98, s20, v129
	v_or_b32_e32 v130, s23, v3
	v_or_b32_e32 v131, s24, v10
	v_or_b32_e32 v132, s25, v3
	v_or_b32_e32 v133, s26, v10
	v_or_b32_e32 v134, s27, v3
	v_or_b32_e32 v135, s28, v10
	v_or_b32_e32 v136, s29, v3
	v_or_b32_e32 v137, s30, v10
	v_or_b32_e32 v138, s31, v3
	v_or_b32_e32 v139, s33, v10
	v_or_b32_e32 v140, s34, v3
	v_or_b32_e32 v141, s35, v10
	v_or_b32_e32 v142, s10, v3
	v_or_b32_e32 v143, s11, v10
	v_add_u32_e32 v96, s8, v128
	v_ashrrev_i32_e32 v99, 31, v98
; __device__ __forceinline__ void transpose_item(const float* W, int N, bf16_t* WT, int dstK, size_t drow0, int kdst0, int k0, int n0, LAS float* scr, int lane) {
; #pragma unroll 8
;     for (int i = 0; i < 32; ++i) { const int kk = 2 * i + (lane >> 5); scr[kk * 33 + (lane & 31)] = W[(size_t)(k0 + kk) * N + n0 + (lane & 31)]; }
	v_add_u32_e32 v100, s8, v130
	v_add_u32_e32 v102, s20, v131
	v_add_u32_e32 v104, s8, v132
	v_add_u32_e32 v106, s20, v133
	v_add_u32_e32 v108, s8, v134
	v_add_u32_e32 v110, s20, v135
	v_add_u32_e32 v112, s8, v136
	v_add_u32_e32 v114, s20, v137
	v_add_u32_e32 v116, s8, v138
	v_add_u32_e32 v118, s20, v139
	v_add_u32_e32 v120, s8, v140
	v_add_u32_e32 v122, s20, v141
	v_add_u32_e32 v124, s8, v142
	v_add_u32_e32 v126, s20, v143
	v_ashrrev_i32_e32 v97, 31, v96
	v_lshlrev_b64 v[98:99], 9, v[98:99]
	v_ashrrev_i32_e32 v103, 31, v102
	v_ashrrev_i32_e32 v101, 31, v100
	v_ashrrev_i32_e32 v107, 31, v106
	v_ashrrev_i32_e32 v105, 31, v104
	v_ashrrev_i32_e32 v111, 31, v110
	v_ashrrev_i32_e32 v109, 31, v108
	v_ashrrev_i32_e32 v115, 31, v114
	v_ashrrev_i32_e32 v113, 31, v112
	v_ashrrev_i32_e32 v119, 31, v118
	v_ashrrev_i32_e32 v117, 31, v116
	v_ashrrev_i32_e32 v123, 31, v122
	v_ashrrev_i32_e32 v121, 31, v120
	v_ashrrev_i32_e32 v127, 31, v126
	v_ashrrev_i32_e32 v125, 31, v124
	v_lshlrev_b64 v[96:97], 9, v[96:97]
	v_lshl_add_u64 v[98:99], v[28:29], 0, v[98:99]
	v_lshlrev_b64 v[100:101], 9, v[100:101]
	v_lshlrev_b64 v[102:103], 9, v[102:103]
	v_lshlrev_b64 v[104:105], 9, v[104:105]
	v_lshlrev_b64 v[106:107], 9, v[106:107]
	v_lshlrev_b64 v[108:109], 9, v[108:109]
	v_lshlrev_b64 v[110:111], 9, v[110:111]
	v_lshlrev_b64 v[112:113], 9, v[112:113]
	v_lshlrev_b64 v[114:115], 9, v[114:115]
	v_lshlrev_b64 v[116:117], 9, v[116:117]
	v_lshlrev_b64 v[118:119], 9, v[118:119]
	v_lshlrev_b64 v[120:121], 9, v[120:121]
	v_lshlrev_b64 v[122:123], 9, v[122:123]
	v_lshlrev_b64 v[124:125], 9, v[124:125]
	v_lshlrev_b64 v[126:127], 9, v[126:127]
	v_lshl_add_u64 v[96:97], v[28:29], 0, v[96:97]
	v_lshl_add_u64 v[102:103], v[28:29], 0, v[102:103]
	v_lshl_add_u64 v[100:101], v[28:29], 0, v[100:101]
	v_lshl_add_u64 v[106:107], v[28:29], 0, v[106:107]
	v_lshl_add_u64 v[104:105], v[28:29], 0, v[104:105]
	v_lshl_add_u64 v[110:111], v[28:29], 0, v[110:111]
	v_lshl_add_u64 v[108:109], v[28:29], 0, v[108:109]
	v_lshl_add_u64 v[114:115], v[28:29], 0, v[114:115]
	v_lshl_add_u64 v[112:113], v[28:29], 0, v[112:113]
	v_lshl_add_u64 v[118:119], v[28:29], 0, v[118:119]
	v_lshl_add_u64 v[116:117], v[28:29], 0, v[116:117]
	v_lshl_add_u64 v[122:123], v[28:29], 0, v[122:123]
	v_lshl_add_u64 v[120:121], v[28:29], 0, v[120:121]
	v_lshl_add_u64 v[126:127], v[28:29], 0, v[126:127]
	v_lshl_add_u64 v[124:125], v[28:29], 0, v[124:125]
	global_load_dword v144, v[98:99], off
	global_load_dword v145, v[96:97], off
	global_load_dword v146, v[102:103], off
	global_load_dword v147, v[100:101], off
	global_load_dword v148, v[106:107], off
	global_load_dword v149, v[104:105], off
	global_load_dword v150, v[110:111], off
	global_load_dword v151, v[108:109], off
	global_load_dword v152, v[114:115], off
	global_load_dword v153, v[112:113], off
	global_load_dword v154, v[118:119], off
	global_load_dword v155, v[116:117], off
	global_load_dword v156, v[122:123], off
	global_load_dword v157, v[120:121], off
	global_load_dword v158, v[126:127], off
	global_load_dword v159, v[124:125], off
	s_add_i32 s21, s21, 16
	s_add_i32 s9, s9, 16
	s_add_i32 s22, s22, -16
	v_mad_u64_u32 v[96:97], s[24:25], v129, s6, v[14:15]
	s_cmp_lg_u32 s22, 0
	v_mad_u64_u32 v[98:99], s[24:25], v128, s6, v[14:15]
	v_mad_u64_u32 v[100:101], s[24:25], v131, s6, v[14:15]
	v_mad_u64_u32 v[102:103], s[24:25], v130, s6, v[14:15]
	v_mad_u64_u32 v[104:105], s[24:25], v133, s6, v[14:15]
	v_mad_u64_u32 v[106:107], s[24:25], v132, s6, v[14:15]
	v_mad_u64_u32 v[108:109], s[24:25], v135, s6, v[14:15]
	v_mad_u64_u32 v[110:111], s[24:25], v134, s6, v[14:15]
	v_mad_u64_u32 v[112:113], s[24:25], v137, s6, v[14:15]
	v_mad_u64_u32 v[114:115], s[24:25], v136, s6, v[14:15]
	v_mad_u64_u32 v[116:117], s[24:25], v139, s6, v[14:15]
	v_mad_u64_u32 v[118:119], s[24:25], v138, s6, v[14:15]
	v_mad_u64_u32 v[120:121], s[24:25], v141, s6, v[14:15]
	v_mad_u64_u32 v[122:123], s[24:25], v140, s6, v[14:15]
	v_mad_u64_u32 v[124:125], s[24:25], v143, s6, v[14:15]
	v_mad_u64_u32 v[126:127], s[24:25], v142, s6, v[14:15]
	s_waitcnt vmcnt(31)
; #define LAS __attribute__((address_space(3)))
; __device__ __forceinline__ unsigned cvt_pk_bf16(float lo, float hi) { f32x2_c v = {lo, hi}; bf16x2_c r = __builtin_convertvector(v, bf16x2_c); return __builtin_bit_cast(unsigned, r); }
; #define LDS_WAIT() asm volatile("s_waitcnt lgkmcnt(0)" ::: "memory")
; __device__ __forceinline__ void transpose_item(const float* W, int N, bf16_t* WT, int dstK, size_t drow0, int kdst0, int k0, int n0, LAS float* scr, int lane) {
;     ...
;     for (int i = 0; i < 32; ++i) { const int kk = 2 * i + (lane >> 5); scr[kk * 33 + (lane & 31)] = W[(size_t)(k0 + kk) * N + n0 + (lane & 31)]; }
;     LDS_WAIT();
;     const int c = lane & 7;
; #pragma unroll
;     for (int j = 0; j < 4; ++j) { const int n = (lane >> 3) + 8 * j; const LAS float* s = scr + (8 * c) * 33 + n;
;         u32x4 o; o.x = cvt_pk_bf16(s[0 * 33], s[1 * 33]); o.y = cvt_pk_bf16(s[2 * 33], s[3 * 33]); o.z = cvt_pk_bf16(s[4 * 33], s[5 * 33]); o.w = cvt_pk_bf16(s[6 * 33], s[7 * 33]);
;         *(u32x4*)(WT + (drow0 + n) * dstK + kdst0 + k0 + 8 * c) = o; }
;     LDS_WAIT();
; }
; __device__ __forceinline__ void transpose_matrix(const float* W, int K, int N, bf16_t* WT, int dstK, int kdst0, int mode, LAS float* scr, int gw, int NGW, int lane) {
;     const int nblk = N / 32, items = (K / 64) * nblk;
;     for (int it = gw; it < items; it += NGW) {
;         const int kb = it / nblk, nb = it % nblk, n0 = nb * 32;
;         size_t drow0 = (size_t)n0;
;         if (mode == 1) { const int half = n0 >= DFF ? 1 : 0, nn = n0 - half * DFF; drow0 = (size_t)(nn >> 7) * 256 + half * 128 + (nn & 127); }
;         transpose_item(W, N, WT, dstK, drow0, kdst0, kb * 64, n0, scr, lane);
;     }
; __global__ void __launch_bounds__(NTHREADS, 2) fwd_kernel(Args args) {
;     ...
;         for (int nb = 0; nb < 8; ++nb) {
;             transpose_matrix(lru_wa + nb * 16384, 128, 128, WLA + nb * 16384, 128, 0, 0, scr, gw, NGW, lane);
;             transpose_matrix(lru_wx + nb * 16384, 128, 128, WLX + nb * 16384, 128, 0, 0, scr, gw, NGW, lane);
;         }
	ds_write_b32 v30, v79
	s_waitcnt vmcnt(30)
	ds_write_b32 v32, v80
	s_waitcnt vmcnt(29)
	ds_write_b32 v34, v81
	s_waitcnt vmcnt(28)
	ds_write_b32 v36, v82
	s_waitcnt vmcnt(27)
	ds_write_b32 v38, v83
	s_waitcnt vmcnt(26)
	ds_write_b32 v40, v84
	s_waitcnt vmcnt(25)
	ds_write_b32 v42, v85
	s_waitcnt vmcnt(24)
	ds_write_b32 v44, v86
	s_waitcnt vmcnt(23)
	ds_write_b32 v46, v87
	s_waitcnt vmcnt(22)
	ds_write_b32 v48, v88
	s_waitcnt vmcnt(21)
	ds_write_b32 v52, v89
	s_waitcnt vmcnt(20)
	ds_write_b32 v54, v90
	s_waitcnt vmcnt(19)
	ds_write_b32 v56, v91
	s_waitcnt vmcnt(18)
	ds_write_b32 v58, v92
	s_waitcnt vmcnt(17)
	ds_write_b32 v60, v93
	s_waitcnt vmcnt(16)
	ds_write_b32 v62, v94
	s_waitcnt vmcnt(15)
	ds_write_b32 v96, v144
	s_waitcnt vmcnt(14)
	ds_write_b32 v98, v145
	s_waitcnt vmcnt(13)
	ds_write_b32 v100, v146
	s_waitcnt vmcnt(12)
	ds_write_b32 v102, v147
	s_waitcnt vmcnt(11)
	ds_write_b32 v104, v148
	s_waitcnt vmcnt(10)
	ds_write_b32 v106, v149
	s_waitcnt vmcnt(9)
	ds_write_b32 v108, v150
	s_waitcnt vmcnt(8)
	ds_write_b32 v110, v151
	s_waitcnt vmcnt(7)
	ds_write_b32 v112, v152
	s_waitcnt vmcnt(6)
	ds_write_b32 v114, v153
	s_waitcnt vmcnt(5)
	ds_write_b32 v116, v154
	s_waitcnt vmcnt(4)
	ds_write_b32 v118, v155
	s_waitcnt vmcnt(3)
	ds_write_b32 v120, v156
	s_waitcnt vmcnt(2)
	ds_write_b32 v122, v157
	s_waitcnt vmcnt(1)
	ds_write_b32 v124, v158
	s_waitcnt vmcnt(0)
	ds_write_b32 v126, v159
	s_waitcnt lgkmcnt(0)
	ds_read2_b32 v[28:29], v2 offset1:33
	ds_read2_b32 v[30:31], v2 offset0:66 offset1:99
	ds_read2_b32 v[32:33], v2 offset0:132 offset1:165
	ds_read2_b32 v[34:35], v2 offset0:198 offset1:231
	s_ashr_i32 s21, s20, 31
	s_waitcnt lgkmcnt(3)
	v_cvt_pk_bf16_f32 v28, v28, v29
	s_waitcnt lgkmcnt(2)
	v_cvt_pk_bf16_f32 v29, v30, v31
	s_waitcnt lgkmcnt(1)
	v_cvt_pk_bf16_f32 v30, v32, v33
	s_waitcnt lgkmcnt(0)
	v_cvt_pk_bf16_f32 v31, v34, v35
	ds_read2_b32 v[34:35], v11 offset1:33
	ds_read2_b32 v[38:39], v11 offset0:66 offset1:99
	ds_read2_b32 v[40:41], v11 offset0:132 offset1:165
	ds_read2_b32 v[42:43], v11 offset0:198 offset1:231
	v_or_b32_e32 v33, s19, v17
	v_or_b32_e32 v32, s18, v16
	v_lshl_add_u64 v[36:37], s[20:21], 1, v[26:27]
	v_lshlrev_b64 v[32:33], 8, v[32:33]
	v_lshl_add_u64 v[32:33], v[36:37], 0, v[32:33]
	global_store_dwordx4 v[32:33], v[28:31], off
	v_or_b32_e32 v33, s19, v1
	v_or_b32_e32 v32, s18, v4
	s_waitcnt lgkmcnt(3)
	v_cvt_pk_bf16_f32 v28, v34, v35
	s_waitcnt lgkmcnt(2)
	v_cvt_pk_bf16_f32 v29, v38, v39
	s_waitcnt lgkmcnt(1)
	v_cvt_pk_bf16_f32 v30, v40, v41
	s_waitcnt lgkmcnt(0)
	v_cvt_pk_bf16_f32 v31, v42, v43
	ds_read2_b32 v[34:35], v13 offset1:33
	ds_read2_b32 v[38:39], v13 offset0:66 offset1:99
	ds_read2_b32 v[40:41], v13 offset0:132 offset1:165
	ds_read2_b32 v[42:43], v13 offset0:198 offset1:231
	v_lshlrev_b64 v[32:33], 8, v[32:33]
	v_lshl_add_u64 v[32:33], v[36:37], 0, v[32:33]
	global_store_dwordx4 v[32:33], v[28:31], off
	v_or_b32_e32 v33, s19, v5
	v_or_b32_e32 v32, s18, v6
	s_waitcnt lgkmcnt(3)
	v_cvt_pk_bf16_f32 v28, v34, v35
	s_waitcnt lgkmcnt(2)
	v_cvt_pk_bf16_f32 v29, v38, v39
	s_waitcnt lgkmcnt(1)
	v_cvt_pk_bf16_f32 v30, v40, v41
	s_waitcnt lgkmcnt(0)
	v_cvt_pk_bf16_f32 v31, v42, v43
	ds_read2_b32 v[34:35], v15 offset1:33
	ds_read2_b32 v[38:39], v15 offset0:66 offset1:99
	ds_read2_b32 v[40:41], v15 offset0:132 offset1:165
	ds_read2_b32 v[42:43], v15 offset0:198 offset1:231
	v_lshlrev_b64 v[32:33], 8, v[32:33]
	v_lshl_add_u64 v[32:33], v[36:37], 0, v[32:33]
	global_store_dwordx4 v[32:33], v[28:31], off
	v_or_b32_e32 v33, s19, v7
	v_or_b32_e32 v32, s18, v12
	v_lshlrev_b64 v[32:33], 8, v[32:33]
	s_waitcnt lgkmcnt(3)
	v_cvt_pk_bf16_f32 v28, v34, v35
	s_waitcnt lgkmcnt(2)
	v_cvt_pk_bf16_f32 v29, v38, v39
	s_waitcnt lgkmcnt(1)
	v_cvt_pk_bf16_f32 v30, v40, v41
	s_waitcnt lgkmcnt(0)
	v_cvt_pk_bf16_f32 v31, v42, v43
	v_lshl_add_u64 v[32:33], v[36:37], 0, v[32:33]
	global_store_dwordx4 v[32:33], v[28:31], off
	s_waitcnt lgkmcnt(0)
	s_add_i32 s0, s0, s36
	s_cmp_lt_i32 s0, 8
	s_cbranch_scc1 .LBB0_77
	s_branch .LBB0_70
